# EpiGate bf16 copy stored as 16 B per lane as well (QKV0, EpiRes, EpiGate epilogues now all 64 B row segments)
# speedup vs baseline: 1.0256x; 1.0039x over previous
.LBB0_747:
	ds_read_b128 v[144:147], v162
	ds_read_b128 v[148:151], v162 offset:1024
	ds_read_b128 v[152:155], v162 offset:2048
	ds_read_b128 v[156:159], v162 offset:3072
	s_add_u32 s67, s20, 0xfff80080
	s_addc_u32 s72, s21, -1
	s_cmp_eq_u32 s63, 28
	s_cselect_b32 s75, s17, s72
	s_cselect_b32 s74, s19, s67
	s_cselect_b32 s73, s54, s57
	s_cselect_b32 s72, s55, s56
	v_lshl_add_u64 v[198:199], s[20:21], 0, v[134:135]
	s_add_i32 m0, s6, 0xc000
	ds_read_b128 v[166:169], v163
	ds_read_b128 v[170:173], v163 offset:1024
	ds_read_b128 v[174:177], v163 offset:2048
	ds_read_b128 v[178:181], v163 offset:3072
	ds_read_b128 v[182:185], v163 offset:4096
	ds_read_b128 v[186:189], v163 offset:5120
	ds_read_b128 v[190:193], v163 offset:6144
	ds_read_b128 v[194:197], v163 offset:7168
	global_load_lds_dwordx4 v[198:199], off
	v_lshl_add_u64 v[198:199], s[20:21], 0, v[138:139]
	s_add_i32 m0, s6, 0xe000
	s_nop 0
	global_load_lds_dwordx4 v[198:199], off
	s_waitcnt lgkmcnt(8)
	s_barrier
	s_waitcnt lgkmcnt(0)
	s_setprio 1
	s_waitcnt lgkmcnt(0)
	v_mfma_f32_16x16x32_bf16 v[124:127], v[144:147], v[166:169], v[124:127]
	v_mfma_f32_16x16x32_bf16 v[120:123], v[152:155], v[166:169], v[120:123]
	v_mfma_f32_16x16x32_bf16 v[108:111], v[144:147], v[174:177], v[108:111]
	v_mfma_f32_16x16x32_bf16 v[104:107], v[152:155], v[174:177], v[104:107]
	v_mfma_f32_16x16x32_bf16 v[92:95], v[144:147], v[182:185], v[92:95]
	v_mfma_f32_16x16x32_bf16 v[88:91], v[152:155], v[182:185], v[88:91]
	v_mfma_f32_16x16x32_bf16 v[76:79], v[144:147], v[190:193], v[76:79]
	v_mfma_f32_16x16x32_bf16 v[72:75], v[152:155], v[190:193], v[72:75]
	v_mfma_f32_16x16x32_bf16 v[124:127], v[148:151], v[170:173], v[124:127]
	v_mfma_f32_16x16x32_bf16 v[120:123], v[156:159], v[170:173], v[120:123]
	v_mfma_f32_16x16x32_bf16 v[108:111], v[148:151], v[178:181], v[108:111]
	v_mfma_f32_16x16x32_bf16 v[104:107], v[156:159], v[178:181], v[104:107]
	v_mfma_f32_16x16x32_bf16 v[92:95], v[148:151], v[186:189], v[92:95]
	v_mfma_f32_16x16x32_bf16 v[88:91], v[156:159], v[186:189], v[88:91]
	v_mfma_f32_16x16x32_bf16 v[76:79], v[148:151], v[194:197], v[76:79]
	v_mfma_f32_16x16x32_bf16 v[72:75], v[156:159], v[194:197], v[72:75]
	s_setprio 0
	s_barrier
	s_add_i32 s67, s45, s5
	v_lshl_add_u64 v[214:215], s[72:73], 0, v[128:129]
	s_mov_b32 m0, s67
	ds_read_b128 v[198:201], v164
	ds_read_b128 v[202:205], v164 offset:1024
	ds_read_b128 v[206:209], v164 offset:2048
	ds_read_b128 v[210:213], v164 offset:3072
	global_load_lds_dwordx4 v[214:215], off
	v_lshl_add_u64 v[216:217], s[72:73], 0, v[130:131]
	s_add_i32 m0, s67, 0x2000
	s_nop 0
	global_load_lds_dwordx4 v[216:217], off
	s_barrier
	s_waitcnt lgkmcnt(0)
	s_setprio 1
	s_waitcnt lgkmcnt(0)
	v_mfma_f32_16x16x32_bf16 v[116:119], v[198:201], v[166:169], v[116:119]
	v_mfma_f32_16x16x32_bf16 v[112:115], v[206:209], v[166:169], v[112:115]
	v_mfma_f32_16x16x32_bf16 v[100:103], v[198:201], v[174:177], v[100:103]
	v_mfma_f32_16x16x32_bf16 v[96:99], v[206:209], v[174:177], v[96:99]
	v_mfma_f32_16x16x32_bf16 v[84:87], v[198:201], v[182:185], v[84:87]
	v_mfma_f32_16x16x32_bf16 v[80:83], v[206:209], v[182:185], v[80:83]
	v_mfma_f32_16x16x32_bf16 v[68:71], v[198:201], v[190:193], v[68:71]
	v_mfma_f32_16x16x32_bf16 v[64:67], v[206:209], v[190:193], v[64:67]
	v_mfma_f32_16x16x32_bf16 v[116:119], v[202:205], v[170:173], v[116:119]
	v_mfma_f32_16x16x32_bf16 v[112:115], v[210:213], v[170:173], v[112:115]
	v_mfma_f32_16x16x32_bf16 v[100:103], v[202:205], v[178:181], v[100:103]
	v_mfma_f32_16x16x32_bf16 v[96:99], v[210:213], v[178:181], v[96:99]
	v_mfma_f32_16x16x32_bf16 v[84:87], v[202:205], v[186:189], v[84:87]
	v_mfma_f32_16x16x32_bf16 v[80:83], v[210:213], v[186:189], v[80:83]
	v_mfma_f32_16x16x32_bf16 v[68:71], v[202:205], v[194:197], v[68:71]
	v_mfma_f32_16x16x32_bf16 v[64:67], v[210:213], v[194:197], v[64:67]
	s_setprio 0
	s_mov_b32 m0, s6
	v_lshl_add_u64 v[218:219], s[74:75], 0, v[128:129]
	s_barrier
	ds_read_b128 v[166:169], v163 offset:16384
	ds_read_b128 v[170:173], v163 offset:17408
	ds_read_b128 v[174:177], v163 offset:18432
	ds_read_b128 v[178:181], v163 offset:19456
	ds_read_b128 v[182:185], v163 offset:20480
	ds_read_b128 v[186:189], v163 offset:21504
	ds_read_b128 v[190:193], v163 offset:22528
	ds_read_b128 v[194:197], v163 offset:23552
	global_load_lds_dwordx4 v[218:219], off
	v_lshl_add_u64 v[220:221], s[74:75], 0, v[130:131]
	s_mov_b32 m0, s7
	s_nop 0
	global_load_lds_dwordx4 v[220:221], off
	s_barrier
	s_waitcnt lgkmcnt(0)
	s_setprio 1
	s_waitcnt lgkmcnt(0)
	v_mfma_f32_16x16x32_bf16 v[60:63], v[144:147], v[166:169], v[60:63]
	v_mfma_f32_16x16x32_bf16 v[56:59], v[152:155], v[166:169], v[56:59]
	v_mfma_f32_16x16x32_bf16 v[44:47], v[144:147], v[174:177], v[44:47]
	v_mfma_f32_16x16x32_bf16 v[40:43], v[152:155], v[174:177], v[40:43]
	v_mfma_f32_16x16x32_bf16 v[28:31], v[144:147], v[182:185], v[28:31]
	v_mfma_f32_16x16x32_bf16 v[24:27], v[152:155], v[182:185], v[24:27]
	v_mfma_f32_16x16x32_bf16 v[12:15], v[144:147], v[190:193], v[12:15]
	v_mfma_f32_16x16x32_bf16 v[8:11], v[152:155], v[190:193], v[8:11]
	v_mfma_f32_16x16x32_bf16 v[60:63], v[148:151], v[170:173], v[60:63]
	v_mfma_f32_16x16x32_bf16 v[56:59], v[156:159], v[170:173], v[56:59]
	v_mfma_f32_16x16x32_bf16 v[44:47], v[148:151], v[178:181], v[44:47]
	v_mfma_f32_16x16x32_bf16 v[40:43], v[156:159], v[178:181], v[40:43]
	v_mfma_f32_16x16x32_bf16 v[28:31], v[148:151], v[186:189], v[28:31]
	v_mfma_f32_16x16x32_bf16 v[24:27], v[156:159], v[186:189], v[24:27]
	v_mfma_f32_16x16x32_bf16 v[12:15], v[148:151], v[194:197], v[12:15]
	v_mfma_f32_16x16x32_bf16 v[8:11], v[156:159], v[194:197], v[8:11]
	s_setprio 0
	s_barrier
	s_add_u32 s76, s72, 0x80000
	s_addc_u32 s77, s73, 0
	s_add_i32 s67, s46, s5
	v_lshl_add_u64 v[144:145], s[76:77], 0, v[128:129]
	s_mov_b32 m0, s67
	s_nop 0
	global_load_lds_dwordx4 v[144:145], off
	v_lshl_add_u64 v[144:145], s[76:77], 0, v[130:131]
	s_add_i32 m0, s67, 0x2000
	s_nop 0
	global_load_lds_dwordx4 v[144:145], off
	s_waitcnt vmcnt(6)
	s_barrier
	s_setprio 1
	v_mfma_f32_16x16x32_bf16 v[52:55], v[198:201], v[166:169], v[52:55]
	v_mfma_f32_16x16x32_bf16 v[48:51], v[206:209], v[166:169], v[48:51]
	v_mfma_f32_16x16x32_bf16 v[36:39], v[198:201], v[174:177], v[36:39]
	v_mfma_f32_16x16x32_bf16 v[32:35], v[206:209], v[174:177], v[32:35]
	v_mfma_f32_16x16x32_bf16 v[20:23], v[198:201], v[182:185], v[20:23]
	v_mfma_f32_16x16x32_bf16 v[16:19], v[206:209], v[182:185], v[16:19]
	v_mfma_f32_16x16x32_bf16 v[4:7], v[198:201], v[190:193], v[4:7]
	v_mfma_f32_16x16x32_bf16 v[0:3], v[206:209], v[190:193], v[0:3]
	v_mfma_f32_16x16x32_bf16 v[52:55], v[202:205], v[170:173], v[52:55]
	v_mfma_f32_16x16x32_bf16 v[48:51], v[210:213], v[170:173], v[48:51]
	v_mfma_f32_16x16x32_bf16 v[36:39], v[202:205], v[178:181], v[36:39]
	v_mfma_f32_16x16x32_bf16 v[32:35], v[210:213], v[178:181], v[32:35]
	v_mfma_f32_16x16x32_bf16 v[20:23], v[202:205], v[186:189], v[20:23]
	v_mfma_f32_16x16x32_bf16 v[16:19], v[210:213], v[186:189], v[16:19]
	v_mfma_f32_16x16x32_bf16 v[4:7], v[202:205], v[194:197], v[4:7]
	v_mfma_f32_16x16x32_bf16 v[0:3], v[210:213], v[194:197], v[0:3]
	s_setprio 0
	s_add_i32 s67, 16, 0x18000
	v_add_u32_e32 v156, s67, v161
	s_barrier
	ds_read_b128 v[144:147], v156
	ds_read_b128 v[148:151], v156 offset:1024
	ds_read_b128 v[152:155], v156 offset:2048
	ds_read_b128 v[156:159], v156 offset:3072
	s_add_u32 s74, s74, 0x80000
	s_addc_u32 s75, s75, 0
	s_mov_b32 m0, s8
	v_lshl_add_u64 v[198:199], s[74:75], 0, v[128:129]
	ds_read_b128 v[166:169], v163 offset:32768
	ds_read_b128 v[170:173], v163 offset:33792
	ds_read_b128 v[174:177], v163 offset:34816
	ds_read_b128 v[178:181], v163 offset:35840
	ds_read_b128 v[182:185], v163 offset:36864
	ds_read_b128 v[186:189], v163 offset:37888
	ds_read_b128 v[190:193], v163 offset:38912
	ds_read_b128 v[194:197], v163 offset:39936
	global_load_lds_dwordx4 v[198:199], off
	v_lshl_add_u64 v[198:199], s[74:75], 0, v[130:131]
	s_mov_b32 m0, s9
	s_nop 0
	global_load_lds_dwordx4 v[198:199], off
	s_waitcnt lgkmcnt(8)
	s_barrier
	s_waitcnt lgkmcnt(0)
	s_setprio 1
	s_waitcnt lgkmcnt(0)
	v_mfma_f32_16x16x32_bf16 v[124:127], v[144:147], v[166:169], v[124:127]
	v_mfma_f32_16x16x32_bf16 v[120:123], v[152:155], v[166:169], v[120:123]
	v_mfma_f32_16x16x32_bf16 v[108:111], v[144:147], v[174:177], v[108:111]
	v_mfma_f32_16x16x32_bf16 v[104:107], v[152:155], v[174:177], v[104:107]
	v_mfma_f32_16x16x32_bf16 v[92:95], v[144:147], v[182:185], v[92:95]
	v_mfma_f32_16x16x32_bf16 v[88:91], v[152:155], v[182:185], v[88:91]
	v_mfma_f32_16x16x32_bf16 v[76:79], v[144:147], v[190:193], v[76:79]
	v_mfma_f32_16x16x32_bf16 v[72:75], v[152:155], v[190:193], v[72:75]
	v_mfma_f32_16x16x32_bf16 v[124:127], v[148:151], v[170:173], v[124:127]
	v_mfma_f32_16x16x32_bf16 v[120:123], v[156:159], v[170:173], v[120:123]
	v_mfma_f32_16x16x32_bf16 v[108:111], v[148:151], v[178:181], v[108:111]
	v_mfma_f32_16x16x32_bf16 v[104:107], v[156:159], v[178:181], v[104:107]
	v_mfma_f32_16x16x32_bf16 v[92:95], v[148:151], v[186:189], v[92:95]
	v_mfma_f32_16x16x32_bf16 v[88:91], v[156:159], v[186:189], v[88:91]
	v_mfma_f32_16x16x32_bf16 v[76:79], v[148:151], v[194:197], v[76:79]
	v_mfma_f32_16x16x32_bf16 v[72:75], v[156:159], v[194:197], v[72:75]
	s_setprio 0
	s_barrier
	s_add_i32 s74, 16, 0x1c000
	s_add_i32 s67, s67, s5
	v_add_u32_e32 v160, s74, v161
	v_lshl_add_u64 v[214:215], v[214:215], 0, s[60:61]
	s_mov_b32 m0, s67
	ds_read_b128 v[198:201], v160
	ds_read_b128 v[202:205], v160 offset:1024
	ds_read_b128 v[206:209], v160 offset:2048
	ds_read_b128 v[210:213], v160 offset:3072
	global_load_lds_dwordx4 v[214:215], off
	v_lshl_add_u64 v[214:215], v[216:217], 0, s[60:61]
	s_add_i32 m0, s67, 0x2000
	s_nop 0
	global_load_lds_dwordx4 v[214:215], off
	s_barrier
	s_waitcnt lgkmcnt(0)
	s_setprio 1
	s_waitcnt lgkmcnt(0)
	v_mfma_f32_16x16x32_bf16 v[116:119], v[198:201], v[166:169], v[116:119]
	v_mfma_f32_16x16x32_bf16 v[112:115], v[206:209], v[166:169], v[112:115]
	v_mfma_f32_16x16x32_bf16 v[100:103], v[198:201], v[174:177], v[100:103]
	v_mfma_f32_16x16x32_bf16 v[96:99], v[206:209], v[174:177], v[96:99]
	v_mfma_f32_16x16x32_bf16 v[84:87], v[198:201], v[182:185], v[84:87]
	v_mfma_f32_16x16x32_bf16 v[80:83], v[206:209], v[182:185], v[80:83]
	v_mfma_f32_16x16x32_bf16 v[68:71], v[198:201], v[190:193], v[68:71]
	v_mfma_f32_16x16x32_bf16 v[64:67], v[206:209], v[190:193], v[64:67]
	v_mfma_f32_16x16x32_bf16 v[116:119], v[202:205], v[170:173], v[116:119]
	v_mfma_f32_16x16x32_bf16 v[112:115], v[210:213], v[170:173], v[112:115]
	v_mfma_f32_16x16x32_bf16 v[100:103], v[202:205], v[178:181], v[100:103]
	v_mfma_f32_16x16x32_bf16 v[96:99], v[210:213], v[178:181], v[96:99]
	v_mfma_f32_16x16x32_bf16 v[84:87], v[202:205], v[186:189], v[84:87]
	v_mfma_f32_16x16x32_bf16 v[80:83], v[210:213], v[186:189], v[80:83]
	v_mfma_f32_16x16x32_bf16 v[68:71], v[202:205], v[194:197], v[68:71]
	v_mfma_f32_16x16x32_bf16 v[64:67], v[210:213], v[194:197], v[64:67]
	s_setprio 0
	s_mov_b32 m0, s26
	v_lshl_add_u64 v[214:215], v[218:219], 0, s[60:61]
	s_barrier
	ds_read_b128 v[166:169], v163 offset:49152
	ds_read_b128 v[170:173], v163 offset:50176
	ds_read_b128 v[174:177], v163 offset:51200
	ds_read_b128 v[178:181], v163 offset:52224
	ds_read_b128 v[182:185], v163 offset:53248
	ds_read_b128 v[186:189], v163 offset:54272
	ds_read_b128 v[190:193], v163 offset:55296
	ds_read_b128 v[194:197], v163 offset:56320
	global_load_lds_dwordx4 v[214:215], off
	v_lshl_add_u64 v[214:215], v[220:221], 0, s[60:61]
	s_mov_b32 m0, s27
	s_nop 0
	global_load_lds_dwordx4 v[214:215], off
	s_barrier
	s_waitcnt lgkmcnt(0)
	s_setprio 1
	s_waitcnt lgkmcnt(0)
	v_mfma_f32_16x16x32_bf16 v[60:63], v[144:147], v[166:169], v[60:63]
	v_mfma_f32_16x16x32_bf16 v[56:59], v[152:155], v[166:169], v[56:59]
	v_mfma_f32_16x16x32_bf16 v[44:47], v[144:147], v[174:177], v[44:47]
	v_mfma_f32_16x16x32_bf16 v[40:43], v[152:155], v[174:177], v[40:43]
	v_mfma_f32_16x16x32_bf16 v[28:31], v[144:147], v[182:185], v[28:31]
	v_mfma_f32_16x16x32_bf16 v[24:27], v[152:155], v[182:185], v[24:27]
	v_mfma_f32_16x16x32_bf16 v[12:15], v[144:147], v[190:193], v[12:15]
	v_mfma_f32_16x16x32_bf16 v[8:11], v[152:155], v[190:193], v[8:11]
	v_mfma_f32_16x16x32_bf16 v[60:63], v[148:151], v[170:173], v[60:63]
	v_mfma_f32_16x16x32_bf16 v[56:59], v[156:159], v[170:173], v[56:59]
	v_mfma_f32_16x16x32_bf16 v[44:47], v[148:151], v[178:181], v[44:47]
	v_mfma_f32_16x16x32_bf16 v[40:43], v[156:159], v[178:181], v[40:43]
	v_mfma_f32_16x16x32_bf16 v[28:31], v[148:151], v[186:189], v[28:31]
	v_mfma_f32_16x16x32_bf16 v[24:27], v[156:159], v[186:189], v[24:27]
	v_mfma_f32_16x16x32_bf16 v[12:15], v[148:151], v[194:197], v[12:15]
	v_mfma_f32_16x16x32_bf16 v[8:11], v[156:159], v[194:197], v[8:11]
	s_setprio 0
	s_barrier
	s_add_u32 s72, s72, 0x80080
	s_addc_u32 s73, s73, 0
	s_add_i32 s67, s74, s5
	v_lshl_add_u64 v[144:145], s[72:73], 0, v[128:129]
	s_mov_b32 m0, s67
	s_nop 0
	global_load_lds_dwordx4 v[144:145], off
	v_lshl_add_u64 v[144:145], s[72:73], 0, v[130:131]
	s_add_i32 m0, s67, 0x2000
	s_nop 0
	global_load_lds_dwordx4 v[144:145], off
	s_waitcnt vmcnt(6)
	s_barrier
	s_setprio 1
	v_mfma_f32_16x16x32_bf16 v[52:55], v[198:201], v[166:169], v[52:55]
	v_mfma_f32_16x16x32_bf16 v[48:51], v[206:209], v[166:169], v[48:51]
	v_mfma_f32_16x16x32_bf16 v[36:39], v[198:201], v[174:177], v[36:39]
	v_mfma_f32_16x16x32_bf16 v[32:35], v[206:209], v[174:177], v[32:35]
	v_mfma_f32_16x16x32_bf16 v[20:23], v[198:201], v[182:185], v[20:23]
	v_mfma_f32_16x16x32_bf16 v[16:19], v[206:209], v[182:185], v[16:19]
	v_mfma_f32_16x16x32_bf16 v[4:7], v[198:201], v[190:193], v[4:7]
	v_mfma_f32_16x16x32_bf16 v[0:3], v[206:209], v[190:193], v[0:3]
	v_mfma_f32_16x16x32_bf16 v[52:55], v[202:205], v[170:173], v[52:55]
	v_mfma_f32_16x16x32_bf16 v[48:51], v[210:213], v[170:173], v[48:51]
	v_mfma_f32_16x16x32_bf16 v[36:39], v[202:205], v[178:181], v[36:39]
	v_mfma_f32_16x16x32_bf16 v[32:35], v[210:213], v[178:181], v[32:35]
	v_mfma_f32_16x16x32_bf16 v[20:23], v[202:205], v[186:189], v[20:23]
	v_mfma_f32_16x16x32_bf16 v[16:19], v[210:213], v[186:189], v[16:19]
	v_mfma_f32_16x16x32_bf16 v[4:7], v[202:205], v[194:197], v[4:7]
	v_mfma_f32_16x16x32_bf16 v[0:3], v[210:213], v[194:197], v[0:3]
	s_setprio 0
	s_add_i32 s63, s63, 2
	s_add_u32 s20, s20, 0x100
	s_addc_u32 s21, s21, 0
	s_add_u32 s56, s56, 0x100
	s_addc_u32 s57, s57, 0
	s_cmp_gt_u32 s63, 29
	s_barrier
	s_cbranch_scc0 .LBB0_747
	v_lshl_add_u32 v154, s18, 8, v133
	v_ashrrev_i32_e32 v155, 31, v154
	s_lshl_b32 s16, s16, 8
	s_ashr_i32 s17, s16, 31
	v_mov_b32_e32 v147, s17
	v_or_b32_e32 v146, s16, v132
	v_bfe_u32 v231, v136, 4, 1
	v_mul_u32_u24_e32 v231, 24, v231
	v_mov_b32_e32 v144, v154
	v_mov_b32_e32 v145, v155
	v_lshl_add_u64 v[148:149], v[144:145], 2, s[64:65]
	global_load_dword v216, v[148:149], off
	v_add_u32_e32 v144, 0x10, v154
	v_mov_b32_e32 v145, v155
	v_lshl_add_u64 v[148:149], v[144:145], 2, s[64:65]
	global_load_dword v217, v[148:149], off
	v_add_u32_e32 v144, 0x20, v154
	v_mov_b32_e32 v145, v155
	v_lshl_add_u64 v[148:149], v[144:145], 2, s[64:65]
	global_load_dword v218, v[148:149], off
	v_add_u32_e32 v144, 0x30, v154
	v_mov_b32_e32 v145, v155
	v_lshl_add_u64 v[148:149], v[144:145], 2, s[64:65]
	global_load_dword v219, v[148:149], off
	v_add_u32_e32 v144, 0x80, v154
	v_mov_b32_e32 v145, v155
	v_lshl_add_u64 v[148:149], v[144:145], 2, s[64:65]
	global_load_dword v220, v[148:149], off
	v_add_u32_e32 v144, 0x90, v154
	v_mov_b32_e32 v145, v155
	v_lshl_add_u64 v[148:149], v[144:145], 2, s[64:65]
	global_load_dword v221, v[148:149], off
	v_add_u32_e32 v144, 0xa0, v154
	v_mov_b32_e32 v145, v155
	v_lshl_add_u64 v[148:149], v[144:145], 2, s[64:65]
	global_load_dword v222, v[148:149], off
	v_add_u32_e32 v144, 0xb0, v154
	v_mov_b32_e32 v145, v155
	v_lshl_add_u64 v[148:149], v[144:145], 2, s[64:65]
	global_load_dword v223, v[148:149], off
	v_mov_b32_e32 v144, v154
	v_mov_b32_e32 v145, v155
	v_lshlrev_b64 v[148:149], 11, v[144:145]
	v_lshl_add_u64 v[148:149], v[148:149], 0, v[146:147]
	v_lshl_add_u64 v[150:151], v[148:149], 2, s[28:29]
	v_lshl_add_u64 v[152:153], v[148:149], 1, s[42:43]
	global_load_dwordx2 v[184:185], v[152:153], off
	global_load_dwordx4 v[168:171], v[150:151], off
	global_load_dwordx2 v[186:187], v[152:153], off offset:32
	global_load_dwordx4 v[172:175], v[150:151], off offset:64
	global_load_dwordx2 v[188:189], v[152:153], off offset:256
	global_load_dwordx4 v[176:179], v[150:151], off offset:512
	global_load_dwordx2 v[190:191], v[152:153], off offset:288
	global_load_dwordx4 v[180:183], v[150:151], off offset:576
	v_add_u32_e32 v144, 0x10, v154
	v_mov_b32_e32 v145, v155
	v_lshlrev_b64 v[148:149], 11, v[144:145]
	v_lshl_add_u64 v[148:149], v[148:149], 0, v[146:147]
	v_lshl_add_u64 v[150:151], v[148:149], 2, s[28:29]
	v_lshl_add_u64 v[152:153], v[148:149], 1, s[42:43]
	global_load_dwordx2 v[208:209], v[152:153], off
	global_load_dwordx4 v[192:195], v[150:151], off
	global_load_dwordx2 v[210:211], v[152:153], off offset:32
	global_load_dwordx4 v[196:199], v[150:151], off offset:64
	global_load_dwordx2 v[212:213], v[152:153], off offset:256
	global_load_dwordx4 v[200:203], v[150:151], off offset:512
	global_load_dwordx2 v[214:215], v[152:153], off offset:288
	global_load_dwordx4 v[204:207], v[150:151], off offset:576
	s_waitcnt vmcnt(8)
	v_fmamk_f32 v216, v216, 0x3a000000, v165
	v_mul_f32_e32 v235, 0x4b800000, v216
	v_cmp_gt_f32_e32 vcc, s47, v216
	s_nop 1
	v_cndmask_b32_e32 v216, v216, v235, vcc
	v_rsq_f32_e32 v216, v216
	s_nop 0
	v_mul_f32_e32 v235, 0x45800000, v216
	v_cndmask_b32_e32 v234, v216, v235, vcc
	v_mov_b32_e32 v144, v154
	v_mov_b32_e32 v145, v155
	v_lshlrev_b64 v[148:149], 11, v[144:145]
	v_lshl_add_u64 v[148:149], v[148:149], 0, v[146:147]
	v_lshl_add_u64 v[150:151], v[148:149], 2, s[28:29]
	v_lshl_add_u64 v[166:167], v[148:149], 1, s[24:25]
	v_add_co_u32_e32 v166, vcc, v166, v231
	s_nop 1
	v_addc_co_u32_e32 v167, vcc, 0, v167, vcc
	v_pk_mul_f32 v[124:125], v[124:125], v[234:235] op_sel_hi:[1,0]
	v_pk_mul_f32 v[126:127], v[126:127], v[234:235] op_sel_hi:[1,0]
	v_mul_f32_e32 v124, 0xbfb8aa3b, v124
	v_mul_f32_e32 v125, 0xbfb8aa3b, v125
	v_mul_f32_e32 v126, 0xbfb8aa3b, v126
	v_mul_f32_e32 v127, 0xbfb8aa3b, v127
	v_exp_f32_e32 v124, v124
	v_exp_f32_e32 v125, v125
	v_exp_f32_e32 v126, v126
	v_exp_f32_e32 v127, v127
	v_pk_add_f32 v[124:125], v[124:125], 1.0 op_sel_hi:[1,0]
	v_pk_add_f32 v[126:127], v[126:127], 1.0 op_sel_hi:[1,0]
	v_div_scale_f32 v224, s[16:17], v124, v124, 1.0
	v_rcp_f32_e32 v225, v224
	s_nop 0
	v_fma_f32 v226, -v224, v225, 1.0
	v_fmac_f32_e32 v225, v226, v225
	v_div_scale_f32 v226, vcc, 1.0, v124, 1.0
	v_mul_f32_e32 v227, v226, v225
	v_fma_f32 v228, -v224, v227, v226
	v_fmac_f32_e32 v227, v228, v225
	v_fma_f32 v224, -v224, v227, v226
	v_div_fmas_f32 v224, v224, v225, v227
	v_div_fixup_f32 v124, v224, v124, 1.0
	v_div_scale_f32 v224, s[16:17], v125, v125, 1.0
	v_rcp_f32_e32 v225, v224
	s_nop 0
	v_fma_f32 v226, -v224, v225, 1.0
	v_fmac_f32_e32 v225, v226, v225
	v_div_scale_f32 v226, vcc, 1.0, v125, 1.0
	v_mul_f32_e32 v227, v226, v225
	v_fma_f32 v228, -v224, v227, v226
	v_fmac_f32_e32 v227, v228, v225
	v_fma_f32 v224, -v224, v227, v226
	v_div_fmas_f32 v224, v224, v225, v227
	v_div_fixup_f32 v125, v224, v125, 1.0
	v_div_scale_f32 v224, s[16:17], v126, v126, 1.0
	v_rcp_f32_e32 v225, v224
	s_nop 0
	v_fma_f32 v226, -v224, v225, 1.0
	v_fmac_f32_e32 v225, v226, v225
	v_div_scale_f32 v226, vcc, 1.0, v126, 1.0
	v_mul_f32_e32 v227, v226, v225
	v_fma_f32 v228, -v224, v227, v226
	v_fmac_f32_e32 v227, v228, v225
	v_fma_f32 v224, -v224, v227, v226
	v_div_fmas_f32 v224, v224, v225, v227
	v_div_fixup_f32 v126, v224, v126, 1.0
	v_div_scale_f32 v224, s[16:17], v127, v127, 1.0
	v_rcp_f32_e32 v225, v224
	s_nop 0
	v_fma_f32 v226, -v224, v225, 1.0
	v_fmac_f32_e32 v225, v226, v225
	v_div_scale_f32 v226, vcc, 1.0, v127, 1.0
	v_mul_f32_e32 v227, v226, v225
	v_fma_f32 v228, -v224, v227, v226
	v_fmac_f32_e32 v227, v228, v225
	v_fma_f32 v224, -v224, v227, v226
	v_div_fmas_f32 v224, v224, v225, v227
	v_div_fixup_f32 v127, v224, v127, 1.0
	v_lshlrev_b32_e32 v236, 16, v184
	v_and_b32_e32 v237, 0xffff0000, v184
	v_lshlrev_b32_e32 v238, 16, v185
	v_and_b32_e32 v239, 0xffff0000, v185
	v_pk_fma_f32 v[124:125], v[124:125], v[236:237], v[168:169]
	v_pk_fma_f32 v[126:127], v[126:127], v[238:239], v[170:171]
	v_cvt_pk_bf16_f32 v157, v126, v127
	v_cvt_pk_bf16_f32 v156, v124, v125
	global_store_dwordx4 v[150:151], v[124:127], off
	s_nop 1
	v_mul_f32_e32 v125, v125, v125
	v_mul_f32_e32 v127, v127, v127
	v_fmac_f32_e32 v125, v124, v124
	v_fmac_f32_e32 v127, v126, v126
	v_add_f32_e32 v229, v125, v127
	v_pk_mul_f32 v[120:121], v[120:121], v[234:235] op_sel_hi:[1,0]
	v_pk_mul_f32 v[122:123], v[122:123], v[234:235] op_sel_hi:[1,0]
	v_mul_f32_e32 v120, 0xbfb8aa3b, v120
	v_mul_f32_e32 v121, 0xbfb8aa3b, v121
	v_mul_f32_e32 v122, 0xbfb8aa3b, v122
	v_mul_f32_e32 v123, 0xbfb8aa3b, v123
	v_exp_f32_e32 v120, v120
	v_exp_f32_e32 v121, v121
	v_exp_f32_e32 v122, v122
	v_exp_f32_e32 v123, v123
	v_pk_add_f32 v[120:121], v[120:121], 1.0 op_sel_hi:[1,0]
	v_pk_add_f32 v[122:123], v[122:123], 1.0 op_sel_hi:[1,0]
	v_div_scale_f32 v224, s[16:17], v120, v120, 1.0
	v_rcp_f32_e32 v225, v224
	s_nop 0
	v_fma_f32 v226, -v224, v225, 1.0
	v_fmac_f32_e32 v225, v226, v225
	v_div_scale_f32 v226, vcc, 1.0, v120, 1.0
	v_mul_f32_e32 v227, v226, v225
	v_fma_f32 v228, -v224, v227, v226
	v_fmac_f32_e32 v227, v228, v225
	v_fma_f32 v224, -v224, v227, v226
	v_div_fmas_f32 v224, v224, v225, v227
	v_div_fixup_f32 v120, v224, v120, 1.0
	v_div_scale_f32 v224, s[16:17], v121, v121, 1.0
	v_rcp_f32_e32 v225, v224
	s_nop 0
	v_fma_f32 v226, -v224, v225, 1.0
	v_fmac_f32_e32 v225, v226, v225
	v_div_scale_f32 v226, vcc, 1.0, v121, 1.0
	v_mul_f32_e32 v227, v226, v225
	v_fma_f32 v228, -v224, v227, v226
	v_fmac_f32_e32 v227, v228, v225
	v_fma_f32 v224, -v224, v227, v226
	v_div_fmas_f32 v224, v224, v225, v227
	v_div_fixup_f32 v121, v224, v121, 1.0
	v_div_scale_f32 v224, s[16:17], v122, v122, 1.0
	v_rcp_f32_e32 v225, v224
	s_nop 0
	v_fma_f32 v226, -v224, v225, 1.0
	v_fmac_f32_e32 v225, v226, v225
	v_div_scale_f32 v226, vcc, 1.0, v122, 1.0
	v_mul_f32_e32 v227, v226, v225
	v_fma_f32 v228, -v224, v227, v226
	v_fmac_f32_e32 v227, v228, v225
	v_fma_f32 v224, -v224, v227, v226
	v_div_fmas_f32 v224, v224, v225, v227
	v_div_fixup_f32 v122, v224, v122, 1.0
	v_div_scale_f32 v224, s[16:17], v123, v123, 1.0
	v_rcp_f32_e32 v225, v224
	s_nop 0
	v_fma_f32 v226, -v224, v225, 1.0
	v_fmac_f32_e32 v225, v226, v225
	v_div_scale_f32 v226, vcc, 1.0, v123, 1.0
	v_mul_f32_e32 v227, v226, v225
	v_fma_f32 v228, -v224, v227, v226
	v_fmac_f32_e32 v227, v228, v225
	v_fma_f32 v224, -v224, v227, v226
	v_div_fmas_f32 v224, v224, v225, v227
	v_div_fixup_f32 v123, v224, v123, 1.0
	v_lshlrev_b32_e32 v236, 16, v186
	v_and_b32_e32 v237, 0xffff0000, v186
	v_lshlrev_b32_e32 v238, 16, v187
	v_and_b32_e32 v239, 0xffff0000, v187
	v_pk_fma_f32 v[120:121], v[120:121], v[236:237], v[172:173]
	v_pk_fma_f32 v[122:123], v[122:123], v[238:239], v[174:175]
	v_cvt_pk_bf16_f32 v159, v122, v123
	v_cvt_pk_bf16_f32 v158, v120, v121
	global_store_dwordx4 v[150:151], v[120:123], off offset:64
	s_nop 1
	v_mul_f32_e32 v121, v121, v121
	v_mul_f32_e32 v123, v123, v123
	v_fmac_f32_e32 v121, v120, v120
	v_fmac_f32_e32 v123, v122, v122
	v_add_f32_e32 v120, v121, v123
	v_add_f32_e32 v229, v229, v120
	v_permlane16_swap_b32_e32 v156, v158
	v_permlane16_swap_b32_e32 v157, v159
	global_store_dwordx4 v[166:167], v[156:159], off
	s_nop 0
	v_pk_mul_f32 v[116:117], v[116:117], v[234:235] op_sel_hi:[1,0]
	v_pk_mul_f32 v[118:119], v[118:119], v[234:235] op_sel_hi:[1,0]
	v_mul_f32_e32 v116, 0xbfb8aa3b, v116
	v_mul_f32_e32 v117, 0xbfb8aa3b, v117
	v_mul_f32_e32 v118, 0xbfb8aa3b, v118
	v_mul_f32_e32 v119, 0xbfb8aa3b, v119
	v_exp_f32_e32 v116, v116
	v_exp_f32_e32 v117, v117
	v_exp_f32_e32 v118, v118
	v_exp_f32_e32 v119, v119
	v_pk_add_f32 v[116:117], v[116:117], 1.0 op_sel_hi:[1,0]
	v_pk_add_f32 v[118:119], v[118:119], 1.0 op_sel_hi:[1,0]
	v_div_scale_f32 v224, s[16:17], v116, v116, 1.0
	v_rcp_f32_e32 v225, v224
	s_nop 0
	v_fma_f32 v226, -v224, v225, 1.0
	v_fmac_f32_e32 v225, v226, v225
	v_div_scale_f32 v226, vcc, 1.0, v116, 1.0
	v_mul_f32_e32 v227, v226, v225
	v_fma_f32 v228, -v224, v227, v226
	v_fmac_f32_e32 v227, v228, v225
	v_fma_f32 v224, -v224, v227, v226
	v_div_fmas_f32 v224, v224, v225, v227
	v_div_fixup_f32 v116, v224, v116, 1.0
	v_div_scale_f32 v224, s[16:17], v117, v117, 1.0
	v_rcp_f32_e32 v225, v224
	s_nop 0
	v_fma_f32 v226, -v224, v225, 1.0
	v_fmac_f32_e32 v225, v226, v225
	v_div_scale_f32 v226, vcc, 1.0, v117, 1.0
	v_mul_f32_e32 v227, v226, v225
	v_fma_f32 v228, -v224, v227, v226
	v_fmac_f32_e32 v227, v228, v225
	v_fma_f32 v224, -v224, v227, v226
	v_div_fmas_f32 v224, v224, v225, v227
	v_div_fixup_f32 v117, v224, v117, 1.0
	v_div_scale_f32 v224, s[16:17], v118, v118, 1.0
	v_rcp_f32_e32 v225, v224
	s_nop 0
	v_fma_f32 v226, -v224, v225, 1.0
	v_fmac_f32_e32 v225, v226, v225
	v_div_scale_f32 v226, vcc, 1.0, v118, 1.0
	v_mul_f32_e32 v227, v226, v225
	v_fma_f32 v228, -v224, v227, v226
	v_fmac_f32_e32 v227, v228, v225
	v_fma_f32 v224, -v224, v227, v226
	v_div_fmas_f32 v224, v224, v225, v227
	v_div_fixup_f32 v118, v224, v118, 1.0
	v_div_scale_f32 v224, s[16:17], v119, v119, 1.0
	v_rcp_f32_e32 v225, v224
	s_nop 0
	v_fma_f32 v226, -v224, v225, 1.0
	v_fmac_f32_e32 v225, v226, v225
	v_div_scale_f32 v226, vcc, 1.0, v119, 1.0
	v_mul_f32_e32 v227, v226, v225
	v_fma_f32 v228, -v224, v227, v226
	v_fmac_f32_e32 v227, v228, v225
	v_fma_f32 v224, -v224, v227, v226
	v_div_fmas_f32 v224, v224, v225, v227
	v_div_fixup_f32 v119, v224, v119, 1.0
	v_lshlrev_b32_e32 v236, 16, v188
	v_and_b32_e32 v237, 0xffff0000, v188
	v_lshlrev_b32_e32 v238, 16, v189
	v_and_b32_e32 v239, 0xffff0000, v189
	v_pk_fma_f32 v[116:117], v[116:117], v[236:237], v[176:177]
	v_pk_fma_f32 v[118:119], v[118:119], v[238:239], v[178:179]
	v_cvt_pk_bf16_f32 v157, v118, v119
	v_cvt_pk_bf16_f32 v156, v116, v117
	global_store_dwordx4 v[150:151], v[116:119], off offset:512
	s_nop 1
	v_mul_f32_e32 v117, v117, v117
	v_mul_f32_e32 v119, v119, v119
	v_fmac_f32_e32 v117, v116, v116
	v_fmac_f32_e32 v119, v118, v118
	v_add_f32_e32 v116, v117, v119
	v_add_f32_e32 v229, v229, v116
	v_pk_mul_f32 v[112:113], v[112:113], v[234:235] op_sel_hi:[1,0]
	v_pk_mul_f32 v[114:115], v[114:115], v[234:235] op_sel_hi:[1,0]
	v_mul_f32_e32 v112, 0xbfb8aa3b, v112
	v_mul_f32_e32 v113, 0xbfb8aa3b, v113
	v_mul_f32_e32 v114, 0xbfb8aa3b, v114
	v_mul_f32_e32 v115, 0xbfb8aa3b, v115
	v_exp_f32_e32 v112, v112
	v_exp_f32_e32 v113, v113
	v_exp_f32_e32 v114, v114
	v_exp_f32_e32 v115, v115
	v_pk_add_f32 v[112:113], v[112:113], 1.0 op_sel_hi:[1,0]
	v_pk_add_f32 v[114:115], v[114:115], 1.0 op_sel_hi:[1,0]
	v_div_scale_f32 v224, s[16:17], v112, v112, 1.0
	v_rcp_f32_e32 v225, v224
	s_nop 0
	v_fma_f32 v226, -v224, v225, 1.0
	v_fmac_f32_e32 v225, v226, v225
	v_div_scale_f32 v226, vcc, 1.0, v112, 1.0
	v_mul_f32_e32 v227, v226, v225
	v_fma_f32 v228, -v224, v227, v226
	v_fmac_f32_e32 v227, v228, v225
	v_fma_f32 v224, -v224, v227, v226
	v_div_fmas_f32 v224, v224, v225, v227
	v_div_fixup_f32 v112, v224, v112, 1.0
	v_div_scale_f32 v224, s[16:17], v113, v113, 1.0
	v_rcp_f32_e32 v225, v224
	s_nop 0
	v_fma_f32 v226, -v224, v225, 1.0
	v_fmac_f32_e32 v225, v226, v225
	v_div_scale_f32 v226, vcc, 1.0, v113, 1.0
	v_mul_f32_e32 v227, v226, v225
	v_fma_f32 v228, -v224, v227, v226
	v_fmac_f32_e32 v227, v228, v225
	v_fma_f32 v224, -v224, v227, v226
	v_div_fmas_f32 v224, v224, v225, v227
	v_div_fixup_f32 v113, v224, v113, 1.0
	v_div_scale_f32 v224, s[16:17], v114, v114, 1.0
	v_rcp_f32_e32 v225, v224
	s_nop 0
	v_fma_f32 v226, -v224, v225, 1.0
	v_fmac_f32_e32 v225, v226, v225
	v_div_scale_f32 v226, vcc, 1.0, v114, 1.0
	v_mul_f32_e32 v227, v226, v225
	v_fma_f32 v228, -v224, v227, v226
	v_fmac_f32_e32 v227, v228, v225
	v_fma_f32 v224, -v224, v227, v226
	v_div_fmas_f32 v224, v224, v225, v227
	v_div_fixup_f32 v114, v224, v114, 1.0
	v_div_scale_f32 v224, s[16:17], v115, v115, 1.0
	v_rcp_f32_e32 v225, v224
	s_nop 0
	v_fma_f32 v226, -v224, v225, 1.0
	v_fmac_f32_e32 v225, v226, v225
	v_div_scale_f32 v226, vcc, 1.0, v115, 1.0
	v_mul_f32_e32 v227, v226, v225
	v_fma_f32 v228, -v224, v227, v226
	v_fmac_f32_e32 v227, v228, v225
	v_fma_f32 v224, -v224, v227, v226
	v_div_fmas_f32 v224, v224, v225, v227
	v_div_fixup_f32 v115, v224, v115, 1.0
	v_lshlrev_b32_e32 v236, 16, v190
	v_and_b32_e32 v237, 0xffff0000, v190
	v_lshlrev_b32_e32 v238, 16, v191
	v_and_b32_e32 v239, 0xffff0000, v191
	v_pk_fma_f32 v[112:113], v[112:113], v[236:237], v[180:181]
	v_pk_fma_f32 v[114:115], v[114:115], v[238:239], v[182:183]
	v_cvt_pk_bf16_f32 v159, v114, v115
	v_cvt_pk_bf16_f32 v158, v112, v113
	global_store_dwordx4 v[150:151], v[112:115], off offset:576
	s_nop 1
	v_mul_f32_e32 v113, v113, v113
	v_mul_f32_e32 v115, v115, v115
	v_fmac_f32_e32 v113, v112, v112
	v_fmac_f32_e32 v115, v114, v114
	v_add_f32_e32 v112, v113, v115
	v_add_f32_e32 v229, v229, v112
	v_permlane16_swap_b32_e32 v156, v158
	v_permlane16_swap_b32_e32 v157, v159
	global_store_dwordx4 v[166:167], v[156:159], off offset:256
	s_nop 0
	v_mov_b32_e32 v230, v229
	s_nop 1
	v_permlane16_swap_b32_e32 v229, v230
	v_add_f32_e32 v229, v229, v230
	v_mov_b32_e32 v230, v229
	s_nop 1
	v_permlane32_swap_b32_e32 v229, v230
	s_and_saveexec_b64 s[16:17], s[10:11]
	v_lshl_add_u64 v[156:157], v[144:145], 2, s[22:23]
	v_add_f32_e32 v229, v229, v230
	global_atomic_add_f32 v[156:157], v229, off
	s_or_b64 exec, exec, s[16:17]
	v_add_u32_e32 v144, 0x20, v154
	v_mov_b32_e32 v145, v155
	v_lshlrev_b64 v[148:149], 11, v[144:145]
	v_lshl_add_u64 v[148:149], v[148:149], 0, v[146:147]
	v_lshl_add_u64 v[150:151], v[148:149], 2, s[28:29]
	v_lshl_add_u64 v[152:153], v[148:149], 1, s[42:43]
	global_load_dwordx2 v[184:185], v[152:153], off
	global_load_dwordx4 v[168:171], v[150:151], off
	global_load_dwordx2 v[186:187], v[152:153], off offset:32
	global_load_dwordx4 v[172:175], v[150:151], off offset:64
	global_load_dwordx2 v[188:189], v[152:153], off offset:256
	global_load_dwordx4 v[176:179], v[150:151], off offset:512
	global_load_dwordx2 v[190:191], v[152:153], off offset:288
	global_load_dwordx4 v[180:183], v[150:151], off offset:576
	s_waitcnt vmcnt(15)
	v_fmamk_f32 v217, v217, 0x3a000000, v165
	v_mul_f32_e32 v235, 0x4b800000, v217
	v_cmp_gt_f32_e32 vcc, s47, v217
	s_nop 1
	v_cndmask_b32_e32 v217, v217, v235, vcc
	v_rsq_f32_e32 v217, v217
	s_nop 0
	v_mul_f32_e32 v235, 0x45800000, v217
	v_cndmask_b32_e32 v234, v217, v235, vcc
	v_add_u32_e32 v144, 0x10, v154
	v_mov_b32_e32 v145, v155
	v_lshlrev_b64 v[148:149], 11, v[144:145]
	v_lshl_add_u64 v[148:149], v[148:149], 0, v[146:147]
	v_lshl_add_u64 v[150:151], v[148:149], 2, s[28:29]
	v_lshl_add_u64 v[166:167], v[148:149], 1, s[24:25]
	v_add_co_u32_e32 v166, vcc, v166, v231
	s_nop 1
	v_addc_co_u32_e32 v167, vcc, 0, v167, vcc
	v_pk_mul_f32 v[108:109], v[108:109], v[234:235] op_sel_hi:[1,0]
	v_pk_mul_f32 v[110:111], v[110:111], v[234:235] op_sel_hi:[1,0]
	v_mul_f32_e32 v108, 0xbfb8aa3b, v108
	v_mul_f32_e32 v109, 0xbfb8aa3b, v109
	v_mul_f32_e32 v110, 0xbfb8aa3b, v110
	v_mul_f32_e32 v111, 0xbfb8aa3b, v111
	v_exp_f32_e32 v108, v108
	v_exp_f32_e32 v109, v109
	v_exp_f32_e32 v110, v110
	v_exp_f32_e32 v111, v111
	v_pk_add_f32 v[108:109], v[108:109], 1.0 op_sel_hi:[1,0]
	v_pk_add_f32 v[110:111], v[110:111], 1.0 op_sel_hi:[1,0]
	v_div_scale_f32 v224, s[16:17], v108, v108, 1.0
	v_rcp_f32_e32 v225, v224
	s_nop 0
	v_fma_f32 v226, -v224, v225, 1.0
	v_fmac_f32_e32 v225, v226, v225
	v_div_scale_f32 v226, vcc, 1.0, v108, 1.0
	v_mul_f32_e32 v227, v226, v225
	v_fma_f32 v228, -v224, v227, v226
	v_fmac_f32_e32 v227, v228, v225
	v_fma_f32 v224, -v224, v227, v226
	v_div_fmas_f32 v224, v224, v225, v227
	v_div_fixup_f32 v108, v224, v108, 1.0
	v_div_scale_f32 v224, s[16:17], v109, v109, 1.0
	v_rcp_f32_e32 v225, v224
	s_nop 0
	v_fma_f32 v226, -v224, v225, 1.0
	v_fmac_f32_e32 v225, v226, v225
	v_div_scale_f32 v226, vcc, 1.0, v109, 1.0
	v_mul_f32_e32 v227, v226, v225
	v_fma_f32 v228, -v224, v227, v226
	v_fmac_f32_e32 v227, v228, v225
	v_fma_f32 v224, -v224, v227, v226
	v_div_fmas_f32 v224, v224, v225, v227
	v_div_fixup_f32 v109, v224, v109, 1.0
	v_div_scale_f32 v224, s[16:17], v110, v110, 1.0
	v_rcp_f32_e32 v225, v224
	s_nop 0
	v_fma_f32 v226, -v224, v225, 1.0
	v_fmac_f32_e32 v225, v226, v225
	v_div_scale_f32 v226, vcc, 1.0, v110, 1.0
	v_mul_f32_e32 v227, v226, v225
	v_fma_f32 v228, -v224, v227, v226
	v_fmac_f32_e32 v227, v228, v225
	v_fma_f32 v224, -v224, v227, v226
	v_div_fmas_f32 v224, v224, v225, v227
	v_div_fixup_f32 v110, v224, v110, 1.0
	v_div_scale_f32 v224, s[16:17], v111, v111, 1.0
	v_rcp_f32_e32 v225, v224
	s_nop 0
	v_fma_f32 v226, -v224, v225, 1.0
	v_fmac_f32_e32 v225, v226, v225
	v_div_scale_f32 v226, vcc, 1.0, v111, 1.0
	v_mul_f32_e32 v227, v226, v225
	v_fma_f32 v228, -v224, v227, v226
	v_fmac_f32_e32 v227, v228, v225
	v_fma_f32 v224, -v224, v227, v226
	v_div_fmas_f32 v224, v224, v225, v227
	v_div_fixup_f32 v111, v224, v111, 1.0
	v_lshlrev_b32_e32 v236, 16, v208
	v_and_b32_e32 v237, 0xffff0000, v208
	v_lshlrev_b32_e32 v238, 16, v209
	v_and_b32_e32 v239, 0xffff0000, v209
	v_pk_fma_f32 v[108:109], v[108:109], v[236:237], v[192:193]
	v_pk_fma_f32 v[110:111], v[110:111], v[238:239], v[194:195]
	v_cvt_pk_bf16_f32 v157, v110, v111
	v_cvt_pk_bf16_f32 v156, v108, v109
	global_store_dwordx4 v[150:151], v[108:111], off
	s_nop 1
	v_mul_f32_e32 v109, v109, v109
	v_mul_f32_e32 v111, v111, v111
	v_fmac_f32_e32 v109, v108, v108
	v_fmac_f32_e32 v111, v110, v110
	v_add_f32_e32 v229, v109, v111
	v_pk_mul_f32 v[104:105], v[104:105], v[234:235] op_sel_hi:[1,0]
	v_pk_mul_f32 v[106:107], v[106:107], v[234:235] op_sel_hi:[1,0]
	v_mul_f32_e32 v104, 0xbfb8aa3b, v104
	v_mul_f32_e32 v105, 0xbfb8aa3b, v105
	v_mul_f32_e32 v106, 0xbfb8aa3b, v106
	v_mul_f32_e32 v107, 0xbfb8aa3b, v107
	v_exp_f32_e32 v104, v104
	v_exp_f32_e32 v105, v105
	v_exp_f32_e32 v106, v106
	v_exp_f32_e32 v107, v107
	v_pk_add_f32 v[104:105], v[104:105], 1.0 op_sel_hi:[1,0]
	v_pk_add_f32 v[106:107], v[106:107], 1.0 op_sel_hi:[1,0]
	v_div_scale_f32 v224, s[16:17], v104, v104, 1.0
	v_rcp_f32_e32 v225, v224
	s_nop 0
	v_fma_f32 v226, -v224, v225, 1.0
	v_fmac_f32_e32 v225, v226, v225
	v_div_scale_f32 v226, vcc, 1.0, v104, 1.0
	v_mul_f32_e32 v227, v226, v225
	v_fma_f32 v228, -v224, v227, v226
	v_fmac_f32_e32 v227, v228, v225
	v_fma_f32 v224, -v224, v227, v226
	v_div_fmas_f32 v224, v224, v225, v227
	v_div_fixup_f32 v104, v224, v104, 1.0
	v_div_scale_f32 v224, s[16:17], v105, v105, 1.0
	v_rcp_f32_e32 v225, v224
	s_nop 0
	v_fma_f32 v226, -v224, v225, 1.0
	v_fmac_f32_e32 v225, v226, v225
	v_div_scale_f32 v226, vcc, 1.0, v105, 1.0
	v_mul_f32_e32 v227, v226, v225
	v_fma_f32 v228, -v224, v227, v226
	v_fmac_f32_e32 v227, v228, v225
	v_fma_f32 v224, -v224, v227, v226
	v_div_fmas_f32 v224, v224, v225, v227
	v_div_fixup_f32 v105, v224, v105, 1.0
	v_div_scale_f32 v224, s[16:17], v106, v106, 1.0
	v_rcp_f32_e32 v225, v224
	s_nop 0
	v_fma_f32 v226, -v224, v225, 1.0
	v_fmac_f32_e32 v225, v226, v225
	v_div_scale_f32 v226, vcc, 1.0, v106, 1.0
	v_mul_f32_e32 v227, v226, v225
	v_fma_f32 v228, -v224, v227, v226
	v_fmac_f32_e32 v227, v228, v225
	v_fma_f32 v224, -v224, v227, v226
	v_div_fmas_f32 v224, v224, v225, v227
	v_div_fixup_f32 v106, v224, v106, 1.0
	v_div_scale_f32 v224, s[16:17], v107, v107, 1.0
	v_rcp_f32_e32 v225, v224
	s_nop 0
	v_fma_f32 v226, -v224, v225, 1.0
	v_fmac_f32_e32 v225, v226, v225
	v_div_scale_f32 v226, vcc, 1.0, v107, 1.0
	v_mul_f32_e32 v227, v226, v225
	v_fma_f32 v228, -v224, v227, v226
	v_fmac_f32_e32 v227, v228, v225
	v_fma_f32 v224, -v224, v227, v226
	v_div_fmas_f32 v224, v224, v225, v227
	v_div_fixup_f32 v107, v224, v107, 1.0
	v_lshlrev_b32_e32 v236, 16, v210
	v_and_b32_e32 v237, 0xffff0000, v210
	v_lshlrev_b32_e32 v238, 16, v211
	v_and_b32_e32 v239, 0xffff0000, v211
	v_pk_fma_f32 v[104:105], v[104:105], v[236:237], v[196:197]
	v_pk_fma_f32 v[106:107], v[106:107], v[238:239], v[198:199]
	v_cvt_pk_bf16_f32 v159, v106, v107
	v_cvt_pk_bf16_f32 v158, v104, v105
	global_store_dwordx4 v[150:151], v[104:107], off offset:64
	s_nop 1
	v_mul_f32_e32 v105, v105, v105
	v_mul_f32_e32 v107, v107, v107
	v_fmac_f32_e32 v105, v104, v104
	v_fmac_f32_e32 v107, v106, v106
	v_add_f32_e32 v104, v105, v107
	v_add_f32_e32 v229, v229, v104
	v_permlane16_swap_b32_e32 v156, v158
	v_permlane16_swap_b32_e32 v157, v159
	global_store_dwordx4 v[166:167], v[156:159], off
	s_nop 0
	v_pk_mul_f32 v[100:101], v[100:101], v[234:235] op_sel_hi:[1,0]
	v_pk_mul_f32 v[102:103], v[102:103], v[234:235] op_sel_hi:[1,0]
	v_mul_f32_e32 v100, 0xbfb8aa3b, v100
	v_mul_f32_e32 v101, 0xbfb8aa3b, v101
	v_mul_f32_e32 v102, 0xbfb8aa3b, v102
	v_mul_f32_e32 v103, 0xbfb8aa3b, v103
	v_exp_f32_e32 v100, v100
	v_exp_f32_e32 v101, v101
	v_exp_f32_e32 v102, v102
	v_exp_f32_e32 v103, v103
	v_pk_add_f32 v[100:101], v[100:101], 1.0 op_sel_hi:[1,0]
	v_pk_add_f32 v[102:103], v[102:103], 1.0 op_sel_hi:[1,0]
	v_div_scale_f32 v224, s[16:17], v100, v100, 1.0
	v_rcp_f32_e32 v225, v224
	s_nop 0
	v_fma_f32 v226, -v224, v225, 1.0
	v_fmac_f32_e32 v225, v226, v225
	v_div_scale_f32 v226, vcc, 1.0, v100, 1.0
	v_mul_f32_e32 v227, v226, v225
	v_fma_f32 v228, -v224, v227, v226
	v_fmac_f32_e32 v227, v228, v225
	v_fma_f32 v224, -v224, v227, v226
	v_div_fmas_f32 v224, v224, v225, v227
	v_div_fixup_f32 v100, v224, v100, 1.0
	v_div_scale_f32 v224, s[16:17], v101, v101, 1.0
	v_rcp_f32_e32 v225, v224
	s_nop 0
	v_fma_f32 v226, -v224, v225, 1.0
	v_fmac_f32_e32 v225, v226, v225
	v_div_scale_f32 v226, vcc, 1.0, v101, 1.0
	v_mul_f32_e32 v227, v226, v225
	v_fma_f32 v228, -v224, v227, v226
	v_fmac_f32_e32 v227, v228, v225
	v_fma_f32 v224, -v224, v227, v226
	v_div_fmas_f32 v224, v224, v225, v227
	v_div_fixup_f32 v101, v224, v101, 1.0
	v_div_scale_f32 v224, s[16:17], v102, v102, 1.0
	v_rcp_f32_e32 v225, v224
	s_nop 0
	v_fma_f32 v226, -v224, v225, 1.0
	v_fmac_f32_e32 v225, v226, v225
	v_div_scale_f32 v226, vcc, 1.0, v102, 1.0
	v_mul_f32_e32 v227, v226, v225
	v_fma_f32 v228, -v224, v227, v226
	v_fmac_f32_e32 v227, v228, v225
	v_fma_f32 v224, -v224, v227, v226
	v_div_fmas_f32 v224, v224, v225, v227
	v_div_fixup_f32 v102, v224, v102, 1.0
	v_div_scale_f32 v224, s[16:17], v103, v103, 1.0
	v_rcp_f32_e32 v225, v224
	s_nop 0
	v_fma_f32 v226, -v224, v225, 1.0
	v_fmac_f32_e32 v225, v226, v225
	v_div_scale_f32 v226, vcc, 1.0, v103, 1.0
	v_mul_f32_e32 v227, v226, v225
	v_fma_f32 v228, -v224, v227, v226
	v_fmac_f32_e32 v227, v228, v225
	v_fma_f32 v224, -v224, v227, v226
	v_div_fmas_f32 v224, v224, v225, v227
	v_div_fixup_f32 v103, v224, v103, 1.0
	v_lshlrev_b32_e32 v236, 16, v212
	v_and_b32_e32 v237, 0xffff0000, v212
	v_lshlrev_b32_e32 v238, 16, v213
	v_and_b32_e32 v239, 0xffff0000, v213
	v_pk_fma_f32 v[100:101], v[100:101], v[236:237], v[200:201]
	v_pk_fma_f32 v[102:103], v[102:103], v[238:239], v[202:203]
	v_cvt_pk_bf16_f32 v157, v102, v103
	v_cvt_pk_bf16_f32 v156, v100, v101
	global_store_dwordx4 v[150:151], v[100:103], off offset:512
	s_nop 1
	v_mul_f32_e32 v101, v101, v101
	v_mul_f32_e32 v103, v103, v103
	v_fmac_f32_e32 v101, v100, v100
	v_fmac_f32_e32 v103, v102, v102
	v_add_f32_e32 v100, v101, v103
	v_add_f32_e32 v229, v229, v100
	v_pk_mul_f32 v[96:97], v[96:97], v[234:235] op_sel_hi:[1,0]
	v_pk_mul_f32 v[98:99], v[98:99], v[234:235] op_sel_hi:[1,0]
	v_mul_f32_e32 v96, 0xbfb8aa3b, v96
	v_mul_f32_e32 v97, 0xbfb8aa3b, v97
	v_mul_f32_e32 v98, 0xbfb8aa3b, v98
	v_mul_f32_e32 v99, 0xbfb8aa3b, v99
	v_exp_f32_e32 v96, v96
	v_exp_f32_e32 v97, v97
	v_exp_f32_e32 v98, v98
	v_exp_f32_e32 v99, v99
	v_pk_add_f32 v[96:97], v[96:97], 1.0 op_sel_hi:[1,0]
	v_pk_add_f32 v[98:99], v[98:99], 1.0 op_sel_hi:[1,0]
	v_div_scale_f32 v224, s[16:17], v96, v96, 1.0
	v_rcp_f32_e32 v225, v224
	s_nop 0
	v_fma_f32 v226, -v224, v225, 1.0
	v_fmac_f32_e32 v225, v226, v225
	v_div_scale_f32 v226, vcc, 1.0, v96, 1.0
	v_mul_f32_e32 v227, v226, v225
	v_fma_f32 v228, -v224, v227, v226
	v_fmac_f32_e32 v227, v228, v225
	v_fma_f32 v224, -v224, v227, v226
	v_div_fmas_f32 v224, v224, v225, v227
	v_div_fixup_f32 v96, v224, v96, 1.0
	v_div_scale_f32 v224, s[16:17], v97, v97, 1.0
	v_rcp_f32_e32 v225, v224
	s_nop 0
	v_fma_f32 v226, -v224, v225, 1.0
	v_fmac_f32_e32 v225, v226, v225
	v_div_scale_f32 v226, vcc, 1.0, v97, 1.0
	v_mul_f32_e32 v227, v226, v225
	v_fma_f32 v228, -v224, v227, v226
	v_fmac_f32_e32 v227, v228, v225
	v_fma_f32 v224, -v224, v227, v226
	v_div_fmas_f32 v224, v224, v225, v227
	v_div_fixup_f32 v97, v224, v97, 1.0
	v_div_scale_f32 v224, s[16:17], v98, v98, 1.0
	v_rcp_f32_e32 v225, v224
	s_nop 0
	v_fma_f32 v226, -v224, v225, 1.0
	v_fmac_f32_e32 v225, v226, v225
	v_div_scale_f32 v226, vcc, 1.0, v98, 1.0
	v_mul_f32_e32 v227, v226, v225
	v_fma_f32 v228, -v224, v227, v226
	v_fmac_f32_e32 v227, v228, v225
	v_fma_f32 v224, -v224, v227, v226
	v_div_fmas_f32 v224, v224, v225, v227
	v_div_fixup_f32 v98, v224, v98, 1.0
	v_div_scale_f32 v224, s[16:17], v99, v99, 1.0
	v_rcp_f32_e32 v225, v224
	s_nop 0
	v_fma_f32 v226, -v224, v225, 1.0
	v_fmac_f32_e32 v225, v226, v225
	v_div_scale_f32 v226, vcc, 1.0, v99, 1.0
	v_mul_f32_e32 v227, v226, v225
	v_fma_f32 v228, -v224, v227, v226
	v_fmac_f32_e32 v227, v228, v225
	v_fma_f32 v224, -v224, v227, v226
	v_div_fmas_f32 v224, v224, v225, v227
	v_div_fixup_f32 v99, v224, v99, 1.0
	v_lshlrev_b32_e32 v236, 16, v214
	v_and_b32_e32 v237, 0xffff0000, v214
	v_lshlrev_b32_e32 v238, 16, v215
	v_and_b32_e32 v239, 0xffff0000, v215
	v_pk_fma_f32 v[96:97], v[96:97], v[236:237], v[204:205]
	v_pk_fma_f32 v[98:99], v[98:99], v[238:239], v[206:207]
	v_cvt_pk_bf16_f32 v159, v98, v99
	v_cvt_pk_bf16_f32 v158, v96, v97
	global_store_dwordx4 v[150:151], v[96:99], off offset:576
	s_nop 1
	v_mul_f32_e32 v97, v97, v97
	v_mul_f32_e32 v99, v99, v99
	v_fmac_f32_e32 v97, v96, v96
	v_fmac_f32_e32 v99, v98, v98
	v_add_f32_e32 v96, v97, v99
	v_add_f32_e32 v229, v229, v96
	v_permlane16_swap_b32_e32 v156, v158
	v_permlane16_swap_b32_e32 v157, v159
	global_store_dwordx4 v[166:167], v[156:159], off offset:256
	s_nop 0
	v_mov_b32_e32 v230, v229
	s_nop 1
	v_permlane16_swap_b32_e32 v229, v230
	v_add_f32_e32 v229, v229, v230
	v_mov_b32_e32 v230, v229
	s_nop 1
	v_permlane32_swap_b32_e32 v229, v230
	s_and_saveexec_b64 s[16:17], s[10:11]
	v_lshl_add_u64 v[156:157], v[144:145], 2, s[22:23]
	v_add_f32_e32 v229, v229, v230
	global_atomic_add_f32 v[156:157], v229, off
	s_or_b64 exec, exec, s[16:17]
	v_add_u32_e32 v144, 0x30, v154
	v_mov_b32_e32 v145, v155
	v_lshlrev_b64 v[148:149], 11, v[144:145]
	v_lshl_add_u64 v[148:149], v[148:149], 0, v[146:147]
	v_lshl_add_u64 v[150:151], v[148:149], 2, s[28:29]
	v_lshl_add_u64 v[152:153], v[148:149], 1, s[42:43]
	global_load_dwordx2 v[208:209], v[152:153], off
	global_load_dwordx4 v[192:195], v[150:151], off
	global_load_dwordx2 v[210:211], v[152:153], off offset:32
	global_load_dwordx4 v[196:199], v[150:151], off offset:64
	global_load_dwordx2 v[212:213], v[152:153], off offset:256
	global_load_dwordx4 v[200:203], v[150:151], off offset:512
	global_load_dwordx2 v[214:215], v[152:153], off offset:288
	global_load_dwordx4 v[204:207], v[150:151], off offset:576
	s_waitcnt vmcnt(15)
	v_fmamk_f32 v218, v218, 0x3a000000, v165
	v_mul_f32_e32 v235, 0x4b800000, v218
	v_cmp_gt_f32_e32 vcc, s47, v218
	s_nop 1
	v_cndmask_b32_e32 v218, v218, v235, vcc
	v_rsq_f32_e32 v218, v218
	s_nop 0
	v_mul_f32_e32 v235, 0x45800000, v218
	v_cndmask_b32_e32 v234, v218, v235, vcc
	v_add_u32_e32 v144, 0x20, v154
	v_mov_b32_e32 v145, v155
	v_lshlrev_b64 v[148:149], 11, v[144:145]
	v_lshl_add_u64 v[148:149], v[148:149], 0, v[146:147]
	v_lshl_add_u64 v[150:151], v[148:149], 2, s[28:29]
	v_lshl_add_u64 v[166:167], v[148:149], 1, s[24:25]
	v_add_co_u32_e32 v166, vcc, v166, v231
	s_nop 1
	v_addc_co_u32_e32 v167, vcc, 0, v167, vcc
	v_pk_mul_f32 v[92:93], v[92:93], v[234:235] op_sel_hi:[1,0]
	v_pk_mul_f32 v[94:95], v[94:95], v[234:235] op_sel_hi:[1,0]
	v_mul_f32_e32 v92, 0xbfb8aa3b, v92
	v_mul_f32_e32 v93, 0xbfb8aa3b, v93
	v_mul_f32_e32 v94, 0xbfb8aa3b, v94
	v_mul_f32_e32 v95, 0xbfb8aa3b, v95
	v_exp_f32_e32 v92, v92
	v_exp_f32_e32 v93, v93
	v_exp_f32_e32 v94, v94
	v_exp_f32_e32 v95, v95
	v_pk_add_f32 v[92:93], v[92:93], 1.0 op_sel_hi:[1,0]
	v_pk_add_f32 v[94:95], v[94:95], 1.0 op_sel_hi:[1,0]
	v_div_scale_f32 v224, s[16:17], v92, v92, 1.0
	v_rcp_f32_e32 v225, v224
	s_nop 0
	v_fma_f32 v226, -v224, v225, 1.0
	v_fmac_f32_e32 v225, v226, v225
	v_div_scale_f32 v226, vcc, 1.0, v92, 1.0
	v_mul_f32_e32 v227, v226, v225
	v_fma_f32 v228, -v224, v227, v226
	v_fmac_f32_e32 v227, v228, v225
	v_fma_f32 v224, -v224, v227, v226
	v_div_fmas_f32 v224, v224, v225, v227
	v_div_fixup_f32 v92, v224, v92, 1.0
	v_div_scale_f32 v224, s[16:17], v93, v93, 1.0
	v_rcp_f32_e32 v225, v224
	s_nop 0
	v_fma_f32 v226, -v224, v225, 1.0
	v_fmac_f32_e32 v225, v226, v225
	v_div_scale_f32 v226, vcc, 1.0, v93, 1.0
	v_mul_f32_e32 v227, v226, v225
	v_fma_f32 v228, -v224, v227, v226
	v_fmac_f32_e32 v227, v228, v225
	v_fma_f32 v224, -v224, v227, v226
	v_div_fmas_f32 v224, v224, v225, v227
	v_div_fixup_f32 v93, v224, v93, 1.0
	v_div_scale_f32 v224, s[16:17], v94, v94, 1.0
	v_rcp_f32_e32 v225, v224
	s_nop 0
	v_fma_f32 v226, -v224, v225, 1.0
	v_fmac_f32_e32 v225, v226, v225
	v_div_scale_f32 v226, vcc, 1.0, v94, 1.0
	v_mul_f32_e32 v227, v226, v225
	v_fma_f32 v228, -v224, v227, v226
	v_fmac_f32_e32 v227, v228, v225
	v_fma_f32 v224, -v224, v227, v226
	v_div_fmas_f32 v224, v224, v225, v227
	v_div_fixup_f32 v94, v224, v94, 1.0
	v_div_scale_f32 v224, s[16:17], v95, v95, 1.0
	v_rcp_f32_e32 v225, v224
	s_nop 0
	v_fma_f32 v226, -v224, v225, 1.0
	v_fmac_f32_e32 v225, v226, v225
	v_div_scale_f32 v226, vcc, 1.0, v95, 1.0
	v_mul_f32_e32 v227, v226, v225
	v_fma_f32 v228, -v224, v227, v226
	v_fmac_f32_e32 v227, v228, v225
	v_fma_f32 v224, -v224, v227, v226
	v_div_fmas_f32 v224, v224, v225, v227
	v_div_fixup_f32 v95, v224, v95, 1.0
	v_lshlrev_b32_e32 v236, 16, v184
	v_and_b32_e32 v237, 0xffff0000, v184
	v_lshlrev_b32_e32 v238, 16, v185
	v_and_b32_e32 v239, 0xffff0000, v185
	v_pk_fma_f32 v[92:93], v[92:93], v[236:237], v[168:169]
	v_pk_fma_f32 v[94:95], v[94:95], v[238:239], v[170:171]
	v_cvt_pk_bf16_f32 v157, v94, v95
	v_cvt_pk_bf16_f32 v156, v92, v93
	global_store_dwordx4 v[150:151], v[92:95], off
	s_nop 1
	v_mul_f32_e32 v93, v93, v93
	v_mul_f32_e32 v95, v95, v95
	v_fmac_f32_e32 v93, v92, v92
	v_fmac_f32_e32 v95, v94, v94
	v_add_f32_e32 v229, v93, v95
	v_pk_mul_f32 v[88:89], v[88:89], v[234:235] op_sel_hi:[1,0]
	v_pk_mul_f32 v[90:91], v[90:91], v[234:235] op_sel_hi:[1,0]
	v_mul_f32_e32 v88, 0xbfb8aa3b, v88
	v_mul_f32_e32 v89, 0xbfb8aa3b, v89
	v_mul_f32_e32 v90, 0xbfb8aa3b, v90
	v_mul_f32_e32 v91, 0xbfb8aa3b, v91
	v_exp_f32_e32 v88, v88
	v_exp_f32_e32 v89, v89
	v_exp_f32_e32 v90, v90
	v_exp_f32_e32 v91, v91
	v_pk_add_f32 v[88:89], v[88:89], 1.0 op_sel_hi:[1,0]
	v_pk_add_f32 v[90:91], v[90:91], 1.0 op_sel_hi:[1,0]
	v_div_scale_f32 v224, s[16:17], v88, v88, 1.0
	v_rcp_f32_e32 v225, v224
	s_nop 0
	v_fma_f32 v226, -v224, v225, 1.0
	v_fmac_f32_e32 v225, v226, v225
	v_div_scale_f32 v226, vcc, 1.0, v88, 1.0
	v_mul_f32_e32 v227, v226, v225
	v_fma_f32 v228, -v224, v227, v226
	v_fmac_f32_e32 v227, v228, v225
	v_fma_f32 v224, -v224, v227, v226
	v_div_fmas_f32 v224, v224, v225, v227
	v_div_fixup_f32 v88, v224, v88, 1.0
	v_div_scale_f32 v224, s[16:17], v89, v89, 1.0
	v_rcp_f32_e32 v225, v224
	s_nop 0
	v_fma_f32 v226, -v224, v225, 1.0
	v_fmac_f32_e32 v225, v226, v225
	v_div_scale_f32 v226, vcc, 1.0, v89, 1.0
	v_mul_f32_e32 v227, v226, v225
	v_fma_f32 v228, -v224, v227, v226
	v_fmac_f32_e32 v227, v228, v225
	v_fma_f32 v224, -v224, v227, v226
	v_div_fmas_f32 v224, v224, v225, v227
	v_div_fixup_f32 v89, v224, v89, 1.0
	v_div_scale_f32 v224, s[16:17], v90, v90, 1.0
	v_rcp_f32_e32 v225, v224
	s_nop 0
	v_fma_f32 v226, -v224, v225, 1.0
	v_fmac_f32_e32 v225, v226, v225
	v_div_scale_f32 v226, vcc, 1.0, v90, 1.0
	v_mul_f32_e32 v227, v226, v225
	v_fma_f32 v228, -v224, v227, v226
	v_fmac_f32_e32 v227, v228, v225
	v_fma_f32 v224, -v224, v227, v226
	v_div_fmas_f32 v224, v224, v225, v227
	v_div_fixup_f32 v90, v224, v90, 1.0
	v_div_scale_f32 v224, s[16:17], v91, v91, 1.0
	v_rcp_f32_e32 v225, v224
	s_nop 0
	v_fma_f32 v226, -v224, v225, 1.0
	v_fmac_f32_e32 v225, v226, v225
	v_div_scale_f32 v226, vcc, 1.0, v91, 1.0
	v_mul_f32_e32 v227, v226, v225
	v_fma_f32 v228, -v224, v227, v226
	v_fmac_f32_e32 v227, v228, v225
	v_fma_f32 v224, -v224, v227, v226
	v_div_fmas_f32 v224, v224, v225, v227
	v_div_fixup_f32 v91, v224, v91, 1.0
	v_lshlrev_b32_e32 v236, 16, v186
	v_and_b32_e32 v237, 0xffff0000, v186
	v_lshlrev_b32_e32 v238, 16, v187
	v_and_b32_e32 v239, 0xffff0000, v187
	v_pk_fma_f32 v[88:89], v[88:89], v[236:237], v[172:173]
	v_pk_fma_f32 v[90:91], v[90:91], v[238:239], v[174:175]
	v_cvt_pk_bf16_f32 v159, v90, v91
	v_cvt_pk_bf16_f32 v158, v88, v89
	global_store_dwordx4 v[150:151], v[88:91], off offset:64
	s_nop 1
	v_mul_f32_e32 v89, v89, v89
	v_mul_f32_e32 v91, v91, v91
	v_fmac_f32_e32 v89, v88, v88
	v_fmac_f32_e32 v91, v90, v90
	v_add_f32_e32 v88, v89, v91
	v_add_f32_e32 v229, v229, v88
	v_permlane16_swap_b32_e32 v156, v158
	v_permlane16_swap_b32_e32 v157, v159
	global_store_dwordx4 v[166:167], v[156:159], off
	s_nop 0
	v_pk_mul_f32 v[84:85], v[84:85], v[234:235] op_sel_hi:[1,0]
	v_pk_mul_f32 v[86:87], v[86:87], v[234:235] op_sel_hi:[1,0]
	v_mul_f32_e32 v84, 0xbfb8aa3b, v84
	v_mul_f32_e32 v85, 0xbfb8aa3b, v85
	v_mul_f32_e32 v86, 0xbfb8aa3b, v86
	v_mul_f32_e32 v87, 0xbfb8aa3b, v87
	v_exp_f32_e32 v84, v84
	v_exp_f32_e32 v85, v85
	v_exp_f32_e32 v86, v86
	v_exp_f32_e32 v87, v87
	v_pk_add_f32 v[84:85], v[84:85], 1.0 op_sel_hi:[1,0]
	v_pk_add_f32 v[86:87], v[86:87], 1.0 op_sel_hi:[1,0]
	v_div_scale_f32 v224, s[16:17], v84, v84, 1.0
	v_rcp_f32_e32 v225, v224
	s_nop 0
	v_fma_f32 v226, -v224, v225, 1.0
	v_fmac_f32_e32 v225, v226, v225
	v_div_scale_f32 v226, vcc, 1.0, v84, 1.0
	v_mul_f32_e32 v227, v226, v225
	v_fma_f32 v228, -v224, v227, v226
	v_fmac_f32_e32 v227, v228, v225
	v_fma_f32 v224, -v224, v227, v226
	v_div_fmas_f32 v224, v224, v225, v227
	v_div_fixup_f32 v84, v224, v84, 1.0
	v_div_scale_f32 v224, s[16:17], v85, v85, 1.0
	v_rcp_f32_e32 v225, v224
	s_nop 0
	v_fma_f32 v226, -v224, v225, 1.0
	v_fmac_f32_e32 v225, v226, v225
	v_div_scale_f32 v226, vcc, 1.0, v85, 1.0
	v_mul_f32_e32 v227, v226, v225
	v_fma_f32 v228, -v224, v227, v226
	v_fmac_f32_e32 v227, v228, v225
	v_fma_f32 v224, -v224, v227, v226
	v_div_fmas_f32 v224, v224, v225, v227
	v_div_fixup_f32 v85, v224, v85, 1.0
	v_div_scale_f32 v224, s[16:17], v86, v86, 1.0
	v_rcp_f32_e32 v225, v224
	s_nop 0
	v_fma_f32 v226, -v224, v225, 1.0
	v_fmac_f32_e32 v225, v226, v225
	v_div_scale_f32 v226, vcc, 1.0, v86, 1.0
	v_mul_f32_e32 v227, v226, v225
	v_fma_f32 v228, -v224, v227, v226
	v_fmac_f32_e32 v227, v228, v225
	v_fma_f32 v224, -v224, v227, v226
	v_div_fmas_f32 v224, v224, v225, v227
	v_div_fixup_f32 v86, v224, v86, 1.0
	v_div_scale_f32 v224, s[16:17], v87, v87, 1.0
	v_rcp_f32_e32 v225, v224
	s_nop 0
	v_fma_f32 v226, -v224, v225, 1.0
	v_fmac_f32_e32 v225, v226, v225
	v_div_scale_f32 v226, vcc, 1.0, v87, 1.0
	v_mul_f32_e32 v227, v226, v225
	v_fma_f32 v228, -v224, v227, v226
	v_fmac_f32_e32 v227, v228, v225
	v_fma_f32 v224, -v224, v227, v226
	v_div_fmas_f32 v224, v224, v225, v227
	v_div_fixup_f32 v87, v224, v87, 1.0
	v_lshlrev_b32_e32 v236, 16, v188
	v_and_b32_e32 v237, 0xffff0000, v188
	v_lshlrev_b32_e32 v238, 16, v189
	v_and_b32_e32 v239, 0xffff0000, v189
	v_pk_fma_f32 v[84:85], v[84:85], v[236:237], v[176:177]
	v_pk_fma_f32 v[86:87], v[86:87], v[238:239], v[178:179]
	v_cvt_pk_bf16_f32 v157, v86, v87
	v_cvt_pk_bf16_f32 v156, v84, v85
	global_store_dwordx4 v[150:151], v[84:87], off offset:512
	s_nop 1
	v_mul_f32_e32 v85, v85, v85
	v_mul_f32_e32 v87, v87, v87
	v_fmac_f32_e32 v85, v84, v84
	v_fmac_f32_e32 v87, v86, v86
	v_add_f32_e32 v84, v85, v87
	v_add_f32_e32 v229, v229, v84
	v_pk_mul_f32 v[80:81], v[80:81], v[234:235] op_sel_hi:[1,0]
	v_pk_mul_f32 v[82:83], v[82:83], v[234:235] op_sel_hi:[1,0]
	v_mul_f32_e32 v80, 0xbfb8aa3b, v80
	v_mul_f32_e32 v81, 0xbfb8aa3b, v81
	v_mul_f32_e32 v82, 0xbfb8aa3b, v82
	v_mul_f32_e32 v83, 0xbfb8aa3b, v83
	v_exp_f32_e32 v80, v80
	v_exp_f32_e32 v81, v81
	v_exp_f32_e32 v82, v82
	v_exp_f32_e32 v83, v83
	v_pk_add_f32 v[80:81], v[80:81], 1.0 op_sel_hi:[1,0]
	v_pk_add_f32 v[82:83], v[82:83], 1.0 op_sel_hi:[1,0]
	v_div_scale_f32 v224, s[16:17], v80, v80, 1.0
	v_rcp_f32_e32 v225, v224
	s_nop 0
	v_fma_f32 v226, -v224, v225, 1.0
	v_fmac_f32_e32 v225, v226, v225
	v_div_scale_f32 v226, vcc, 1.0, v80, 1.0
	v_mul_f32_e32 v227, v226, v225
	v_fma_f32 v228, -v224, v227, v226
	v_fmac_f32_e32 v227, v228, v225
	v_fma_f32 v224, -v224, v227, v226
	v_div_fmas_f32 v224, v224, v225, v227
	v_div_fixup_f32 v80, v224, v80, 1.0
	v_div_scale_f32 v224, s[16:17], v81, v81, 1.0
	v_rcp_f32_e32 v225, v224
	s_nop 0
	v_fma_f32 v226, -v224, v225, 1.0
	v_fmac_f32_e32 v225, v226, v225
	v_div_scale_f32 v226, vcc, 1.0, v81, 1.0
	v_mul_f32_e32 v227, v226, v225
	v_fma_f32 v228, -v224, v227, v226
	v_fmac_f32_e32 v227, v228, v225
	v_fma_f32 v224, -v224, v227, v226
	v_div_fmas_f32 v224, v224, v225, v227
	v_div_fixup_f32 v81, v224, v81, 1.0
	v_div_scale_f32 v224, s[16:17], v82, v82, 1.0
	v_rcp_f32_e32 v225, v224
	s_nop 0
	v_fma_f32 v226, -v224, v225, 1.0
	v_fmac_f32_e32 v225, v226, v225
	v_div_scale_f32 v226, vcc, 1.0, v82, 1.0
	v_mul_f32_e32 v227, v226, v225
	v_fma_f32 v228, -v224, v227, v226
	v_fmac_f32_e32 v227, v228, v225
	v_fma_f32 v224, -v224, v227, v226
	v_div_fmas_f32 v224, v224, v225, v227
	v_div_fixup_f32 v82, v224, v82, 1.0
	v_div_scale_f32 v224, s[16:17], v83, v83, 1.0
	v_rcp_f32_e32 v225, v224
	s_nop 0
	v_fma_f32 v226, -v224, v225, 1.0
	v_fmac_f32_e32 v225, v226, v225
	v_div_scale_f32 v226, vcc, 1.0, v83, 1.0
	v_mul_f32_e32 v227, v226, v225
	v_fma_f32 v228, -v224, v227, v226
	v_fmac_f32_e32 v227, v228, v225
	v_fma_f32 v224, -v224, v227, v226
	v_div_fmas_f32 v224, v224, v225, v227
	v_div_fixup_f32 v83, v224, v83, 1.0
	v_lshlrev_b32_e32 v236, 16, v190
	v_and_b32_e32 v237, 0xffff0000, v190
	v_lshlrev_b32_e32 v238, 16, v191
	v_and_b32_e32 v239, 0xffff0000, v191
	v_pk_fma_f32 v[80:81], v[80:81], v[236:237], v[180:181]
	v_pk_fma_f32 v[82:83], v[82:83], v[238:239], v[182:183]
	v_cvt_pk_bf16_f32 v159, v82, v83
	v_cvt_pk_bf16_f32 v158, v80, v81
	global_store_dwordx4 v[150:151], v[80:83], off offset:576
	s_nop 1
	v_mul_f32_e32 v81, v81, v81
	v_mul_f32_e32 v83, v83, v83
	v_fmac_f32_e32 v81, v80, v80
	v_fmac_f32_e32 v83, v82, v82
	v_add_f32_e32 v80, v81, v83
	v_add_f32_e32 v229, v229, v80
	v_permlane16_swap_b32_e32 v156, v158
	v_permlane16_swap_b32_e32 v157, v159
	global_store_dwordx4 v[166:167], v[156:159], off offset:256
	s_nop 0
	v_mov_b32_e32 v230, v229
	s_nop 1
	v_permlane16_swap_b32_e32 v229, v230
	v_add_f32_e32 v229, v229, v230
	v_mov_b32_e32 v230, v229
	s_nop 1
	v_permlane32_swap_b32_e32 v229, v230
	s_and_saveexec_b64 s[16:17], s[10:11]
	v_lshl_add_u64 v[156:157], v[144:145], 2, s[22:23]
	v_add_f32_e32 v229, v229, v230
	global_atomic_add_f32 v[156:157], v229, off
	s_or_b64 exec, exec, s[16:17]
	v_add_u32_e32 v144, 0x80, v154
	v_mov_b32_e32 v145, v155
	v_lshlrev_b64 v[148:149], 11, v[144:145]
	v_lshl_add_u64 v[148:149], v[148:149], 0, v[146:147]
	v_lshl_add_u64 v[150:151], v[148:149], 2, s[28:29]
	v_lshl_add_u64 v[152:153], v[148:149], 1, s[42:43]
	global_load_dwordx2 v[184:185], v[152:153], off
	global_load_dwordx4 v[168:171], v[150:151], off
	global_load_dwordx2 v[186:187], v[152:153], off offset:32
	global_load_dwordx4 v[172:175], v[150:151], off offset:64
	global_load_dwordx2 v[188:189], v[152:153], off offset:256
	global_load_dwordx4 v[176:179], v[150:151], off offset:512
	global_load_dwordx2 v[190:191], v[152:153], off offset:288
	global_load_dwordx4 v[180:183], v[150:151], off offset:576
	s_waitcnt vmcnt(15)
	v_fmamk_f32 v219, v219, 0x3a000000, v165
	v_mul_f32_e32 v235, 0x4b800000, v219
	v_cmp_gt_f32_e32 vcc, s47, v219
	s_nop 1
	v_cndmask_b32_e32 v219, v219, v235, vcc
	v_rsq_f32_e32 v219, v219
	s_nop 0
	v_mul_f32_e32 v235, 0x45800000, v219
	v_cndmask_b32_e32 v234, v219, v235, vcc
	v_add_u32_e32 v144, 0x30, v154
	v_mov_b32_e32 v145, v155
	v_lshlrev_b64 v[148:149], 11, v[144:145]
	v_lshl_add_u64 v[148:149], v[148:149], 0, v[146:147]
	v_lshl_add_u64 v[150:151], v[148:149], 2, s[28:29]
	v_lshl_add_u64 v[166:167], v[148:149], 1, s[24:25]
	v_add_co_u32_e32 v166, vcc, v166, v231
	s_nop 1
	v_addc_co_u32_e32 v167, vcc, 0, v167, vcc
	v_pk_mul_f32 v[76:77], v[76:77], v[234:235] op_sel_hi:[1,0]
	v_pk_mul_f32 v[78:79], v[78:79], v[234:235] op_sel_hi:[1,0]
	v_mul_f32_e32 v76, 0xbfb8aa3b, v76
	v_mul_f32_e32 v77, 0xbfb8aa3b, v77
	v_mul_f32_e32 v78, 0xbfb8aa3b, v78
	v_mul_f32_e32 v79, 0xbfb8aa3b, v79
	v_exp_f32_e32 v76, v76
	v_exp_f32_e32 v77, v77
	v_exp_f32_e32 v78, v78
	v_exp_f32_e32 v79, v79
	v_pk_add_f32 v[76:77], v[76:77], 1.0 op_sel_hi:[1,0]
	v_pk_add_f32 v[78:79], v[78:79], 1.0 op_sel_hi:[1,0]
	v_div_scale_f32 v224, s[16:17], v76, v76, 1.0
	v_rcp_f32_e32 v225, v224
	s_nop 0
	v_fma_f32 v226, -v224, v225, 1.0
	v_fmac_f32_e32 v225, v226, v225
	v_div_scale_f32 v226, vcc, 1.0, v76, 1.0
	v_mul_f32_e32 v227, v226, v225
	v_fma_f32 v228, -v224, v227, v226
	v_fmac_f32_e32 v227, v228, v225
	v_fma_f32 v224, -v224, v227, v226
	v_div_fmas_f32 v224, v224, v225, v227
	v_div_fixup_f32 v76, v224, v76, 1.0
	v_div_scale_f32 v224, s[16:17], v77, v77, 1.0
	v_rcp_f32_e32 v225, v224
	s_nop 0
	v_fma_f32 v226, -v224, v225, 1.0
	v_fmac_f32_e32 v225, v226, v225
	v_div_scale_f32 v226, vcc, 1.0, v77, 1.0
	v_mul_f32_e32 v227, v226, v225
	v_fma_f32 v228, -v224, v227, v226
	v_fmac_f32_e32 v227, v228, v225
	v_fma_f32 v224, -v224, v227, v226
	v_div_fmas_f32 v224, v224, v225, v227
	v_div_fixup_f32 v77, v224, v77, 1.0
	v_div_scale_f32 v224, s[16:17], v78, v78, 1.0
	v_rcp_f32_e32 v225, v224
	s_nop 0
	v_fma_f32 v226, -v224, v225, 1.0
	v_fmac_f32_e32 v225, v226, v225
	v_div_scale_f32 v226, vcc, 1.0, v78, 1.0
	v_mul_f32_e32 v227, v226, v225
	v_fma_f32 v228, -v224, v227, v226
	v_fmac_f32_e32 v227, v228, v225
	v_fma_f32 v224, -v224, v227, v226
	v_div_fmas_f32 v224, v224, v225, v227
	v_div_fixup_f32 v78, v224, v78, 1.0
	v_div_scale_f32 v224, s[16:17], v79, v79, 1.0
	v_rcp_f32_e32 v225, v224
	s_nop 0
	v_fma_f32 v226, -v224, v225, 1.0
	v_fmac_f32_e32 v225, v226, v225
	v_div_scale_f32 v226, vcc, 1.0, v79, 1.0
	v_mul_f32_e32 v227, v226, v225
	v_fma_f32 v228, -v224, v227, v226
	v_fmac_f32_e32 v227, v228, v225
	v_fma_f32 v224, -v224, v227, v226
	v_div_fmas_f32 v224, v224, v225, v227
	v_div_fixup_f32 v79, v224, v79, 1.0
	v_lshlrev_b32_e32 v236, 16, v208
	v_and_b32_e32 v237, 0xffff0000, v208
	v_lshlrev_b32_e32 v238, 16, v209
	v_and_b32_e32 v239, 0xffff0000, v209
	v_pk_fma_f32 v[76:77], v[76:77], v[236:237], v[192:193]
	v_pk_fma_f32 v[78:79], v[78:79], v[238:239], v[194:195]
	v_cvt_pk_bf16_f32 v157, v78, v79
	v_cvt_pk_bf16_f32 v156, v76, v77
	global_store_dwordx4 v[150:151], v[76:79], off
	s_nop 1
	v_mul_f32_e32 v77, v77, v77
	v_mul_f32_e32 v79, v79, v79
	v_fmac_f32_e32 v77, v76, v76
	v_fmac_f32_e32 v79, v78, v78
	v_add_f32_e32 v229, v77, v79
	v_pk_mul_f32 v[72:73], v[72:73], v[234:235] op_sel_hi:[1,0]
	v_pk_mul_f32 v[74:75], v[74:75], v[234:235] op_sel_hi:[1,0]
	v_mul_f32_e32 v72, 0xbfb8aa3b, v72
	v_mul_f32_e32 v73, 0xbfb8aa3b, v73
	v_mul_f32_e32 v74, 0xbfb8aa3b, v74
	v_mul_f32_e32 v75, 0xbfb8aa3b, v75
	v_exp_f32_e32 v72, v72
	v_exp_f32_e32 v73, v73
	v_exp_f32_e32 v74, v74
	v_exp_f32_e32 v75, v75
	v_pk_add_f32 v[72:73], v[72:73], 1.0 op_sel_hi:[1,0]
	v_pk_add_f32 v[74:75], v[74:75], 1.0 op_sel_hi:[1,0]
	v_div_scale_f32 v224, s[16:17], v72, v72, 1.0
	v_rcp_f32_e32 v225, v224
	s_nop 0
	v_fma_f32 v226, -v224, v225, 1.0
	v_fmac_f32_e32 v225, v226, v225
	v_div_scale_f32 v226, vcc, 1.0, v72, 1.0
	v_mul_f32_e32 v227, v226, v225
	v_fma_f32 v228, -v224, v227, v226
	v_fmac_f32_e32 v227, v228, v225
	v_fma_f32 v224, -v224, v227, v226
	v_div_fmas_f32 v224, v224, v225, v227
	v_div_fixup_f32 v72, v224, v72, 1.0
	v_div_scale_f32 v224, s[16:17], v73, v73, 1.0
	v_rcp_f32_e32 v225, v224
	s_nop 0
	v_fma_f32 v226, -v224, v225, 1.0
	v_fmac_f32_e32 v225, v226, v225
	v_div_scale_f32 v226, vcc, 1.0, v73, 1.0
	v_mul_f32_e32 v227, v226, v225
	v_fma_f32 v228, -v224, v227, v226
	v_fmac_f32_e32 v227, v228, v225
	v_fma_f32 v224, -v224, v227, v226
	v_div_fmas_f32 v224, v224, v225, v227
	v_div_fixup_f32 v73, v224, v73, 1.0
	v_div_scale_f32 v224, s[16:17], v74, v74, 1.0
	v_rcp_f32_e32 v225, v224
	s_nop 0
	v_fma_f32 v226, -v224, v225, 1.0
	v_fmac_f32_e32 v225, v226, v225
	v_div_scale_f32 v226, vcc, 1.0, v74, 1.0
	v_mul_f32_e32 v227, v226, v225
	v_fma_f32 v228, -v224, v227, v226
	v_fmac_f32_e32 v227, v228, v225
	v_fma_f32 v224, -v224, v227, v226
	v_div_fmas_f32 v224, v224, v225, v227
	v_div_fixup_f32 v74, v224, v74, 1.0
	v_div_scale_f32 v224, s[16:17], v75, v75, 1.0
	v_rcp_f32_e32 v225, v224
	s_nop 0
	v_fma_f32 v226, -v224, v225, 1.0
	v_fmac_f32_e32 v225, v226, v225
	v_div_scale_f32 v226, vcc, 1.0, v75, 1.0
	v_mul_f32_e32 v227, v226, v225
	v_fma_f32 v228, -v224, v227, v226
	v_fmac_f32_e32 v227, v228, v225
	v_fma_f32 v224, -v224, v227, v226
	v_div_fmas_f32 v224, v224, v225, v227
	v_div_fixup_f32 v75, v224, v75, 1.0
	v_lshlrev_b32_e32 v236, 16, v210
	v_and_b32_e32 v237, 0xffff0000, v210
	v_lshlrev_b32_e32 v238, 16, v211
	v_and_b32_e32 v239, 0xffff0000, v211
	v_pk_fma_f32 v[72:73], v[72:73], v[236:237], v[196:197]
	v_pk_fma_f32 v[74:75], v[74:75], v[238:239], v[198:199]
	v_cvt_pk_bf16_f32 v159, v74, v75
	v_cvt_pk_bf16_f32 v158, v72, v73
	global_store_dwordx4 v[150:151], v[72:75], off offset:64
	s_nop 1
	v_mul_f32_e32 v73, v73, v73
	v_mul_f32_e32 v75, v75, v75
	v_fmac_f32_e32 v73, v72, v72
	v_fmac_f32_e32 v75, v74, v74
	v_add_f32_e32 v72, v73, v75
	v_add_f32_e32 v229, v229, v72
	v_permlane16_swap_b32_e32 v156, v158
	v_permlane16_swap_b32_e32 v157, v159
	global_store_dwordx4 v[166:167], v[156:159], off
	s_nop 0
	v_pk_mul_f32 v[68:69], v[68:69], v[234:235] op_sel_hi:[1,0]
	v_pk_mul_f32 v[70:71], v[70:71], v[234:235] op_sel_hi:[1,0]
	v_mul_f32_e32 v68, 0xbfb8aa3b, v68
	v_mul_f32_e32 v69, 0xbfb8aa3b, v69
	v_mul_f32_e32 v70, 0xbfb8aa3b, v70
	v_mul_f32_e32 v71, 0xbfb8aa3b, v71
	v_exp_f32_e32 v68, v68
	v_exp_f32_e32 v69, v69
	v_exp_f32_e32 v70, v70
	v_exp_f32_e32 v71, v71
	v_pk_add_f32 v[68:69], v[68:69], 1.0 op_sel_hi:[1,0]
	v_pk_add_f32 v[70:71], v[70:71], 1.0 op_sel_hi:[1,0]
	v_div_scale_f32 v224, s[16:17], v68, v68, 1.0
	v_rcp_f32_e32 v225, v224
	s_nop 0
	v_fma_f32 v226, -v224, v225, 1.0
	v_fmac_f32_e32 v225, v226, v225
	v_div_scale_f32 v226, vcc, 1.0, v68, 1.0
	v_mul_f32_e32 v227, v226, v225
	v_fma_f32 v228, -v224, v227, v226
	v_fmac_f32_e32 v227, v228, v225
	v_fma_f32 v224, -v224, v227, v226
	v_div_fmas_f32 v224, v224, v225, v227
	v_div_fixup_f32 v68, v224, v68, 1.0
	v_div_scale_f32 v224, s[16:17], v69, v69, 1.0
	v_rcp_f32_e32 v225, v224
	s_nop 0
	v_fma_f32 v226, -v224, v225, 1.0
	v_fmac_f32_e32 v225, v226, v225
	v_div_scale_f32 v226, vcc, 1.0, v69, 1.0
	v_mul_f32_e32 v227, v226, v225
	v_fma_f32 v228, -v224, v227, v226
	v_fmac_f32_e32 v227, v228, v225
	v_fma_f32 v224, -v224, v227, v226
	v_div_fmas_f32 v224, v224, v225, v227
	v_div_fixup_f32 v69, v224, v69, 1.0
	v_div_scale_f32 v224, s[16:17], v70, v70, 1.0
	v_rcp_f32_e32 v225, v224
	s_nop 0
	v_fma_f32 v226, -v224, v225, 1.0
	v_fmac_f32_e32 v225, v226, v225
	v_div_scale_f32 v226, vcc, 1.0, v70, 1.0
	v_mul_f32_e32 v227, v226, v225
	v_fma_f32 v228, -v224, v227, v226
	v_fmac_f32_e32 v227, v228, v225
	v_fma_f32 v224, -v224, v227, v226
	v_div_fmas_f32 v224, v224, v225, v227
	v_div_fixup_f32 v70, v224, v70, 1.0
	v_div_scale_f32 v224, s[16:17], v71, v71, 1.0
	v_rcp_f32_e32 v225, v224
	s_nop 0
	v_fma_f32 v226, -v224, v225, 1.0
	v_fmac_f32_e32 v225, v226, v225
	v_div_scale_f32 v226, vcc, 1.0, v71, 1.0
	v_mul_f32_e32 v227, v226, v225
	v_fma_f32 v228, -v224, v227, v226
	v_fmac_f32_e32 v227, v228, v225
	v_fma_f32 v224, -v224, v227, v226
	v_div_fmas_f32 v224, v224, v225, v227
	v_div_fixup_f32 v71, v224, v71, 1.0
	v_lshlrev_b32_e32 v236, 16, v212
	v_and_b32_e32 v237, 0xffff0000, v212
	v_lshlrev_b32_e32 v238, 16, v213
	v_and_b32_e32 v239, 0xffff0000, v213
	v_pk_fma_f32 v[68:69], v[68:69], v[236:237], v[200:201]
	v_pk_fma_f32 v[70:71], v[70:71], v[238:239], v[202:203]
	v_cvt_pk_bf16_f32 v157, v70, v71
	v_cvt_pk_bf16_f32 v156, v68, v69
	global_store_dwordx4 v[150:151], v[68:71], off offset:512
	s_nop 1
	v_mul_f32_e32 v69, v69, v69
	v_mul_f32_e32 v71, v71, v71
	v_fmac_f32_e32 v69, v68, v68
	v_fmac_f32_e32 v71, v70, v70
	v_add_f32_e32 v68, v69, v71
	v_add_f32_e32 v229, v229, v68
	v_pk_mul_f32 v[64:65], v[64:65], v[234:235] op_sel_hi:[1,0]
	v_pk_mul_f32 v[66:67], v[66:67], v[234:235] op_sel_hi:[1,0]
	v_mul_f32_e32 v64, 0xbfb8aa3b, v64
	v_mul_f32_e32 v65, 0xbfb8aa3b, v65
	v_mul_f32_e32 v66, 0xbfb8aa3b, v66
	v_mul_f32_e32 v67, 0xbfb8aa3b, v67
	v_exp_f32_e32 v64, v64
	v_exp_f32_e32 v65, v65
	v_exp_f32_e32 v66, v66
	v_exp_f32_e32 v67, v67
	v_pk_add_f32 v[64:65], v[64:65], 1.0 op_sel_hi:[1,0]
	v_pk_add_f32 v[66:67], v[66:67], 1.0 op_sel_hi:[1,0]
	v_div_scale_f32 v224, s[16:17], v64, v64, 1.0
	v_rcp_f32_e32 v225, v224
	s_nop 0
	v_fma_f32 v226, -v224, v225, 1.0
	v_fmac_f32_e32 v225, v226, v225
	v_div_scale_f32 v226, vcc, 1.0, v64, 1.0
	v_mul_f32_e32 v227, v226, v225
	v_fma_f32 v228, -v224, v227, v226
	v_fmac_f32_e32 v227, v228, v225
	v_fma_f32 v224, -v224, v227, v226
	v_div_fmas_f32 v224, v224, v225, v227
	v_div_fixup_f32 v64, v224, v64, 1.0
	v_div_scale_f32 v224, s[16:17], v65, v65, 1.0
	v_rcp_f32_e32 v225, v224
	s_nop 0
	v_fma_f32 v226, -v224, v225, 1.0
	v_fmac_f32_e32 v225, v226, v225
	v_div_scale_f32 v226, vcc, 1.0, v65, 1.0
	v_mul_f32_e32 v227, v226, v225
	v_fma_f32 v228, -v224, v227, v226
	v_fmac_f32_e32 v227, v228, v225
	v_fma_f32 v224, -v224, v227, v226
	v_div_fmas_f32 v224, v224, v225, v227
	v_div_fixup_f32 v65, v224, v65, 1.0
	v_div_scale_f32 v224, s[16:17], v66, v66, 1.0
	v_rcp_f32_e32 v225, v224
	s_nop 0
	v_fma_f32 v226, -v224, v225, 1.0
	v_fmac_f32_e32 v225, v226, v225
	v_div_scale_f32 v226, vcc, 1.0, v66, 1.0
	v_mul_f32_e32 v227, v226, v225
	v_fma_f32 v228, -v224, v227, v226
	v_fmac_f32_e32 v227, v228, v225
	v_fma_f32 v224, -v224, v227, v226
	v_div_fmas_f32 v224, v224, v225, v227
	v_div_fixup_f32 v66, v224, v66, 1.0
	v_div_scale_f32 v224, s[16:17], v67, v67, 1.0
	v_rcp_f32_e32 v225, v224
	s_nop 0
	v_fma_f32 v226, -v224, v225, 1.0
	v_fmac_f32_e32 v225, v226, v225
	v_div_scale_f32 v226, vcc, 1.0, v67, 1.0
	v_mul_f32_e32 v227, v226, v225
	v_fma_f32 v228, -v224, v227, v226
	v_fmac_f32_e32 v227, v228, v225
	v_fma_f32 v224, -v224, v227, v226
	v_div_fmas_f32 v224, v224, v225, v227
	v_div_fixup_f32 v67, v224, v67, 1.0
	v_lshlrev_b32_e32 v236, 16, v214
	v_and_b32_e32 v237, 0xffff0000, v214
	v_lshlrev_b32_e32 v238, 16, v215
	v_and_b32_e32 v239, 0xffff0000, v215
	v_pk_fma_f32 v[64:65], v[64:65], v[236:237], v[204:205]
	v_pk_fma_f32 v[66:67], v[66:67], v[238:239], v[206:207]
	v_cvt_pk_bf16_f32 v159, v66, v67
	v_cvt_pk_bf16_f32 v158, v64, v65
	global_store_dwordx4 v[150:151], v[64:67], off offset:576
	s_nop 1
	v_mul_f32_e32 v65, v65, v65
	v_mul_f32_e32 v67, v67, v67
	v_fmac_f32_e32 v65, v64, v64
	v_fmac_f32_e32 v67, v66, v66
	v_add_f32_e32 v64, v65, v67
	v_add_f32_e32 v229, v229, v64
	v_permlane16_swap_b32_e32 v156, v158
	v_permlane16_swap_b32_e32 v157, v159
	global_store_dwordx4 v[166:167], v[156:159], off offset:256
	s_nop 0
	v_mov_b32_e32 v230, v229
	s_nop 1
	v_permlane16_swap_b32_e32 v229, v230
	v_add_f32_e32 v229, v229, v230
	v_mov_b32_e32 v230, v229
	s_nop 1
	v_permlane32_swap_b32_e32 v229, v230
	s_and_saveexec_b64 s[16:17], s[10:11]
	v_lshl_add_u64 v[156:157], v[144:145], 2, s[22:23]
	v_add_f32_e32 v229, v229, v230
	global_atomic_add_f32 v[156:157], v229, off
	s_or_b64 exec, exec, s[16:17]
	v_add_u32_e32 v144, 0x90, v154
	v_mov_b32_e32 v145, v155
	v_lshlrev_b64 v[148:149], 11, v[144:145]
	v_lshl_add_u64 v[148:149], v[148:149], 0, v[146:147]
	v_lshl_add_u64 v[150:151], v[148:149], 2, s[28:29]
	v_lshl_add_u64 v[152:153], v[148:149], 1, s[42:43]
	global_load_dwordx2 v[208:209], v[152:153], off
	global_load_dwordx4 v[192:195], v[150:151], off
	global_load_dwordx2 v[210:211], v[152:153], off offset:32
	global_load_dwordx4 v[196:199], v[150:151], off offset:64
	global_load_dwordx2 v[212:213], v[152:153], off offset:256
	global_load_dwordx4 v[200:203], v[150:151], off offset:512
	global_load_dwordx2 v[214:215], v[152:153], off offset:288
	global_load_dwordx4 v[204:207], v[150:151], off offset:576
	s_waitcnt vmcnt(15)
	v_fmamk_f32 v220, v220, 0x3a000000, v165
	v_mul_f32_e32 v235, 0x4b800000, v220
	v_cmp_gt_f32_e32 vcc, s47, v220
	s_nop 1
	v_cndmask_b32_e32 v220, v220, v235, vcc
	v_rsq_f32_e32 v220, v220
	s_nop 0
	v_mul_f32_e32 v235, 0x45800000, v220
	v_cndmask_b32_e32 v234, v220, v235, vcc
	v_add_u32_e32 v144, 0x80, v154
	v_mov_b32_e32 v145, v155
	v_lshlrev_b64 v[148:149], 11, v[144:145]
	v_lshl_add_u64 v[148:149], v[148:149], 0, v[146:147]
	v_lshl_add_u64 v[150:151], v[148:149], 2, s[28:29]
	v_lshl_add_u64 v[166:167], v[148:149], 1, s[24:25]
	v_add_co_u32_e32 v166, vcc, v166, v231
	s_nop 1
	v_addc_co_u32_e32 v167, vcc, 0, v167, vcc
	v_pk_mul_f32 v[60:61], v[60:61], v[234:235] op_sel_hi:[1,0]
	v_pk_mul_f32 v[62:63], v[62:63], v[234:235] op_sel_hi:[1,0]
	v_mul_f32_e32 v60, 0xbfb8aa3b, v60
	v_mul_f32_e32 v61, 0xbfb8aa3b, v61
	v_mul_f32_e32 v62, 0xbfb8aa3b, v62
	v_mul_f32_e32 v63, 0xbfb8aa3b, v63
	v_exp_f32_e32 v60, v60
	v_exp_f32_e32 v61, v61
	v_exp_f32_e32 v62, v62
	v_exp_f32_e32 v63, v63
	v_pk_add_f32 v[60:61], v[60:61], 1.0 op_sel_hi:[1,0]
	v_pk_add_f32 v[62:63], v[62:63], 1.0 op_sel_hi:[1,0]
	v_div_scale_f32 v224, s[16:17], v60, v60, 1.0
	v_rcp_f32_e32 v225, v224
	s_nop 0
	v_fma_f32 v226, -v224, v225, 1.0
	v_fmac_f32_e32 v225, v226, v225
	v_div_scale_f32 v226, vcc, 1.0, v60, 1.0
	v_mul_f32_e32 v227, v226, v225
	v_fma_f32 v228, -v224, v227, v226
	v_fmac_f32_e32 v227, v228, v225
	v_fma_f32 v224, -v224, v227, v226
	v_div_fmas_f32 v224, v224, v225, v227
	v_div_fixup_f32 v60, v224, v60, 1.0
	v_div_scale_f32 v224, s[16:17], v61, v61, 1.0
	v_rcp_f32_e32 v225, v224
	s_nop 0
	v_fma_f32 v226, -v224, v225, 1.0
	v_fmac_f32_e32 v225, v226, v225
	v_div_scale_f32 v226, vcc, 1.0, v61, 1.0
	v_mul_f32_e32 v227, v226, v225
	v_fma_f32 v228, -v224, v227, v226
	v_fmac_f32_e32 v227, v228, v225
	v_fma_f32 v224, -v224, v227, v226
	v_div_fmas_f32 v224, v224, v225, v227
	v_div_fixup_f32 v61, v224, v61, 1.0
	v_div_scale_f32 v224, s[16:17], v62, v62, 1.0
	v_rcp_f32_e32 v225, v224
	s_nop 0
	v_fma_f32 v226, -v224, v225, 1.0
	v_fmac_f32_e32 v225, v226, v225
	v_div_scale_f32 v226, vcc, 1.0, v62, 1.0
	v_mul_f32_e32 v227, v226, v225
	v_fma_f32 v228, -v224, v227, v226
	v_fmac_f32_e32 v227, v228, v225
	v_fma_f32 v224, -v224, v227, v226
	v_div_fmas_f32 v224, v224, v225, v227
	v_div_fixup_f32 v62, v224, v62, 1.0
	v_div_scale_f32 v224, s[16:17], v63, v63, 1.0
	v_rcp_f32_e32 v225, v224
	s_nop 0
	v_fma_f32 v226, -v224, v225, 1.0
	v_fmac_f32_e32 v225, v226, v225
	v_div_scale_f32 v226, vcc, 1.0, v63, 1.0
	v_mul_f32_e32 v227, v226, v225
	v_fma_f32 v228, -v224, v227, v226
	v_fmac_f32_e32 v227, v228, v225
	v_fma_f32 v224, -v224, v227, v226
	v_div_fmas_f32 v224, v224, v225, v227
	v_div_fixup_f32 v63, v224, v63, 1.0
	v_lshlrev_b32_e32 v236, 16, v184
	v_and_b32_e32 v237, 0xffff0000, v184
	v_lshlrev_b32_e32 v238, 16, v185
	v_and_b32_e32 v239, 0xffff0000, v185
	v_pk_fma_f32 v[60:61], v[60:61], v[236:237], v[168:169]
	v_pk_fma_f32 v[62:63], v[62:63], v[238:239], v[170:171]
	v_cvt_pk_bf16_f32 v157, v62, v63
	v_cvt_pk_bf16_f32 v156, v60, v61
	global_store_dwordx4 v[150:151], v[60:63], off
	s_nop 1
	v_mul_f32_e32 v61, v61, v61
	v_mul_f32_e32 v63, v63, v63
	v_fmac_f32_e32 v61, v60, v60
	v_fmac_f32_e32 v63, v62, v62
	v_add_f32_e32 v229, v61, v63
	v_pk_mul_f32 v[56:57], v[56:57], v[234:235] op_sel_hi:[1,0]
	v_pk_mul_f32 v[58:59], v[58:59], v[234:235] op_sel_hi:[1,0]
	v_mul_f32_e32 v56, 0xbfb8aa3b, v56
	v_mul_f32_e32 v57, 0xbfb8aa3b, v57
	v_mul_f32_e32 v58, 0xbfb8aa3b, v58
	v_mul_f32_e32 v59, 0xbfb8aa3b, v59
	v_exp_f32_e32 v56, v56
	v_exp_f32_e32 v57, v57
	v_exp_f32_e32 v58, v58
	v_exp_f32_e32 v59, v59
	v_pk_add_f32 v[56:57], v[56:57], 1.0 op_sel_hi:[1,0]
	v_pk_add_f32 v[58:59], v[58:59], 1.0 op_sel_hi:[1,0]
	v_div_scale_f32 v224, s[16:17], v56, v56, 1.0
	v_rcp_f32_e32 v225, v224
	s_nop 0
	v_fma_f32 v226, -v224, v225, 1.0
	v_fmac_f32_e32 v225, v226, v225
	v_div_scale_f32 v226, vcc, 1.0, v56, 1.0
	v_mul_f32_e32 v227, v226, v225
	v_fma_f32 v228, -v224, v227, v226
	v_fmac_f32_e32 v227, v228, v225
	v_fma_f32 v224, -v224, v227, v226
	v_div_fmas_f32 v224, v224, v225, v227
	v_div_fixup_f32 v56, v224, v56, 1.0
	v_div_scale_f32 v224, s[16:17], v57, v57, 1.0
	v_rcp_f32_e32 v225, v224
	s_nop 0
	v_fma_f32 v226, -v224, v225, 1.0
	v_fmac_f32_e32 v225, v226, v225
	v_div_scale_f32 v226, vcc, 1.0, v57, 1.0
	v_mul_f32_e32 v227, v226, v225
	v_fma_f32 v228, -v224, v227, v226
	v_fmac_f32_e32 v227, v228, v225
	v_fma_f32 v224, -v224, v227, v226
	v_div_fmas_f32 v224, v224, v225, v227
	v_div_fixup_f32 v57, v224, v57, 1.0
	v_div_scale_f32 v224, s[16:17], v58, v58, 1.0
	v_rcp_f32_e32 v225, v224
	s_nop 0
	v_fma_f32 v226, -v224, v225, 1.0
	v_fmac_f32_e32 v225, v226, v225
	v_div_scale_f32 v226, vcc, 1.0, v58, 1.0
	v_mul_f32_e32 v227, v226, v225
	v_fma_f32 v228, -v224, v227, v226
	v_fmac_f32_e32 v227, v228, v225
	v_fma_f32 v224, -v224, v227, v226
	v_div_fmas_f32 v224, v224, v225, v227
	v_div_fixup_f32 v58, v224, v58, 1.0
	v_div_scale_f32 v224, s[16:17], v59, v59, 1.0
	v_rcp_f32_e32 v225, v224
	s_nop 0
	v_fma_f32 v226, -v224, v225, 1.0
	v_fmac_f32_e32 v225, v226, v225
	v_div_scale_f32 v226, vcc, 1.0, v59, 1.0
	v_mul_f32_e32 v227, v226, v225
	v_fma_f32 v228, -v224, v227, v226
	v_fmac_f32_e32 v227, v228, v225
	v_fma_f32 v224, -v224, v227, v226
	v_div_fmas_f32 v224, v224, v225, v227
	v_div_fixup_f32 v59, v224, v59, 1.0
	v_lshlrev_b32_e32 v236, 16, v186
	v_and_b32_e32 v237, 0xffff0000, v186
	v_lshlrev_b32_e32 v238, 16, v187
	v_and_b32_e32 v239, 0xffff0000, v187
	v_pk_fma_f32 v[56:57], v[56:57], v[236:237], v[172:173]
	v_pk_fma_f32 v[58:59], v[58:59], v[238:239], v[174:175]
	v_cvt_pk_bf16_f32 v159, v58, v59
	v_cvt_pk_bf16_f32 v158, v56, v57
	global_store_dwordx4 v[150:151], v[56:59], off offset:64
	s_nop 1
	v_mul_f32_e32 v57, v57, v57
	v_mul_f32_e32 v59, v59, v59
	v_fmac_f32_e32 v57, v56, v56
	v_fmac_f32_e32 v59, v58, v58
	v_add_f32_e32 v56, v57, v59
	v_add_f32_e32 v229, v229, v56
	v_permlane16_swap_b32_e32 v156, v158
	v_permlane16_swap_b32_e32 v157, v159
	global_store_dwordx4 v[166:167], v[156:159], off
	s_nop 0
	v_pk_mul_f32 v[52:53], v[52:53], v[234:235] op_sel_hi:[1,0]
	v_pk_mul_f32 v[54:55], v[54:55], v[234:235] op_sel_hi:[1,0]
	v_mul_f32_e32 v52, 0xbfb8aa3b, v52
	v_mul_f32_e32 v53, 0xbfb8aa3b, v53
	v_mul_f32_e32 v54, 0xbfb8aa3b, v54
	v_mul_f32_e32 v55, 0xbfb8aa3b, v55
	v_exp_f32_e32 v52, v52
	v_exp_f32_e32 v53, v53
	v_exp_f32_e32 v54, v54
	v_exp_f32_e32 v55, v55
	v_pk_add_f32 v[52:53], v[52:53], 1.0 op_sel_hi:[1,0]
	v_pk_add_f32 v[54:55], v[54:55], 1.0 op_sel_hi:[1,0]
	v_div_scale_f32 v224, s[16:17], v52, v52, 1.0
	v_rcp_f32_e32 v225, v224
	s_nop 0
	v_fma_f32 v226, -v224, v225, 1.0
	v_fmac_f32_e32 v225, v226, v225
	v_div_scale_f32 v226, vcc, 1.0, v52, 1.0
	v_mul_f32_e32 v227, v226, v225
	v_fma_f32 v228, -v224, v227, v226
	v_fmac_f32_e32 v227, v228, v225
	v_fma_f32 v224, -v224, v227, v226
	v_div_fmas_f32 v224, v224, v225, v227
	v_div_fixup_f32 v52, v224, v52, 1.0
	v_div_scale_f32 v224, s[16:17], v53, v53, 1.0
	v_rcp_f32_e32 v225, v224
	s_nop 0
	v_fma_f32 v226, -v224, v225, 1.0
	v_fmac_f32_e32 v225, v226, v225
	v_div_scale_f32 v226, vcc, 1.0, v53, 1.0
	v_mul_f32_e32 v227, v226, v225
	v_fma_f32 v228, -v224, v227, v226
	v_fmac_f32_e32 v227, v228, v225
	v_fma_f32 v224, -v224, v227, v226
	v_div_fmas_f32 v224, v224, v225, v227
	v_div_fixup_f32 v53, v224, v53, 1.0
	v_div_scale_f32 v224, s[16:17], v54, v54, 1.0
	v_rcp_f32_e32 v225, v224
	s_nop 0
	v_fma_f32 v226, -v224, v225, 1.0
	v_fmac_f32_e32 v225, v226, v225
	v_div_scale_f32 v226, vcc, 1.0, v54, 1.0
	v_mul_f32_e32 v227, v226, v225
	v_fma_f32 v228, -v224, v227, v226
	v_fmac_f32_e32 v227, v228, v225
	v_fma_f32 v224, -v224, v227, v226
	v_div_fmas_f32 v224, v224, v225, v227
	v_div_fixup_f32 v54, v224, v54, 1.0
	v_div_scale_f32 v224, s[16:17], v55, v55, 1.0
	v_rcp_f32_e32 v225, v224
	s_nop 0
	v_fma_f32 v226, -v224, v225, 1.0
	v_fmac_f32_e32 v225, v226, v225
	v_div_scale_f32 v226, vcc, 1.0, v55, 1.0
	v_mul_f32_e32 v227, v226, v225
	v_fma_f32 v228, -v224, v227, v226
	v_fmac_f32_e32 v227, v228, v225
	v_fma_f32 v224, -v224, v227, v226
	v_div_fmas_f32 v224, v224, v225, v227
	v_div_fixup_f32 v55, v224, v55, 1.0
	v_lshlrev_b32_e32 v236, 16, v188
	v_and_b32_e32 v237, 0xffff0000, v188
	v_lshlrev_b32_e32 v238, 16, v189
	v_and_b32_e32 v239, 0xffff0000, v189
	v_pk_fma_f32 v[52:53], v[52:53], v[236:237], v[176:177]
	v_pk_fma_f32 v[54:55], v[54:55], v[238:239], v[178:179]
	v_cvt_pk_bf16_f32 v157, v54, v55
	v_cvt_pk_bf16_f32 v156, v52, v53
	global_store_dwordx4 v[150:151], v[52:55], off offset:512
	s_nop 1
	v_mul_f32_e32 v53, v53, v53
	v_mul_f32_e32 v55, v55, v55
	v_fmac_f32_e32 v53, v52, v52
	v_fmac_f32_e32 v55, v54, v54
	v_add_f32_e32 v52, v53, v55
	v_add_f32_e32 v229, v229, v52
	v_pk_mul_f32 v[48:49], v[48:49], v[234:235] op_sel_hi:[1,0]
	v_pk_mul_f32 v[50:51], v[50:51], v[234:235] op_sel_hi:[1,0]
	v_mul_f32_e32 v48, 0xbfb8aa3b, v48
	v_mul_f32_e32 v49, 0xbfb8aa3b, v49
	v_mul_f32_e32 v50, 0xbfb8aa3b, v50
	v_mul_f32_e32 v51, 0xbfb8aa3b, v51
	v_exp_f32_e32 v48, v48
	v_exp_f32_e32 v49, v49
	v_exp_f32_e32 v50, v50
	v_exp_f32_e32 v51, v51
	v_pk_add_f32 v[48:49], v[48:49], 1.0 op_sel_hi:[1,0]
	v_pk_add_f32 v[50:51], v[50:51], 1.0 op_sel_hi:[1,0]
	v_div_scale_f32 v224, s[16:17], v48, v48, 1.0
	v_rcp_f32_e32 v225, v224
	s_nop 0
	v_fma_f32 v226, -v224, v225, 1.0
	v_fmac_f32_e32 v225, v226, v225
	v_div_scale_f32 v226, vcc, 1.0, v48, 1.0
	v_mul_f32_e32 v227, v226, v225
	v_fma_f32 v228, -v224, v227, v226
	v_fmac_f32_e32 v227, v228, v225
	v_fma_f32 v224, -v224, v227, v226
	v_div_fmas_f32 v224, v224, v225, v227
	v_div_fixup_f32 v48, v224, v48, 1.0
	v_div_scale_f32 v224, s[16:17], v49, v49, 1.0
	v_rcp_f32_e32 v225, v224
	s_nop 0
	v_fma_f32 v226, -v224, v225, 1.0
	v_fmac_f32_e32 v225, v226, v225
	v_div_scale_f32 v226, vcc, 1.0, v49, 1.0
	v_mul_f32_e32 v227, v226, v225
	v_fma_f32 v228, -v224, v227, v226
	v_fmac_f32_e32 v227, v228, v225
	v_fma_f32 v224, -v224, v227, v226
	v_div_fmas_f32 v224, v224, v225, v227
	v_div_fixup_f32 v49, v224, v49, 1.0
	v_div_scale_f32 v224, s[16:17], v50, v50, 1.0
	v_rcp_f32_e32 v225, v224
	s_nop 0
	v_fma_f32 v226, -v224, v225, 1.0
	v_fmac_f32_e32 v225, v226, v225
	v_div_scale_f32 v226, vcc, 1.0, v50, 1.0
	v_mul_f32_e32 v227, v226, v225
	v_fma_f32 v228, -v224, v227, v226
	v_fmac_f32_e32 v227, v228, v225
	v_fma_f32 v224, -v224, v227, v226
	v_div_fmas_f32 v224, v224, v225, v227
	v_div_fixup_f32 v50, v224, v50, 1.0
	v_div_scale_f32 v224, s[16:17], v51, v51, 1.0
	v_rcp_f32_e32 v225, v224
	s_nop 0
	v_fma_f32 v226, -v224, v225, 1.0
	v_fmac_f32_e32 v225, v226, v225
	v_div_scale_f32 v226, vcc, 1.0, v51, 1.0
	v_mul_f32_e32 v227, v226, v225
	v_fma_f32 v228, -v224, v227, v226
	v_fmac_f32_e32 v227, v228, v225
	v_fma_f32 v224, -v224, v227, v226
	v_div_fmas_f32 v224, v224, v225, v227
	v_div_fixup_f32 v51, v224, v51, 1.0
	v_lshlrev_b32_e32 v236, 16, v190
	v_and_b32_e32 v237, 0xffff0000, v190
	v_lshlrev_b32_e32 v238, 16, v191
	v_and_b32_e32 v239, 0xffff0000, v191
	v_pk_fma_f32 v[48:49], v[48:49], v[236:237], v[180:181]
	v_pk_fma_f32 v[50:51], v[50:51], v[238:239], v[182:183]
	v_cvt_pk_bf16_f32 v159, v50, v51
	v_cvt_pk_bf16_f32 v158, v48, v49
	global_store_dwordx4 v[150:151], v[48:51], off offset:576
	s_nop 1
	v_mul_f32_e32 v49, v49, v49
	v_mul_f32_e32 v51, v51, v51
	v_fmac_f32_e32 v49, v48, v48
	v_fmac_f32_e32 v51, v50, v50
	v_add_f32_e32 v48, v49, v51
	v_add_f32_e32 v229, v229, v48
	v_permlane16_swap_b32_e32 v156, v158
	v_permlane16_swap_b32_e32 v157, v159
	global_store_dwordx4 v[166:167], v[156:159], off offset:256
	s_nop 0
	v_mov_b32_e32 v230, v229
	s_nop 1
	v_permlane16_swap_b32_e32 v229, v230
	v_add_f32_e32 v229, v229, v230
	v_mov_b32_e32 v230, v229
	s_nop 1
	v_permlane32_swap_b32_e32 v229, v230
	s_and_saveexec_b64 s[16:17], s[10:11]
	v_lshl_add_u64 v[156:157], v[144:145], 2, s[22:23]
	v_add_f32_e32 v229, v229, v230
	global_atomic_add_f32 v[156:157], v229, off
	s_or_b64 exec, exec, s[16:17]
	v_add_u32_e32 v144, 0xa0, v154
	v_mov_b32_e32 v145, v155
	v_lshlrev_b64 v[148:149], 11, v[144:145]
	v_lshl_add_u64 v[148:149], v[148:149], 0, v[146:147]
	v_lshl_add_u64 v[150:151], v[148:149], 2, s[28:29]
	v_lshl_add_u64 v[152:153], v[148:149], 1, s[42:43]
	global_load_dwordx2 v[184:185], v[152:153], off
	global_load_dwordx4 v[168:171], v[150:151], off
	global_load_dwordx2 v[186:187], v[152:153], off offset:32
	global_load_dwordx4 v[172:175], v[150:151], off offset:64
	global_load_dwordx2 v[188:189], v[152:153], off offset:256
	global_load_dwordx4 v[176:179], v[150:151], off offset:512
	global_load_dwordx2 v[190:191], v[152:153], off offset:288
	global_load_dwordx4 v[180:183], v[150:151], off offset:576
	s_waitcnt vmcnt(15)
	v_fmamk_f32 v221, v221, 0x3a000000, v165
	v_mul_f32_e32 v235, 0x4b800000, v221
	v_cmp_gt_f32_e32 vcc, s47, v221
	s_nop 1
	v_cndmask_b32_e32 v221, v221, v235, vcc
	v_rsq_f32_e32 v221, v221
	s_nop 0
	v_mul_f32_e32 v235, 0x45800000, v221
	v_cndmask_b32_e32 v234, v221, v235, vcc
	v_add_u32_e32 v144, 0x90, v154
	v_mov_b32_e32 v145, v155
	v_lshlrev_b64 v[148:149], 11, v[144:145]
	v_lshl_add_u64 v[148:149], v[148:149], 0, v[146:147]
	v_lshl_add_u64 v[150:151], v[148:149], 2, s[28:29]
	v_lshl_add_u64 v[166:167], v[148:149], 1, s[24:25]
	v_add_co_u32_e32 v166, vcc, v166, v231
	s_nop 1
	v_addc_co_u32_e32 v167, vcc, 0, v167, vcc
	v_pk_mul_f32 v[44:45], v[44:45], v[234:235] op_sel_hi:[1,0]
	v_pk_mul_f32 v[46:47], v[46:47], v[234:235] op_sel_hi:[1,0]
	v_mul_f32_e32 v44, 0xbfb8aa3b, v44
	v_mul_f32_e32 v45, 0xbfb8aa3b, v45
	v_mul_f32_e32 v46, 0xbfb8aa3b, v46
	v_mul_f32_e32 v47, 0xbfb8aa3b, v47
	v_exp_f32_e32 v44, v44
	v_exp_f32_e32 v45, v45
	v_exp_f32_e32 v46, v46
	v_exp_f32_e32 v47, v47
	v_pk_add_f32 v[44:45], v[44:45], 1.0 op_sel_hi:[1,0]
	v_pk_add_f32 v[46:47], v[46:47], 1.0 op_sel_hi:[1,0]
	v_div_scale_f32 v224, s[16:17], v44, v44, 1.0
	v_rcp_f32_e32 v225, v224
	s_nop 0
	v_fma_f32 v226, -v224, v225, 1.0
	v_fmac_f32_e32 v225, v226, v225
	v_div_scale_f32 v226, vcc, 1.0, v44, 1.0
	v_mul_f32_e32 v227, v226, v225
	v_fma_f32 v228, -v224, v227, v226
	v_fmac_f32_e32 v227, v228, v225
	v_fma_f32 v224, -v224, v227, v226
	v_div_fmas_f32 v224, v224, v225, v227
	v_div_fixup_f32 v44, v224, v44, 1.0
	v_div_scale_f32 v224, s[16:17], v45, v45, 1.0
	v_rcp_f32_e32 v225, v224
	s_nop 0
	v_fma_f32 v226, -v224, v225, 1.0
	v_fmac_f32_e32 v225, v226, v225
	v_div_scale_f32 v226, vcc, 1.0, v45, 1.0
	v_mul_f32_e32 v227, v226, v225
	v_fma_f32 v228, -v224, v227, v226
	v_fmac_f32_e32 v227, v228, v225
	v_fma_f32 v224, -v224, v227, v226
	v_div_fmas_f32 v224, v224, v225, v227
	v_div_fixup_f32 v45, v224, v45, 1.0
	v_div_scale_f32 v224, s[16:17], v46, v46, 1.0
	v_rcp_f32_e32 v225, v224
	s_nop 0
	v_fma_f32 v226, -v224, v225, 1.0
	v_fmac_f32_e32 v225, v226, v225
	v_div_scale_f32 v226, vcc, 1.0, v46, 1.0
	v_mul_f32_e32 v227, v226, v225
	v_fma_f32 v228, -v224, v227, v226
	v_fmac_f32_e32 v227, v228, v225
	v_fma_f32 v224, -v224, v227, v226
	v_div_fmas_f32 v224, v224, v225, v227
	v_div_fixup_f32 v46, v224, v46, 1.0
	v_div_scale_f32 v224, s[16:17], v47, v47, 1.0
	v_rcp_f32_e32 v225, v224
	s_nop 0
	v_fma_f32 v226, -v224, v225, 1.0
	v_fmac_f32_e32 v225, v226, v225
	v_div_scale_f32 v226, vcc, 1.0, v47, 1.0
	v_mul_f32_e32 v227, v226, v225
	v_fma_f32 v228, -v224, v227, v226
	v_fmac_f32_e32 v227, v228, v225
	v_fma_f32 v224, -v224, v227, v226
	v_div_fmas_f32 v224, v224, v225, v227
	v_div_fixup_f32 v47, v224, v47, 1.0
	v_lshlrev_b32_e32 v236, 16, v208
	v_and_b32_e32 v237, 0xffff0000, v208
	v_lshlrev_b32_e32 v238, 16, v209
	v_and_b32_e32 v239, 0xffff0000, v209
	v_pk_fma_f32 v[44:45], v[44:45], v[236:237], v[192:193]
	v_pk_fma_f32 v[46:47], v[46:47], v[238:239], v[194:195]
	v_cvt_pk_bf16_f32 v157, v46, v47
	v_cvt_pk_bf16_f32 v156, v44, v45
	global_store_dwordx4 v[150:151], v[44:47], off
	s_nop 1
	v_mul_f32_e32 v45, v45, v45
	v_mul_f32_e32 v47, v47, v47
	v_fmac_f32_e32 v45, v44, v44
	v_fmac_f32_e32 v47, v46, v46
	v_add_f32_e32 v229, v45, v47
	v_pk_mul_f32 v[40:41], v[40:41], v[234:235] op_sel_hi:[1,0]
	v_pk_mul_f32 v[42:43], v[42:43], v[234:235] op_sel_hi:[1,0]
	v_mul_f32_e32 v40, 0xbfb8aa3b, v40
	v_mul_f32_e32 v41, 0xbfb8aa3b, v41
	v_mul_f32_e32 v42, 0xbfb8aa3b, v42
	v_mul_f32_e32 v43, 0xbfb8aa3b, v43
	v_exp_f32_e32 v40, v40
	v_exp_f32_e32 v41, v41
	v_exp_f32_e32 v42, v42
	v_exp_f32_e32 v43, v43
	v_pk_add_f32 v[40:41], v[40:41], 1.0 op_sel_hi:[1,0]
	v_pk_add_f32 v[42:43], v[42:43], 1.0 op_sel_hi:[1,0]
	v_div_scale_f32 v224, s[16:17], v40, v40, 1.0
	v_rcp_f32_e32 v225, v224
	s_nop 0
	v_fma_f32 v226, -v224, v225, 1.0
	v_fmac_f32_e32 v225, v226, v225
	v_div_scale_f32 v226, vcc, 1.0, v40, 1.0
	v_mul_f32_e32 v227, v226, v225
	v_fma_f32 v228, -v224, v227, v226
	v_fmac_f32_e32 v227, v228, v225
	v_fma_f32 v224, -v224, v227, v226
	v_div_fmas_f32 v224, v224, v225, v227
	v_div_fixup_f32 v40, v224, v40, 1.0
	v_div_scale_f32 v224, s[16:17], v41, v41, 1.0
	v_rcp_f32_e32 v225, v224
	s_nop 0
	v_fma_f32 v226, -v224, v225, 1.0
	v_fmac_f32_e32 v225, v226, v225
	v_div_scale_f32 v226, vcc, 1.0, v41, 1.0
	v_mul_f32_e32 v227, v226, v225
	v_fma_f32 v228, -v224, v227, v226
	v_fmac_f32_e32 v227, v228, v225
	v_fma_f32 v224, -v224, v227, v226
	v_div_fmas_f32 v224, v224, v225, v227
	v_div_fixup_f32 v41, v224, v41, 1.0
	v_div_scale_f32 v224, s[16:17], v42, v42, 1.0
	v_rcp_f32_e32 v225, v224
	s_nop 0
	v_fma_f32 v226, -v224, v225, 1.0
	v_fmac_f32_e32 v225, v226, v225
	v_div_scale_f32 v226, vcc, 1.0, v42, 1.0
	v_mul_f32_e32 v227, v226, v225
	v_fma_f32 v228, -v224, v227, v226
	v_fmac_f32_e32 v227, v228, v225
	v_fma_f32 v224, -v224, v227, v226
	v_div_fmas_f32 v224, v224, v225, v227
	v_div_fixup_f32 v42, v224, v42, 1.0
	v_div_scale_f32 v224, s[16:17], v43, v43, 1.0
	v_rcp_f32_e32 v225, v224
	s_nop 0
	v_fma_f32 v226, -v224, v225, 1.0
	v_fmac_f32_e32 v225, v226, v225
	v_div_scale_f32 v226, vcc, 1.0, v43, 1.0
	v_mul_f32_e32 v227, v226, v225
	v_fma_f32 v228, -v224, v227, v226
	v_fmac_f32_e32 v227, v228, v225
	v_fma_f32 v224, -v224, v227, v226
	v_div_fmas_f32 v224, v224, v225, v227
	v_div_fixup_f32 v43, v224, v43, 1.0
	v_lshlrev_b32_e32 v236, 16, v210
	v_and_b32_e32 v237, 0xffff0000, v210
	v_lshlrev_b32_e32 v238, 16, v211
	v_and_b32_e32 v239, 0xffff0000, v211
	v_pk_fma_f32 v[40:41], v[40:41], v[236:237], v[196:197]
	v_pk_fma_f32 v[42:43], v[42:43], v[238:239], v[198:199]
	v_cvt_pk_bf16_f32 v159, v42, v43
	v_cvt_pk_bf16_f32 v158, v40, v41
	global_store_dwordx4 v[150:151], v[40:43], off offset:64
	s_nop 1
	v_mul_f32_e32 v41, v41, v41
	v_mul_f32_e32 v43, v43, v43
	v_fmac_f32_e32 v41, v40, v40
	v_fmac_f32_e32 v43, v42, v42
	v_add_f32_e32 v40, v41, v43
	v_add_f32_e32 v229, v229, v40
	v_permlane16_swap_b32_e32 v156, v158
	v_permlane16_swap_b32_e32 v157, v159
	global_store_dwordx4 v[166:167], v[156:159], off
	s_nop 0
	v_pk_mul_f32 v[36:37], v[36:37], v[234:235] op_sel_hi:[1,0]
	v_pk_mul_f32 v[38:39], v[38:39], v[234:235] op_sel_hi:[1,0]
	v_mul_f32_e32 v36, 0xbfb8aa3b, v36
	v_mul_f32_e32 v37, 0xbfb8aa3b, v37
	v_mul_f32_e32 v38, 0xbfb8aa3b, v38
	v_mul_f32_e32 v39, 0xbfb8aa3b, v39
	v_exp_f32_e32 v36, v36
	v_exp_f32_e32 v37, v37
	v_exp_f32_e32 v38, v38
	v_exp_f32_e32 v39, v39
	v_pk_add_f32 v[36:37], v[36:37], 1.0 op_sel_hi:[1,0]
	v_pk_add_f32 v[38:39], v[38:39], 1.0 op_sel_hi:[1,0]
	v_div_scale_f32 v224, s[16:17], v36, v36, 1.0
	v_rcp_f32_e32 v225, v224
	s_nop 0
	v_fma_f32 v226, -v224, v225, 1.0
	v_fmac_f32_e32 v225, v226, v225
	v_div_scale_f32 v226, vcc, 1.0, v36, 1.0
	v_mul_f32_e32 v227, v226, v225
	v_fma_f32 v228, -v224, v227, v226
	v_fmac_f32_e32 v227, v228, v225
	v_fma_f32 v224, -v224, v227, v226
	v_div_fmas_f32 v224, v224, v225, v227
	v_div_fixup_f32 v36, v224, v36, 1.0
	v_div_scale_f32 v224, s[16:17], v37, v37, 1.0
	v_rcp_f32_e32 v225, v224
	s_nop 0
	v_fma_f32 v226, -v224, v225, 1.0
	v_fmac_f32_e32 v225, v226, v225
	v_div_scale_f32 v226, vcc, 1.0, v37, 1.0
	v_mul_f32_e32 v227, v226, v225
	v_fma_f32 v228, -v224, v227, v226
	v_fmac_f32_e32 v227, v228, v225
	v_fma_f32 v224, -v224, v227, v226
	v_div_fmas_f32 v224, v224, v225, v227
	v_div_fixup_f32 v37, v224, v37, 1.0
	v_div_scale_f32 v224, s[16:17], v38, v38, 1.0
	v_rcp_f32_e32 v225, v224
	s_nop 0
	v_fma_f32 v226, -v224, v225, 1.0
	v_fmac_f32_e32 v225, v226, v225
	v_div_scale_f32 v226, vcc, 1.0, v38, 1.0
	v_mul_f32_e32 v227, v226, v225
	v_fma_f32 v228, -v224, v227, v226
	v_fmac_f32_e32 v227, v228, v225
	v_fma_f32 v224, -v224, v227, v226
	v_div_fmas_f32 v224, v224, v225, v227
	v_div_fixup_f32 v38, v224, v38, 1.0
	v_div_scale_f32 v224, s[16:17], v39, v39, 1.0
	v_rcp_f32_e32 v225, v224
	s_nop 0
	v_fma_f32 v226, -v224, v225, 1.0
	v_fmac_f32_e32 v225, v226, v225
	v_div_scale_f32 v226, vcc, 1.0, v39, 1.0
	v_mul_f32_e32 v227, v226, v225
	v_fma_f32 v228, -v224, v227, v226
	v_fmac_f32_e32 v227, v228, v225
	v_fma_f32 v224, -v224, v227, v226
	v_div_fmas_f32 v224, v224, v225, v227
	v_div_fixup_f32 v39, v224, v39, 1.0
	v_lshlrev_b32_e32 v236, 16, v212
	v_and_b32_e32 v237, 0xffff0000, v212
	v_lshlrev_b32_e32 v238, 16, v213
	v_and_b32_e32 v239, 0xffff0000, v213
	v_pk_fma_f32 v[36:37], v[36:37], v[236:237], v[200:201]
	v_pk_fma_f32 v[38:39], v[38:39], v[238:239], v[202:203]
	v_cvt_pk_bf16_f32 v157, v38, v39
	v_cvt_pk_bf16_f32 v156, v36, v37
	global_store_dwordx4 v[150:151], v[36:39], off offset:512
	s_nop 1
	v_mul_f32_e32 v37, v37, v37
	v_mul_f32_e32 v39, v39, v39
	v_fmac_f32_e32 v37, v36, v36
	v_fmac_f32_e32 v39, v38, v38
	v_add_f32_e32 v36, v37, v39
	v_add_f32_e32 v229, v229, v36
	v_pk_mul_f32 v[32:33], v[32:33], v[234:235] op_sel_hi:[1,0]
	v_pk_mul_f32 v[34:35], v[34:35], v[234:235] op_sel_hi:[1,0]
	v_mul_f32_e32 v32, 0xbfb8aa3b, v32
	v_mul_f32_e32 v33, 0xbfb8aa3b, v33
	v_mul_f32_e32 v34, 0xbfb8aa3b, v34
	v_mul_f32_e32 v35, 0xbfb8aa3b, v35
	v_exp_f32_e32 v32, v32
	v_exp_f32_e32 v33, v33
	v_exp_f32_e32 v34, v34
	v_exp_f32_e32 v35, v35
	v_pk_add_f32 v[32:33], v[32:33], 1.0 op_sel_hi:[1,0]
	v_pk_add_f32 v[34:35], v[34:35], 1.0 op_sel_hi:[1,0]
	v_div_scale_f32 v224, s[16:17], v32, v32, 1.0
	v_rcp_f32_e32 v225, v224
	s_nop 0
	v_fma_f32 v226, -v224, v225, 1.0
	v_fmac_f32_e32 v225, v226, v225
	v_div_scale_f32 v226, vcc, 1.0, v32, 1.0
	v_mul_f32_e32 v227, v226, v225
	v_fma_f32 v228, -v224, v227, v226
	v_fmac_f32_e32 v227, v228, v225
	v_fma_f32 v224, -v224, v227, v226
	v_div_fmas_f32 v224, v224, v225, v227
	v_div_fixup_f32 v32, v224, v32, 1.0
	v_div_scale_f32 v224, s[16:17], v33, v33, 1.0
	v_rcp_f32_e32 v225, v224
	s_nop 0
	v_fma_f32 v226, -v224, v225, 1.0
	v_fmac_f32_e32 v225, v226, v225
	v_div_scale_f32 v226, vcc, 1.0, v33, 1.0
	v_mul_f32_e32 v227, v226, v225
	v_fma_f32 v228, -v224, v227, v226
	v_fmac_f32_e32 v227, v228, v225
	v_fma_f32 v224, -v224, v227, v226
	v_div_fmas_f32 v224, v224, v225, v227
	v_div_fixup_f32 v33, v224, v33, 1.0
	v_div_scale_f32 v224, s[16:17], v34, v34, 1.0
	v_rcp_f32_e32 v225, v224
	s_nop 0
	v_fma_f32 v226, -v224, v225, 1.0
	v_fmac_f32_e32 v225, v226, v225
	v_div_scale_f32 v226, vcc, 1.0, v34, 1.0
	v_mul_f32_e32 v227, v226, v225
	v_fma_f32 v228, -v224, v227, v226
	v_fmac_f32_e32 v227, v228, v225
	v_fma_f32 v224, -v224, v227, v226
	v_div_fmas_f32 v224, v224, v225, v227
	v_div_fixup_f32 v34, v224, v34, 1.0
	v_div_scale_f32 v224, s[16:17], v35, v35, 1.0
	v_rcp_f32_e32 v225, v224
	s_nop 0
	v_fma_f32 v226, -v224, v225, 1.0
	v_fmac_f32_e32 v225, v226, v225
	v_div_scale_f32 v226, vcc, 1.0, v35, 1.0
	v_mul_f32_e32 v227, v226, v225
	v_fma_f32 v228, -v224, v227, v226
	v_fmac_f32_e32 v227, v228, v225
	v_fma_f32 v224, -v224, v227, v226
	v_div_fmas_f32 v224, v224, v225, v227
	v_div_fixup_f32 v35, v224, v35, 1.0
	v_lshlrev_b32_e32 v236, 16, v214
	v_and_b32_e32 v237, 0xffff0000, v214
	v_lshlrev_b32_e32 v238, 16, v215
	v_and_b32_e32 v239, 0xffff0000, v215
	v_pk_fma_f32 v[32:33], v[32:33], v[236:237], v[204:205]
	v_pk_fma_f32 v[34:35], v[34:35], v[238:239], v[206:207]
	v_cvt_pk_bf16_f32 v159, v34, v35
	v_cvt_pk_bf16_f32 v158, v32, v33
	global_store_dwordx4 v[150:151], v[32:35], off offset:576
	s_nop 1
	v_mul_f32_e32 v33, v33, v33
	v_mul_f32_e32 v35, v35, v35
	v_fmac_f32_e32 v33, v32, v32
	v_fmac_f32_e32 v35, v34, v34
	v_add_f32_e32 v32, v33, v35
	v_add_f32_e32 v229, v229, v32
	v_permlane16_swap_b32_e32 v156, v158
	v_permlane16_swap_b32_e32 v157, v159
	global_store_dwordx4 v[166:167], v[156:159], off offset:256
	s_nop 0
	v_mov_b32_e32 v230, v229
	s_nop 1
	v_permlane16_swap_b32_e32 v229, v230
	v_add_f32_e32 v229, v229, v230
	v_mov_b32_e32 v230, v229
	s_nop 1
	v_permlane32_swap_b32_e32 v229, v230
	s_and_saveexec_b64 s[16:17], s[10:11]
	v_lshl_add_u64 v[156:157], v[144:145], 2, s[22:23]
	v_add_f32_e32 v229, v229, v230
	global_atomic_add_f32 v[156:157], v229, off
	s_or_b64 exec, exec, s[16:17]
	v_add_u32_e32 v144, 0xb0, v154
	v_mov_b32_e32 v145, v155
	v_lshlrev_b64 v[148:149], 11, v[144:145]
	v_lshl_add_u64 v[148:149], v[148:149], 0, v[146:147]
	v_lshl_add_u64 v[150:151], v[148:149], 2, s[28:29]
	v_lshl_add_u64 v[152:153], v[148:149], 1, s[42:43]
	global_load_dwordx2 v[208:209], v[152:153], off
	global_load_dwordx4 v[192:195], v[150:151], off
	global_load_dwordx2 v[210:211], v[152:153], off offset:32
	global_load_dwordx4 v[196:199], v[150:151], off offset:64
	global_load_dwordx2 v[212:213], v[152:153], off offset:256
	global_load_dwordx4 v[200:203], v[150:151], off offset:512
	global_load_dwordx2 v[214:215], v[152:153], off offset:288
	global_load_dwordx4 v[204:207], v[150:151], off offset:576
	s_waitcnt vmcnt(15)
	v_fmamk_f32 v222, v222, 0x3a000000, v165
	v_mul_f32_e32 v235, 0x4b800000, v222
	v_cmp_gt_f32_e32 vcc, s47, v222
	s_nop 1
	v_cndmask_b32_e32 v222, v222, v235, vcc
	v_rsq_f32_e32 v222, v222
	s_nop 0
	v_mul_f32_e32 v235, 0x45800000, v222
	v_cndmask_b32_e32 v234, v222, v235, vcc
	v_add_u32_e32 v144, 0xa0, v154
	v_mov_b32_e32 v145, v155
	v_lshlrev_b64 v[148:149], 11, v[144:145]
	v_lshl_add_u64 v[148:149], v[148:149], 0, v[146:147]
	v_lshl_add_u64 v[150:151], v[148:149], 2, s[28:29]
	v_lshl_add_u64 v[166:167], v[148:149], 1, s[24:25]
	v_add_co_u32_e32 v166, vcc, v166, v231
	s_nop 1
	v_addc_co_u32_e32 v167, vcc, 0, v167, vcc
	v_pk_mul_f32 v[28:29], v[28:29], v[234:235] op_sel_hi:[1,0]
	v_pk_mul_f32 v[30:31], v[30:31], v[234:235] op_sel_hi:[1,0]
	v_mul_f32_e32 v28, 0xbfb8aa3b, v28
	v_mul_f32_e32 v29, 0xbfb8aa3b, v29
	v_mul_f32_e32 v30, 0xbfb8aa3b, v30
	v_mul_f32_e32 v31, 0xbfb8aa3b, v31
	v_exp_f32_e32 v28, v28
	v_exp_f32_e32 v29, v29
	v_exp_f32_e32 v30, v30
	v_exp_f32_e32 v31, v31
	v_pk_add_f32 v[28:29], v[28:29], 1.0 op_sel_hi:[1,0]
	v_pk_add_f32 v[30:31], v[30:31], 1.0 op_sel_hi:[1,0]
	v_div_scale_f32 v224, s[16:17], v28, v28, 1.0
	v_rcp_f32_e32 v225, v224
	s_nop 0
	v_fma_f32 v226, -v224, v225, 1.0
	v_fmac_f32_e32 v225, v226, v225
	v_div_scale_f32 v226, vcc, 1.0, v28, 1.0
	v_mul_f32_e32 v227, v226, v225
	v_fma_f32 v228, -v224, v227, v226
	v_fmac_f32_e32 v227, v228, v225
	v_fma_f32 v224, -v224, v227, v226
	v_div_fmas_f32 v224, v224, v225, v227
	v_div_fixup_f32 v28, v224, v28, 1.0
	v_div_scale_f32 v224, s[16:17], v29, v29, 1.0
	v_rcp_f32_e32 v225, v224
	s_nop 0
	v_fma_f32 v226, -v224, v225, 1.0
	v_fmac_f32_e32 v225, v226, v225
	v_div_scale_f32 v226, vcc, 1.0, v29, 1.0
	v_mul_f32_e32 v227, v226, v225
	v_fma_f32 v228, -v224, v227, v226
	v_fmac_f32_e32 v227, v228, v225
	v_fma_f32 v224, -v224, v227, v226
	v_div_fmas_f32 v224, v224, v225, v227
	v_div_fixup_f32 v29, v224, v29, 1.0
	v_div_scale_f32 v224, s[16:17], v30, v30, 1.0
	v_rcp_f32_e32 v225, v224
	s_nop 0
	v_fma_f32 v226, -v224, v225, 1.0
	v_fmac_f32_e32 v225, v226, v225
	v_div_scale_f32 v226, vcc, 1.0, v30, 1.0
	v_mul_f32_e32 v227, v226, v225
	v_fma_f32 v228, -v224, v227, v226
	v_fmac_f32_e32 v227, v228, v225
	v_fma_f32 v224, -v224, v227, v226
	v_div_fmas_f32 v224, v224, v225, v227
	v_div_fixup_f32 v30, v224, v30, 1.0
	v_div_scale_f32 v224, s[16:17], v31, v31, 1.0
	v_rcp_f32_e32 v225, v224
	s_nop 0
	v_fma_f32 v226, -v224, v225, 1.0
	v_fmac_f32_e32 v225, v226, v225
	v_div_scale_f32 v226, vcc, 1.0, v31, 1.0
	v_mul_f32_e32 v227, v226, v225
	v_fma_f32 v228, -v224, v227, v226
	v_fmac_f32_e32 v227, v228, v225
	v_fma_f32 v224, -v224, v227, v226
	v_div_fmas_f32 v224, v224, v225, v227
	v_div_fixup_f32 v31, v224, v31, 1.0
	v_lshlrev_b32_e32 v236, 16, v184
	v_and_b32_e32 v237, 0xffff0000, v184
	v_lshlrev_b32_e32 v238, 16, v185
	v_and_b32_e32 v239, 0xffff0000, v185
	v_pk_fma_f32 v[28:29], v[28:29], v[236:237], v[168:169]
	v_pk_fma_f32 v[30:31], v[30:31], v[238:239], v[170:171]
	v_cvt_pk_bf16_f32 v157, v30, v31
	v_cvt_pk_bf16_f32 v156, v28, v29
	global_store_dwordx4 v[150:151], v[28:31], off
	s_nop 1
	v_mul_f32_e32 v29, v29, v29
	v_mul_f32_e32 v31, v31, v31
	v_fmac_f32_e32 v29, v28, v28
	v_fmac_f32_e32 v31, v30, v30
	v_add_f32_e32 v229, v29, v31
	v_pk_mul_f32 v[24:25], v[24:25], v[234:235] op_sel_hi:[1,0]
	v_pk_mul_f32 v[26:27], v[26:27], v[234:235] op_sel_hi:[1,0]
	v_mul_f32_e32 v24, 0xbfb8aa3b, v24
	v_mul_f32_e32 v25, 0xbfb8aa3b, v25
	v_mul_f32_e32 v26, 0xbfb8aa3b, v26
	v_mul_f32_e32 v27, 0xbfb8aa3b, v27
	v_exp_f32_e32 v24, v24
	v_exp_f32_e32 v25, v25
	v_exp_f32_e32 v26, v26
	v_exp_f32_e32 v27, v27
	v_pk_add_f32 v[24:25], v[24:25], 1.0 op_sel_hi:[1,0]
	v_pk_add_f32 v[26:27], v[26:27], 1.0 op_sel_hi:[1,0]
	v_div_scale_f32 v224, s[16:17], v24, v24, 1.0
	v_rcp_f32_e32 v225, v224
	s_nop 0
	v_fma_f32 v226, -v224, v225, 1.0
	v_fmac_f32_e32 v225, v226, v225
	v_div_scale_f32 v226, vcc, 1.0, v24, 1.0
	v_mul_f32_e32 v227, v226, v225
	v_fma_f32 v228, -v224, v227, v226
	v_fmac_f32_e32 v227, v228, v225
	v_fma_f32 v224, -v224, v227, v226
	v_div_fmas_f32 v224, v224, v225, v227
	v_div_fixup_f32 v24, v224, v24, 1.0
	v_div_scale_f32 v224, s[16:17], v25, v25, 1.0
	v_rcp_f32_e32 v225, v224
	s_nop 0
	v_fma_f32 v226, -v224, v225, 1.0
	v_fmac_f32_e32 v225, v226, v225
	v_div_scale_f32 v226, vcc, 1.0, v25, 1.0
	v_mul_f32_e32 v227, v226, v225
	v_fma_f32 v228, -v224, v227, v226
	v_fmac_f32_e32 v227, v228, v225
	v_fma_f32 v224, -v224, v227, v226
	v_div_fmas_f32 v224, v224, v225, v227
	v_div_fixup_f32 v25, v224, v25, 1.0
	v_div_scale_f32 v224, s[16:17], v26, v26, 1.0
	v_rcp_f32_e32 v225, v224
	s_nop 0
	v_fma_f32 v226, -v224, v225, 1.0
	v_fmac_f32_e32 v225, v226, v225
	v_div_scale_f32 v226, vcc, 1.0, v26, 1.0
	v_mul_f32_e32 v227, v226, v225
	v_fma_f32 v228, -v224, v227, v226
	v_fmac_f32_e32 v227, v228, v225
	v_fma_f32 v224, -v224, v227, v226
	v_div_fmas_f32 v224, v224, v225, v227
	v_div_fixup_f32 v26, v224, v26, 1.0
	v_div_scale_f32 v224, s[16:17], v27, v27, 1.0
	v_rcp_f32_e32 v225, v224
	s_nop 0
	v_fma_f32 v226, -v224, v225, 1.0
	v_fmac_f32_e32 v225, v226, v225
	v_div_scale_f32 v226, vcc, 1.0, v27, 1.0
	v_mul_f32_e32 v227, v226, v225
	v_fma_f32 v228, -v224, v227, v226
	v_fmac_f32_e32 v227, v228, v225
	v_fma_f32 v224, -v224, v227, v226
	v_div_fmas_f32 v224, v224, v225, v227
	v_div_fixup_f32 v27, v224, v27, 1.0
	v_lshlrev_b32_e32 v236, 16, v186
	v_and_b32_e32 v237, 0xffff0000, v186
	v_lshlrev_b32_e32 v238, 16, v187
	v_and_b32_e32 v239, 0xffff0000, v187
	v_pk_fma_f32 v[24:25], v[24:25], v[236:237], v[172:173]
	v_pk_fma_f32 v[26:27], v[26:27], v[238:239], v[174:175]
	v_cvt_pk_bf16_f32 v159, v26, v27
	v_cvt_pk_bf16_f32 v158, v24, v25
	global_store_dwordx4 v[150:151], v[24:27], off offset:64
	s_nop 1
	v_mul_f32_e32 v25, v25, v25
	v_mul_f32_e32 v27, v27, v27
	v_fmac_f32_e32 v25, v24, v24
	v_fmac_f32_e32 v27, v26, v26
	v_add_f32_e32 v24, v25, v27
	v_add_f32_e32 v229, v229, v24
	v_permlane16_swap_b32_e32 v156, v158
	v_permlane16_swap_b32_e32 v157, v159
	global_store_dwordx4 v[166:167], v[156:159], off
	s_nop 0
	v_pk_mul_f32 v[20:21], v[20:21], v[234:235] op_sel_hi:[1,0]
	v_pk_mul_f32 v[22:23], v[22:23], v[234:235] op_sel_hi:[1,0]
	v_mul_f32_e32 v20, 0xbfb8aa3b, v20
	v_mul_f32_e32 v21, 0xbfb8aa3b, v21
	v_mul_f32_e32 v22, 0xbfb8aa3b, v22
	v_mul_f32_e32 v23, 0xbfb8aa3b, v23
	v_exp_f32_e32 v20, v20
	v_exp_f32_e32 v21, v21
	v_exp_f32_e32 v22, v22
	v_exp_f32_e32 v23, v23
	v_pk_add_f32 v[20:21], v[20:21], 1.0 op_sel_hi:[1,0]
	v_pk_add_f32 v[22:23], v[22:23], 1.0 op_sel_hi:[1,0]
	v_div_scale_f32 v224, s[16:17], v20, v20, 1.0
	v_rcp_f32_e32 v225, v224
	s_nop 0
	v_fma_f32 v226, -v224, v225, 1.0
	v_fmac_f32_e32 v225, v226, v225
	v_div_scale_f32 v226, vcc, 1.0, v20, 1.0
	v_mul_f32_e32 v227, v226, v225
	v_fma_f32 v228, -v224, v227, v226
	v_fmac_f32_e32 v227, v228, v225
	v_fma_f32 v224, -v224, v227, v226
	v_div_fmas_f32 v224, v224, v225, v227
	v_div_fixup_f32 v20, v224, v20, 1.0
	v_div_scale_f32 v224, s[16:17], v21, v21, 1.0
	v_rcp_f32_e32 v225, v224
	s_nop 0
	v_fma_f32 v226, -v224, v225, 1.0
	v_fmac_f32_e32 v225, v226, v225
	v_div_scale_f32 v226, vcc, 1.0, v21, 1.0
	v_mul_f32_e32 v227, v226, v225
	v_fma_f32 v228, -v224, v227, v226
	v_fmac_f32_e32 v227, v228, v225
	v_fma_f32 v224, -v224, v227, v226
	v_div_fmas_f32 v224, v224, v225, v227
	v_div_fixup_f32 v21, v224, v21, 1.0
	v_div_scale_f32 v224, s[16:17], v22, v22, 1.0
	v_rcp_f32_e32 v225, v224
	s_nop 0
	v_fma_f32 v226, -v224, v225, 1.0
	v_fmac_f32_e32 v225, v226, v225
	v_div_scale_f32 v226, vcc, 1.0, v22, 1.0
	v_mul_f32_e32 v227, v226, v225
	v_fma_f32 v228, -v224, v227, v226
	v_fmac_f32_e32 v227, v228, v225
	v_fma_f32 v224, -v224, v227, v226
	v_div_fmas_f32 v224, v224, v225, v227
	v_div_fixup_f32 v22, v224, v22, 1.0
	v_div_scale_f32 v224, s[16:17], v23, v23, 1.0
	v_rcp_f32_e32 v225, v224
	s_nop 0
	v_fma_f32 v226, -v224, v225, 1.0
	v_fmac_f32_e32 v225, v226, v225
	v_div_scale_f32 v226, vcc, 1.0, v23, 1.0
	v_mul_f32_e32 v227, v226, v225
	v_fma_f32 v228, -v224, v227, v226
	v_fmac_f32_e32 v227, v228, v225
	v_fma_f32 v224, -v224, v227, v226
	v_div_fmas_f32 v224, v224, v225, v227
	v_div_fixup_f32 v23, v224, v23, 1.0
	v_lshlrev_b32_e32 v236, 16, v188
	v_and_b32_e32 v237, 0xffff0000, v188
	v_lshlrev_b32_e32 v238, 16, v189
	v_and_b32_e32 v239, 0xffff0000, v189
	v_pk_fma_f32 v[20:21], v[20:21], v[236:237], v[176:177]
	v_pk_fma_f32 v[22:23], v[22:23], v[238:239], v[178:179]
	v_cvt_pk_bf16_f32 v157, v22, v23
	v_cvt_pk_bf16_f32 v156, v20, v21
	global_store_dwordx4 v[150:151], v[20:23], off offset:512
	s_nop 1
	v_mul_f32_e32 v21, v21, v21
	v_mul_f32_e32 v23, v23, v23
	v_fmac_f32_e32 v21, v20, v20
	v_fmac_f32_e32 v23, v22, v22
	v_add_f32_e32 v20, v21, v23
	v_add_f32_e32 v229, v229, v20
	v_pk_mul_f32 v[16:17], v[16:17], v[234:235] op_sel_hi:[1,0]
	v_pk_mul_f32 v[18:19], v[18:19], v[234:235] op_sel_hi:[1,0]
	v_mul_f32_e32 v16, 0xbfb8aa3b, v16
	v_mul_f32_e32 v17, 0xbfb8aa3b, v17
	v_mul_f32_e32 v18, 0xbfb8aa3b, v18
	v_mul_f32_e32 v19, 0xbfb8aa3b, v19
	v_exp_f32_e32 v16, v16
	v_exp_f32_e32 v17, v17
	v_exp_f32_e32 v18, v18
	v_exp_f32_e32 v19, v19
	v_pk_add_f32 v[16:17], v[16:17], 1.0 op_sel_hi:[1,0]
	v_pk_add_f32 v[18:19], v[18:19], 1.0 op_sel_hi:[1,0]
	v_div_scale_f32 v224, s[16:17], v16, v16, 1.0
	v_rcp_f32_e32 v225, v224
	s_nop 0
	v_fma_f32 v226, -v224, v225, 1.0
	v_fmac_f32_e32 v225, v226, v225
	v_div_scale_f32 v226, vcc, 1.0, v16, 1.0
	v_mul_f32_e32 v227, v226, v225
	v_fma_f32 v228, -v224, v227, v226
	v_fmac_f32_e32 v227, v228, v225
	v_fma_f32 v224, -v224, v227, v226
	v_div_fmas_f32 v224, v224, v225, v227
	v_div_fixup_f32 v16, v224, v16, 1.0
	v_div_scale_f32 v224, s[16:17], v17, v17, 1.0
	v_rcp_f32_e32 v225, v224
	s_nop 0
	v_fma_f32 v226, -v224, v225, 1.0
	v_fmac_f32_e32 v225, v226, v225
	v_div_scale_f32 v226, vcc, 1.0, v17, 1.0
	v_mul_f32_e32 v227, v226, v225
	v_fma_f32 v228, -v224, v227, v226
	v_fmac_f32_e32 v227, v228, v225
	v_fma_f32 v224, -v224, v227, v226
	v_div_fmas_f32 v224, v224, v225, v227
	v_div_fixup_f32 v17, v224, v17, 1.0
	v_div_scale_f32 v224, s[16:17], v18, v18, 1.0
	v_rcp_f32_e32 v225, v224
	s_nop 0
	v_fma_f32 v226, -v224, v225, 1.0
	v_fmac_f32_e32 v225, v226, v225
	v_div_scale_f32 v226, vcc, 1.0, v18, 1.0
	v_mul_f32_e32 v227, v226, v225
	v_fma_f32 v228, -v224, v227, v226
	v_fmac_f32_e32 v227, v228, v225
	v_fma_f32 v224, -v224, v227, v226
	v_div_fmas_f32 v224, v224, v225, v227
	v_div_fixup_f32 v18, v224, v18, 1.0
	v_div_scale_f32 v224, s[16:17], v19, v19, 1.0
	v_rcp_f32_e32 v225, v224
	s_nop 0
	v_fma_f32 v226, -v224, v225, 1.0
	v_fmac_f32_e32 v225, v226, v225
	v_div_scale_f32 v226, vcc, 1.0, v19, 1.0
	v_mul_f32_e32 v227, v226, v225
	v_fma_f32 v228, -v224, v227, v226
	v_fmac_f32_e32 v227, v228, v225
	v_fma_f32 v224, -v224, v227, v226
	v_div_fmas_f32 v224, v224, v225, v227
	v_div_fixup_f32 v19, v224, v19, 1.0
	v_lshlrev_b32_e32 v236, 16, v190
	v_and_b32_e32 v237, 0xffff0000, v190
	v_lshlrev_b32_e32 v238, 16, v191
	v_and_b32_e32 v239, 0xffff0000, v191
	v_pk_fma_f32 v[16:17], v[16:17], v[236:237], v[180:181]
	v_pk_fma_f32 v[18:19], v[18:19], v[238:239], v[182:183]
	v_cvt_pk_bf16_f32 v159, v18, v19
	v_cvt_pk_bf16_f32 v158, v16, v17
	global_store_dwordx4 v[150:151], v[16:19], off offset:576
	s_nop 1
	v_mul_f32_e32 v17, v17, v17
	v_mul_f32_e32 v19, v19, v19
	v_fmac_f32_e32 v17, v16, v16
	v_fmac_f32_e32 v19, v18, v18
	v_add_f32_e32 v16, v17, v19
	v_add_f32_e32 v229, v229, v16
	v_permlane16_swap_b32_e32 v156, v158
	v_permlane16_swap_b32_e32 v157, v159
	global_store_dwordx4 v[166:167], v[156:159], off offset:256
	s_nop 0
	v_mov_b32_e32 v230, v229
	s_nop 1
	v_permlane16_swap_b32_e32 v229, v230
	v_add_f32_e32 v229, v229, v230
	v_mov_b32_e32 v230, v229
	s_nop 1
	v_permlane32_swap_b32_e32 v229, v230
	s_and_saveexec_b64 s[16:17], s[10:11]
	v_lshl_add_u64 v[156:157], v[144:145], 2, s[22:23]
	v_add_f32_e32 v229, v229, v230
	global_atomic_add_f32 v[156:157], v229, off
	s_or_b64 exec, exec, s[16:17]
	s_waitcnt vmcnt(7)
	v_fmamk_f32 v223, v223, 0x3a000000, v165
	v_mul_f32_e32 v235, 0x4b800000, v223
	v_cmp_gt_f32_e32 vcc, s47, v223
	s_nop 1
	v_cndmask_b32_e32 v223, v223, v235, vcc
	v_rsq_f32_e32 v223, v223
	s_nop 0
	v_mul_f32_e32 v235, 0x45800000, v223
	v_cndmask_b32_e32 v234, v223, v235, vcc
	v_add_u32_e32 v144, 0xb0, v154
	v_mov_b32_e32 v145, v155
	v_lshlrev_b64 v[148:149], 11, v[144:145]
	v_lshl_add_u64 v[148:149], v[148:149], 0, v[146:147]
	v_lshl_add_u64 v[150:151], v[148:149], 2, s[28:29]
	v_lshl_add_u64 v[166:167], v[148:149], 1, s[24:25]
	v_add_co_u32_e32 v166, vcc, v166, v231
	s_nop 1
	v_addc_co_u32_e32 v167, vcc, 0, v167, vcc
	v_pk_mul_f32 v[12:13], v[12:13], v[234:235] op_sel_hi:[1,0]
	v_pk_mul_f32 v[14:15], v[14:15], v[234:235] op_sel_hi:[1,0]
	v_mul_f32_e32 v12, 0xbfb8aa3b, v12
	v_mul_f32_e32 v13, 0xbfb8aa3b, v13
	v_mul_f32_e32 v14, 0xbfb8aa3b, v14
	v_mul_f32_e32 v15, 0xbfb8aa3b, v15
	v_exp_f32_e32 v12, v12
	v_exp_f32_e32 v13, v13
	v_exp_f32_e32 v14, v14
	v_exp_f32_e32 v15, v15
	v_pk_add_f32 v[12:13], v[12:13], 1.0 op_sel_hi:[1,0]
	v_pk_add_f32 v[14:15], v[14:15], 1.0 op_sel_hi:[1,0]
	v_div_scale_f32 v224, s[16:17], v12, v12, 1.0
	v_rcp_f32_e32 v225, v224
	s_nop 0
	v_fma_f32 v226, -v224, v225, 1.0
	v_fmac_f32_e32 v225, v226, v225
	v_div_scale_f32 v226, vcc, 1.0, v12, 1.0
	v_mul_f32_e32 v227, v226, v225
	v_fma_f32 v228, -v224, v227, v226
	v_fmac_f32_e32 v227, v228, v225
	v_fma_f32 v224, -v224, v227, v226
	v_div_fmas_f32 v224, v224, v225, v227
	v_div_fixup_f32 v12, v224, v12, 1.0
	v_div_scale_f32 v224, s[16:17], v13, v13, 1.0
	v_rcp_f32_e32 v225, v224
	s_nop 0
	v_fma_f32 v226, -v224, v225, 1.0
	v_fmac_f32_e32 v225, v226, v225
	v_div_scale_f32 v226, vcc, 1.0, v13, 1.0
	v_mul_f32_e32 v227, v226, v225
	v_fma_f32 v228, -v224, v227, v226
	v_fmac_f32_e32 v227, v228, v225
	v_fma_f32 v224, -v224, v227, v226
	v_div_fmas_f32 v224, v224, v225, v227
	v_div_fixup_f32 v13, v224, v13, 1.0
	v_div_scale_f32 v224, s[16:17], v14, v14, 1.0
	v_rcp_f32_e32 v225, v224
	s_nop 0
	v_fma_f32 v226, -v224, v225, 1.0
	v_fmac_f32_e32 v225, v226, v225
	v_div_scale_f32 v226, vcc, 1.0, v14, 1.0
	v_mul_f32_e32 v227, v226, v225
	v_fma_f32 v228, -v224, v227, v226
	v_fmac_f32_e32 v227, v228, v225
	v_fma_f32 v224, -v224, v227, v226
	v_div_fmas_f32 v224, v224, v225, v227
	v_div_fixup_f32 v14, v224, v14, 1.0
	v_div_scale_f32 v224, s[16:17], v15, v15, 1.0
	v_rcp_f32_e32 v225, v224
	s_nop 0
	v_fma_f32 v226, -v224, v225, 1.0
	v_fmac_f32_e32 v225, v226, v225
	v_div_scale_f32 v226, vcc, 1.0, v15, 1.0
	v_mul_f32_e32 v227, v226, v225
	v_fma_f32 v228, -v224, v227, v226
	v_fmac_f32_e32 v227, v228, v225
	v_fma_f32 v224, -v224, v227, v226
	v_div_fmas_f32 v224, v224, v225, v227
	v_div_fixup_f32 v15, v224, v15, 1.0
	v_lshlrev_b32_e32 v236, 16, v208
	v_and_b32_e32 v237, 0xffff0000, v208
	v_lshlrev_b32_e32 v238, 16, v209
	v_and_b32_e32 v239, 0xffff0000, v209
	v_pk_fma_f32 v[12:13], v[12:13], v[236:237], v[192:193]
	v_pk_fma_f32 v[14:15], v[14:15], v[238:239], v[194:195]
	v_cvt_pk_bf16_f32 v157, v14, v15
	v_cvt_pk_bf16_f32 v156, v12, v13
	global_store_dwordx4 v[150:151], v[12:15], off
	s_nop 1
	v_mul_f32_e32 v13, v13, v13
	v_mul_f32_e32 v15, v15, v15
	v_fmac_f32_e32 v13, v12, v12
	v_fmac_f32_e32 v15, v14, v14
	v_add_f32_e32 v229, v13, v15
	v_pk_mul_f32 v[8:9], v[8:9], v[234:235] op_sel_hi:[1,0]
	v_pk_mul_f32 v[10:11], v[10:11], v[234:235] op_sel_hi:[1,0]
	v_mul_f32_e32 v8, 0xbfb8aa3b, v8
	v_mul_f32_e32 v9, 0xbfb8aa3b, v9
	v_mul_f32_e32 v10, 0xbfb8aa3b, v10
	v_mul_f32_e32 v11, 0xbfb8aa3b, v11
	v_exp_f32_e32 v8, v8
	v_exp_f32_e32 v9, v9
	v_exp_f32_e32 v10, v10
	v_exp_f32_e32 v11, v11
	v_pk_add_f32 v[8:9], v[8:9], 1.0 op_sel_hi:[1,0]
	v_pk_add_f32 v[10:11], v[10:11], 1.0 op_sel_hi:[1,0]
	v_div_scale_f32 v224, s[16:17], v8, v8, 1.0
	v_rcp_f32_e32 v225, v224
	s_nop 0
	v_fma_f32 v226, -v224, v225, 1.0
	v_fmac_f32_e32 v225, v226, v225
	v_div_scale_f32 v226, vcc, 1.0, v8, 1.0
	v_mul_f32_e32 v227, v226, v225
	v_fma_f32 v228, -v224, v227, v226
	v_fmac_f32_e32 v227, v228, v225
	v_fma_f32 v224, -v224, v227, v226
	v_div_fmas_f32 v224, v224, v225, v227
	v_div_fixup_f32 v8, v224, v8, 1.0
	v_div_scale_f32 v224, s[16:17], v9, v9, 1.0
	v_rcp_f32_e32 v225, v224
	s_nop 0
	v_fma_f32 v226, -v224, v225, 1.0
	v_fmac_f32_e32 v225, v226, v225
	v_div_scale_f32 v226, vcc, 1.0, v9, 1.0
	v_mul_f32_e32 v227, v226, v225
	v_fma_f32 v228, -v224, v227, v226
	v_fmac_f32_e32 v227, v228, v225
	v_fma_f32 v224, -v224, v227, v226
	v_div_fmas_f32 v224, v224, v225, v227
	v_div_fixup_f32 v9, v224, v9, 1.0
	v_div_scale_f32 v224, s[16:17], v10, v10, 1.0
	v_rcp_f32_e32 v225, v224
	s_nop 0
	v_fma_f32 v226, -v224, v225, 1.0
	v_fmac_f32_e32 v225, v226, v225
	v_div_scale_f32 v226, vcc, 1.0, v10, 1.0
	v_mul_f32_e32 v227, v226, v225
	v_fma_f32 v228, -v224, v227, v226
	v_fmac_f32_e32 v227, v228, v225
	v_fma_f32 v224, -v224, v227, v226
	v_div_fmas_f32 v224, v224, v225, v227
	v_div_fixup_f32 v10, v224, v10, 1.0
	v_div_scale_f32 v224, s[16:17], v11, v11, 1.0
	v_rcp_f32_e32 v225, v224
	s_nop 0
	v_fma_f32 v226, -v224, v225, 1.0
	v_fmac_f32_e32 v225, v226, v225
	v_div_scale_f32 v226, vcc, 1.0, v11, 1.0
	v_mul_f32_e32 v227, v226, v225
	v_fma_f32 v228, -v224, v227, v226
	v_fmac_f32_e32 v227, v228, v225
	v_fma_f32 v224, -v224, v227, v226
	v_div_fmas_f32 v224, v224, v225, v227
	v_div_fixup_f32 v11, v224, v11, 1.0
	v_lshlrev_b32_e32 v236, 16, v210
	v_and_b32_e32 v237, 0xffff0000, v210
	v_lshlrev_b32_e32 v238, 16, v211
	v_and_b32_e32 v239, 0xffff0000, v211
	v_pk_fma_f32 v[8:9], v[8:9], v[236:237], v[196:197]
	v_pk_fma_f32 v[10:11], v[10:11], v[238:239], v[198:199]
	v_cvt_pk_bf16_f32 v159, v10, v11
	v_cvt_pk_bf16_f32 v158, v8, v9
	global_store_dwordx4 v[150:151], v[8:11], off offset:64
	s_nop 1
	v_mul_f32_e32 v9, v9, v9
	v_mul_f32_e32 v11, v11, v11
	v_fmac_f32_e32 v9, v8, v8
	v_fmac_f32_e32 v11, v10, v10
	v_add_f32_e32 v8, v9, v11
	v_add_f32_e32 v229, v229, v8
	v_permlane16_swap_b32_e32 v156, v158
	v_permlane16_swap_b32_e32 v157, v159
	global_store_dwordx4 v[166:167], v[156:159], off
	s_nop 0
	v_pk_mul_f32 v[4:5], v[4:5], v[234:235] op_sel_hi:[1,0]
	v_pk_mul_f32 v[6:7], v[6:7], v[234:235] op_sel_hi:[1,0]
	v_mul_f32_e32 v4, 0xbfb8aa3b, v4
	v_mul_f32_e32 v5, 0xbfb8aa3b, v5
	v_mul_f32_e32 v6, 0xbfb8aa3b, v6
	v_mul_f32_e32 v7, 0xbfb8aa3b, v7
	v_exp_f32_e32 v4, v4
	v_exp_f32_e32 v5, v5
	v_exp_f32_e32 v6, v6
	v_exp_f32_e32 v7, v7
	v_pk_add_f32 v[4:5], v[4:5], 1.0 op_sel_hi:[1,0]
	v_pk_add_f32 v[6:7], v[6:7], 1.0 op_sel_hi:[1,0]
	v_div_scale_f32 v224, s[16:17], v4, v4, 1.0
	v_rcp_f32_e32 v225, v224
	s_nop 0
	v_fma_f32 v226, -v224, v225, 1.0
	v_fmac_f32_e32 v225, v226, v225
	v_div_scale_f32 v226, vcc, 1.0, v4, 1.0
	v_mul_f32_e32 v227, v226, v225
	v_fma_f32 v228, -v224, v227, v226
	v_fmac_f32_e32 v227, v228, v225
	v_fma_f32 v224, -v224, v227, v226
	v_div_fmas_f32 v224, v224, v225, v227
	v_div_fixup_f32 v4, v224, v4, 1.0
	v_div_scale_f32 v224, s[16:17], v5, v5, 1.0
	v_rcp_f32_e32 v225, v224
	s_nop 0
	v_fma_f32 v226, -v224, v225, 1.0
	v_fmac_f32_e32 v225, v226, v225
	v_div_scale_f32 v226, vcc, 1.0, v5, 1.0
	v_mul_f32_e32 v227, v226, v225
	v_fma_f32 v228, -v224, v227, v226
	v_fmac_f32_e32 v227, v228, v225
	v_fma_f32 v224, -v224, v227, v226
	v_div_fmas_f32 v224, v224, v225, v227
	v_div_fixup_f32 v5, v224, v5, 1.0
	v_div_scale_f32 v224, s[16:17], v6, v6, 1.0
	v_rcp_f32_e32 v225, v224
	s_nop 0
	v_fma_f32 v226, -v224, v225, 1.0
	v_fmac_f32_e32 v225, v226, v225
	v_div_scale_f32 v226, vcc, 1.0, v6, 1.0
	v_mul_f32_e32 v227, v226, v225
	v_fma_f32 v228, -v224, v227, v226
	v_fmac_f32_e32 v227, v228, v225
	v_fma_f32 v224, -v224, v227, v226
	v_div_fmas_f32 v224, v224, v225, v227
	v_div_fixup_f32 v6, v224, v6, 1.0
	v_div_scale_f32 v224, s[16:17], v7, v7, 1.0
	v_rcp_f32_e32 v225, v224
	s_nop 0
	v_fma_f32 v226, -v224, v225, 1.0
	v_fmac_f32_e32 v225, v226, v225
	v_div_scale_f32 v226, vcc, 1.0, v7, 1.0
	v_mul_f32_e32 v227, v226, v225
	v_fma_f32 v228, -v224, v227, v226
	v_fmac_f32_e32 v227, v228, v225
	v_fma_f32 v224, -v224, v227, v226
	v_div_fmas_f32 v224, v224, v225, v227
	v_div_fixup_f32 v7, v224, v7, 1.0
	v_lshlrev_b32_e32 v236, 16, v212
	v_and_b32_e32 v237, 0xffff0000, v212
	v_lshlrev_b32_e32 v238, 16, v213
	v_and_b32_e32 v239, 0xffff0000, v213
	v_pk_fma_f32 v[4:5], v[4:5], v[236:237], v[200:201]
	v_pk_fma_f32 v[6:7], v[6:7], v[238:239], v[202:203]
	v_cvt_pk_bf16_f32 v157, v6, v7
	v_cvt_pk_bf16_f32 v156, v4, v5
	global_store_dwordx4 v[150:151], v[4:7], off offset:512
	s_nop 1
	v_mul_f32_e32 v5, v5, v5
	v_mul_f32_e32 v7, v7, v7
	v_fmac_f32_e32 v5, v4, v4
	v_fmac_f32_e32 v7, v6, v6
	v_add_f32_e32 v4, v5, v7
	v_add_f32_e32 v229, v229, v4
	v_pk_mul_f32 v[0:1], v[0:1], v[234:235] op_sel_hi:[1,0]
	v_pk_mul_f32 v[2:3], v[2:3], v[234:235] op_sel_hi:[1,0]
	v_mul_f32_e32 v0, 0xbfb8aa3b, v0
	v_mul_f32_e32 v1, 0xbfb8aa3b, v1
	v_mul_f32_e32 v2, 0xbfb8aa3b, v2
	v_mul_f32_e32 v3, 0xbfb8aa3b, v3
	v_exp_f32_e32 v0, v0
	v_exp_f32_e32 v1, v1
	v_exp_f32_e32 v2, v2
	v_exp_f32_e32 v3, v3
	v_pk_add_f32 v[0:1], v[0:1], 1.0 op_sel_hi:[1,0]
	v_pk_add_f32 v[2:3], v[2:3], 1.0 op_sel_hi:[1,0]
	v_div_scale_f32 v224, s[16:17], v0, v0, 1.0
	v_rcp_f32_e32 v225, v224
	s_nop 0
	v_fma_f32 v226, -v224, v225, 1.0
	v_fmac_f32_e32 v225, v226, v225
	v_div_scale_f32 v226, vcc, 1.0, v0, 1.0
	v_mul_f32_e32 v227, v226, v225
	v_fma_f32 v228, -v224, v227, v226
	v_fmac_f32_e32 v227, v228, v225
	v_fma_f32 v224, -v224, v227, v226
	v_div_fmas_f32 v224, v224, v225, v227
	v_div_fixup_f32 v0, v224, v0, 1.0
	v_div_scale_f32 v224, s[16:17], v1, v1, 1.0
	v_rcp_f32_e32 v225, v224
	s_nop 0
	v_fma_f32 v226, -v224, v225, 1.0
	v_fmac_f32_e32 v225, v226, v225
	v_div_scale_f32 v226, vcc, 1.0, v1, 1.0
	v_mul_f32_e32 v227, v226, v225
	v_fma_f32 v228, -v224, v227, v226
	v_fmac_f32_e32 v227, v228, v225
	v_fma_f32 v224, -v224, v227, v226
	v_div_fmas_f32 v224, v224, v225, v227
	v_div_fixup_f32 v1, v224, v1, 1.0
	v_div_scale_f32 v224, s[16:17], v2, v2, 1.0
	v_rcp_f32_e32 v225, v224
	s_nop 0
	v_fma_f32 v226, -v224, v225, 1.0
	v_fmac_f32_e32 v225, v226, v225
	v_div_scale_f32 v226, vcc, 1.0, v2, 1.0
	v_mul_f32_e32 v227, v226, v225
	v_fma_f32 v228, -v224, v227, v226
	v_fmac_f32_e32 v227, v228, v225
	v_fma_f32 v224, -v224, v227, v226
	v_div_fmas_f32 v224, v224, v225, v227
	v_div_fixup_f32 v2, v224, v2, 1.0
	v_div_scale_f32 v224, s[16:17], v3, v3, 1.0
	v_rcp_f32_e32 v225, v224
	s_nop 0
	v_fma_f32 v226, -v224, v225, 1.0
	v_fmac_f32_e32 v225, v226, v225
	v_div_scale_f32 v226, vcc, 1.0, v3, 1.0
	v_mul_f32_e32 v227, v226, v225
	v_fma_f32 v228, -v224, v227, v226
	v_fmac_f32_e32 v227, v228, v225
	v_fma_f32 v224, -v224, v227, v226
	v_div_fmas_f32 v224, v224, v225, v227
	v_div_fixup_f32 v3, v224, v3, 1.0
	v_lshlrev_b32_e32 v236, 16, v214
	v_and_b32_e32 v237, 0xffff0000, v214
	v_lshlrev_b32_e32 v238, 16, v215
	v_and_b32_e32 v239, 0xffff0000, v215
	v_pk_fma_f32 v[0:1], v[0:1], v[236:237], v[204:205]
	v_pk_fma_f32 v[2:3], v[2:3], v[238:239], v[206:207]
	v_cvt_pk_bf16_f32 v159, v2, v3
	v_cvt_pk_bf16_f32 v158, v0, v1
	global_store_dwordx4 v[150:151], v[0:3], off offset:576
	s_nop 1
	v_mul_f32_e32 v1, v1, v1
	v_mul_f32_e32 v3, v3, v3
	v_fmac_f32_e32 v1, v0, v0
	v_fmac_f32_e32 v3, v2, v2
	v_add_f32_e32 v0, v1, v3
	v_add_f32_e32 v229, v229, v0
	v_permlane16_swap_b32_e32 v156, v158
	v_permlane16_swap_b32_e32 v157, v159
	global_store_dwordx4 v[166:167], v[156:159], off offset:256
	s_nop 0
	v_mov_b32_e32 v230, v229
	s_nop 1
	v_permlane16_swap_b32_e32 v229, v230
	v_add_f32_e32 v229, v229, v230
	v_mov_b32_e32 v230, v229
	s_nop 1
	v_permlane32_swap_b32_e32 v229, v230
	s_and_saveexec_b64 s[16:17], s[10:11]
	v_lshl_add_u64 v[156:157], v[144:145], 2, s[22:23]
	v_add_f32_e32 v229, v229, v230
	global_atomic_add_f32 v[156:157], v229, off
	s_or_b64 exec, exec, s[16:17]
	s_branch .LBB0_739

.LBB0_1893:
	ds_read_b128 v[144:147], v161
	ds_read_b128 v[148:151], v161 offset:1024
	ds_read_b128 v[152:155], v161 offset:2048
	ds_read_b128 v[156:159], v161 offset:3072
	s_add_u32 s56, s14, 0xfff80080
	s_addc_u32 s57, s15, -1
	s_cmp_eq_u32 s64, 28
	s_cselect_b32 s59, s11, s57
	s_cselect_b32 s58, s13, s56
	s_cselect_b32 s57, s23, s63
	s_cselect_b32 s56, s51, s62
	v_lshl_add_u64 v[198:199], s[14:15], 0, v[134:135]
	s_add_i32 m0, s26, 0xc000
	ds_read_b128 v[166:169], v162
	ds_read_b128 v[170:173], v162 offset:1024
	ds_read_b128 v[174:177], v162 offset:2048
	ds_read_b128 v[178:181], v162 offset:3072
	ds_read_b128 v[182:185], v162 offset:4096
	ds_read_b128 v[186:189], v162 offset:5120
	ds_read_b128 v[190:193], v162 offset:6144
	ds_read_b128 v[194:197], v162 offset:7168
	global_load_lds_dwordx4 v[198:199], off
	v_lshl_add_u64 v[198:199], s[14:15], 0, v[138:139]
	s_add_i32 m0, s26, 0xe000
	s_nop 0
	global_load_lds_dwordx4 v[198:199], off
	s_waitcnt lgkmcnt(8)
	s_barrier
	s_waitcnt lgkmcnt(0)
	s_setprio 1
	s_waitcnt lgkmcnt(0)
	v_mfma_f32_16x16x32_bf16 v[124:127], v[144:147], v[166:169], v[124:127]
	v_mfma_f32_16x16x32_bf16 v[120:123], v[152:155], v[166:169], v[120:123]
	v_mfma_f32_16x16x32_bf16 v[108:111], v[144:147], v[174:177], v[108:111]
	v_mfma_f32_16x16x32_bf16 v[104:107], v[152:155], v[174:177], v[104:107]
	v_mfma_f32_16x16x32_bf16 v[92:95], v[144:147], v[182:185], v[92:95]
	v_mfma_f32_16x16x32_bf16 v[88:91], v[152:155], v[182:185], v[88:91]
	v_mfma_f32_16x16x32_bf16 v[76:79], v[144:147], v[190:193], v[76:79]
	v_mfma_f32_16x16x32_bf16 v[72:75], v[152:155], v[190:193], v[72:75]
	v_mfma_f32_16x16x32_bf16 v[124:127], v[148:151], v[170:173], v[124:127]
	v_mfma_f32_16x16x32_bf16 v[120:123], v[156:159], v[170:173], v[120:123]
	v_mfma_f32_16x16x32_bf16 v[108:111], v[148:151], v[178:181], v[108:111]
	v_mfma_f32_16x16x32_bf16 v[104:107], v[156:159], v[178:181], v[104:107]
	v_mfma_f32_16x16x32_bf16 v[92:95], v[148:151], v[186:189], v[92:95]
	v_mfma_f32_16x16x32_bf16 v[88:91], v[156:159], v[186:189], v[88:91]
	v_mfma_f32_16x16x32_bf16 v[76:79], v[148:151], v[194:197], v[76:79]
	v_mfma_f32_16x16x32_bf16 v[72:75], v[156:159], v[194:197], v[72:75]
	s_setprio 0
	s_barrier
	s_add_i32 s65, s49, s5
	v_lshl_add_u64 v[214:215], s[56:57], 0, v[128:129]
	s_mov_b32 m0, s65
	ds_read_b128 v[198:201], v163
	ds_read_b128 v[202:205], v163 offset:1024
	ds_read_b128 v[206:209], v163 offset:2048
	ds_read_b128 v[210:213], v163 offset:3072
	global_load_lds_dwordx4 v[214:215], off
	v_lshl_add_u64 v[216:217], s[56:57], 0, v[130:131]
	s_add_i32 m0, s65, 0x2000
	s_nop 0
	global_load_lds_dwordx4 v[216:217], off
	s_barrier
	s_waitcnt lgkmcnt(0)
	s_setprio 1
	s_waitcnt lgkmcnt(0)
	v_mfma_f32_16x16x32_bf16 v[116:119], v[198:201], v[166:169], v[116:119]
	v_mfma_f32_16x16x32_bf16 v[112:115], v[206:209], v[166:169], v[112:115]
	v_mfma_f32_16x16x32_bf16 v[100:103], v[198:201], v[174:177], v[100:103]
	v_mfma_f32_16x16x32_bf16 v[96:99], v[206:209], v[174:177], v[96:99]
	v_mfma_f32_16x16x32_bf16 v[84:87], v[198:201], v[182:185], v[84:87]
	v_mfma_f32_16x16x32_bf16 v[80:83], v[206:209], v[182:185], v[80:83]
	v_mfma_f32_16x16x32_bf16 v[68:71], v[198:201], v[190:193], v[68:71]
	v_mfma_f32_16x16x32_bf16 v[64:67], v[206:209], v[190:193], v[64:67]
	v_mfma_f32_16x16x32_bf16 v[116:119], v[202:205], v[170:173], v[116:119]
	v_mfma_f32_16x16x32_bf16 v[112:115], v[210:213], v[170:173], v[112:115]
	v_mfma_f32_16x16x32_bf16 v[100:103], v[202:205], v[178:181], v[100:103]
	v_mfma_f32_16x16x32_bf16 v[96:99], v[210:213], v[178:181], v[96:99]
	v_mfma_f32_16x16x32_bf16 v[84:87], v[202:205], v[186:189], v[84:87]
	v_mfma_f32_16x16x32_bf16 v[80:83], v[210:213], v[186:189], v[80:83]
	v_mfma_f32_16x16x32_bf16 v[68:71], v[202:205], v[194:197], v[68:71]
	v_mfma_f32_16x16x32_bf16 v[64:67], v[210:213], v[194:197], v[64:67]
	s_setprio 0
	s_mov_b32 m0, s26
	v_lshl_add_u64 v[218:219], s[58:59], 0, v[128:129]
	s_barrier
	ds_read_b128 v[166:169], v162 offset:16384
	ds_read_b128 v[170:173], v162 offset:17408
	ds_read_b128 v[174:177], v162 offset:18432
	ds_read_b128 v[178:181], v162 offset:19456
	ds_read_b128 v[182:185], v162 offset:20480
	ds_read_b128 v[186:189], v162 offset:21504
	ds_read_b128 v[190:193], v162 offset:22528
	ds_read_b128 v[194:197], v162 offset:23552
	global_load_lds_dwordx4 v[218:219], off
	v_lshl_add_u64 v[220:221], s[58:59], 0, v[130:131]
	s_mov_b32 m0, s27
	s_nop 0
	global_load_lds_dwordx4 v[220:221], off
	s_barrier
	s_waitcnt lgkmcnt(0)
	s_setprio 1
	s_waitcnt lgkmcnt(0)
	v_mfma_f32_16x16x32_bf16 v[60:63], v[144:147], v[166:169], v[60:63]
	v_mfma_f32_16x16x32_bf16 v[56:59], v[152:155], v[166:169], v[56:59]
	v_mfma_f32_16x16x32_bf16 v[44:47], v[144:147], v[174:177], v[44:47]
	v_mfma_f32_16x16x32_bf16 v[40:43], v[152:155], v[174:177], v[40:43]
	v_mfma_f32_16x16x32_bf16 v[28:31], v[144:147], v[182:185], v[28:31]
	v_mfma_f32_16x16x32_bf16 v[24:27], v[152:155], v[182:185], v[24:27]
	v_mfma_f32_16x16x32_bf16 v[12:15], v[144:147], v[190:193], v[12:15]
	v_mfma_f32_16x16x32_bf16 v[8:11], v[152:155], v[190:193], v[8:11]
	v_mfma_f32_16x16x32_bf16 v[60:63], v[148:151], v[170:173], v[60:63]
	v_mfma_f32_16x16x32_bf16 v[56:59], v[156:159], v[170:173], v[56:59]
	v_mfma_f32_16x16x32_bf16 v[44:47], v[148:151], v[178:181], v[44:47]
	v_mfma_f32_16x16x32_bf16 v[40:43], v[156:159], v[178:181], v[40:43]
	v_mfma_f32_16x16x32_bf16 v[28:31], v[148:151], v[186:189], v[28:31]
	v_mfma_f32_16x16x32_bf16 v[24:27], v[156:159], v[186:189], v[24:27]
	v_mfma_f32_16x16x32_bf16 v[12:15], v[148:151], v[194:197], v[12:15]
	v_mfma_f32_16x16x32_bf16 v[8:11], v[156:159], v[194:197], v[8:11]
	s_setprio 0
	s_barrier
	s_add_u32 s66, s56, 0x80000
	s_addc_u32 s67, s57, 0
	s_add_i32 s65, s60, s5
	v_lshl_add_u64 v[144:145], s[66:67], 0, v[128:129]
	s_mov_b32 m0, s65
	s_nop 0
	global_load_lds_dwordx4 v[144:145], off
	v_lshl_add_u64 v[144:145], s[66:67], 0, v[130:131]
	s_add_i32 m0, s65, 0x2000
	s_nop 0
	global_load_lds_dwordx4 v[144:145], off
	s_waitcnt vmcnt(6)
	s_barrier
	s_setprio 1
	v_mfma_f32_16x16x32_bf16 v[52:55], v[198:201], v[166:169], v[52:55]
	v_mfma_f32_16x16x32_bf16 v[48:51], v[206:209], v[166:169], v[48:51]
	v_mfma_f32_16x16x32_bf16 v[36:39], v[198:201], v[174:177], v[36:39]
	v_mfma_f32_16x16x32_bf16 v[32:35], v[206:209], v[174:177], v[32:35]
	v_mfma_f32_16x16x32_bf16 v[20:23], v[198:201], v[182:185], v[20:23]
	v_mfma_f32_16x16x32_bf16 v[16:19], v[206:209], v[182:185], v[16:19]
	v_mfma_f32_16x16x32_bf16 v[4:7], v[198:201], v[190:193], v[4:7]
	v_mfma_f32_16x16x32_bf16 v[0:3], v[206:209], v[190:193], v[0:3]
	v_mfma_f32_16x16x32_bf16 v[52:55], v[202:205], v[170:173], v[52:55]
	v_mfma_f32_16x16x32_bf16 v[48:51], v[210:213], v[170:173], v[48:51]
	v_mfma_f32_16x16x32_bf16 v[36:39], v[202:205], v[178:181], v[36:39]
	v_mfma_f32_16x16x32_bf16 v[32:35], v[210:213], v[178:181], v[32:35]
	v_mfma_f32_16x16x32_bf16 v[20:23], v[202:205], v[186:189], v[20:23]
	v_mfma_f32_16x16x32_bf16 v[16:19], v[210:213], v[186:189], v[16:19]
	v_mfma_f32_16x16x32_bf16 v[4:7], v[202:205], v[194:197], v[4:7]
	v_mfma_f32_16x16x32_bf16 v[0:3], v[210:213], v[194:197], v[0:3]
	s_setprio 0
	s_add_i32 s65, 16, 0x18000
	v_add_u32_e32 v156, s65, v137
	s_barrier
	ds_read_b128 v[144:147], v156
	ds_read_b128 v[148:151], v156 offset:1024
	ds_read_b128 v[152:155], v156 offset:2048
	ds_read_b128 v[156:159], v156 offset:3072
	s_add_u32 s58, s58, 0x80000
	s_addc_u32 s59, s59, 0
	s_mov_b32 m0, s39
	v_lshl_add_u64 v[198:199], s[58:59], 0, v[128:129]
	ds_read_b128 v[166:169], v162 offset:32768
	ds_read_b128 v[170:173], v162 offset:33792
	ds_read_b128 v[174:177], v162 offset:34816
	ds_read_b128 v[178:181], v162 offset:35840
	ds_read_b128 v[182:185], v162 offset:36864
	ds_read_b128 v[186:189], v162 offset:37888
	ds_read_b128 v[190:193], v162 offset:38912
	ds_read_b128 v[194:197], v162 offset:39936
	global_load_lds_dwordx4 v[198:199], off
	v_lshl_add_u64 v[198:199], s[58:59], 0, v[130:131]
	s_mov_b32 m0, s44
	s_nop 0
	global_load_lds_dwordx4 v[198:199], off
	s_waitcnt lgkmcnt(8)
	s_barrier
	s_waitcnt lgkmcnt(0)
	s_setprio 1
	s_waitcnt lgkmcnt(0)
	v_mfma_f32_16x16x32_bf16 v[124:127], v[144:147], v[166:169], v[124:127]
	v_mfma_f32_16x16x32_bf16 v[120:123], v[152:155], v[166:169], v[120:123]
	v_mfma_f32_16x16x32_bf16 v[108:111], v[144:147], v[174:177], v[108:111]
	v_mfma_f32_16x16x32_bf16 v[104:107], v[152:155], v[174:177], v[104:107]
	v_mfma_f32_16x16x32_bf16 v[92:95], v[144:147], v[182:185], v[92:95]
	v_mfma_f32_16x16x32_bf16 v[88:91], v[152:155], v[182:185], v[88:91]
	v_mfma_f32_16x16x32_bf16 v[76:79], v[144:147], v[190:193], v[76:79]
	v_mfma_f32_16x16x32_bf16 v[72:75], v[152:155], v[190:193], v[72:75]
	v_mfma_f32_16x16x32_bf16 v[124:127], v[148:151], v[170:173], v[124:127]
	v_mfma_f32_16x16x32_bf16 v[120:123], v[156:159], v[170:173], v[120:123]
	v_mfma_f32_16x16x32_bf16 v[108:111], v[148:151], v[178:181], v[108:111]
	v_mfma_f32_16x16x32_bf16 v[104:107], v[156:159], v[178:181], v[104:107]
	v_mfma_f32_16x16x32_bf16 v[92:95], v[148:151], v[186:189], v[92:95]
	v_mfma_f32_16x16x32_bf16 v[88:91], v[156:159], v[186:189], v[88:91]
	v_mfma_f32_16x16x32_bf16 v[76:79], v[148:151], v[194:197], v[76:79]
	v_mfma_f32_16x16x32_bf16 v[72:75], v[156:159], v[194:197], v[72:75]
	s_setprio 0
	s_barrier
	s_add_i32 s58, 16, 0x1c000
	s_add_i32 s59, s65, s5
	v_add_u32_e32 v160, s58, v137
	v_lshl_add_u64 v[214:215], v[214:215], 0, s[20:21]
	s_mov_b32 m0, s59
	ds_read_b128 v[198:201], v160
	ds_read_b128 v[202:205], v160 offset:1024
	ds_read_b128 v[206:209], v160 offset:2048
	ds_read_b128 v[210:213], v160 offset:3072
	global_load_lds_dwordx4 v[214:215], off
	v_lshl_add_u64 v[214:215], v[216:217], 0, s[20:21]
	s_add_i32 m0, s59, 0x2000
	s_nop 0
	global_load_lds_dwordx4 v[214:215], off
	s_barrier
	s_waitcnt lgkmcnt(0)
	s_setprio 1
	s_waitcnt lgkmcnt(0)
	v_mfma_f32_16x16x32_bf16 v[116:119], v[198:201], v[166:169], v[116:119]
	v_mfma_f32_16x16x32_bf16 v[112:115], v[206:209], v[166:169], v[112:115]
	v_mfma_f32_16x16x32_bf16 v[100:103], v[198:201], v[174:177], v[100:103]
	v_mfma_f32_16x16x32_bf16 v[96:99], v[206:209], v[174:177], v[96:99]
	v_mfma_f32_16x16x32_bf16 v[84:87], v[198:201], v[182:185], v[84:87]
	v_mfma_f32_16x16x32_bf16 v[80:83], v[206:209], v[182:185], v[80:83]
	v_mfma_f32_16x16x32_bf16 v[68:71], v[198:201], v[190:193], v[68:71]
	v_mfma_f32_16x16x32_bf16 v[64:67], v[206:209], v[190:193], v[64:67]
	v_mfma_f32_16x16x32_bf16 v[116:119], v[202:205], v[170:173], v[116:119]
	v_mfma_f32_16x16x32_bf16 v[112:115], v[210:213], v[170:173], v[112:115]
	v_mfma_f32_16x16x32_bf16 v[100:103], v[202:205], v[178:181], v[100:103]
	v_mfma_f32_16x16x32_bf16 v[96:99], v[210:213], v[178:181], v[96:99]
	v_mfma_f32_16x16x32_bf16 v[84:87], v[202:205], v[186:189], v[84:87]
	v_mfma_f32_16x16x32_bf16 v[80:83], v[210:213], v[186:189], v[80:83]
	v_mfma_f32_16x16x32_bf16 v[68:71], v[202:205], v[194:197], v[68:71]
	v_mfma_f32_16x16x32_bf16 v[64:67], v[210:213], v[194:197], v[64:67]
	s_setprio 0
	s_mov_b32 m0, s45
	v_lshl_add_u64 v[214:215], v[218:219], 0, s[20:21]
	s_barrier
	ds_read_b128 v[166:169], v162 offset:49152
	ds_read_b128 v[170:173], v162 offset:50176
	ds_read_b128 v[174:177], v162 offset:51200
	ds_read_b128 v[178:181], v162 offset:52224
	ds_read_b128 v[182:185], v162 offset:53248
	ds_read_b128 v[186:189], v162 offset:54272
	ds_read_b128 v[190:193], v162 offset:55296
	ds_read_b128 v[194:197], v162 offset:56320
	global_load_lds_dwordx4 v[214:215], off
	v_lshl_add_u64 v[214:215], v[220:221], 0, s[20:21]
	s_mov_b32 m0, s46
	s_nop 0
	global_load_lds_dwordx4 v[214:215], off
	s_barrier
	s_waitcnt lgkmcnt(0)
	s_setprio 1
	s_waitcnt lgkmcnt(0)
	v_mfma_f32_16x16x32_bf16 v[60:63], v[144:147], v[166:169], v[60:63]
	v_mfma_f32_16x16x32_bf16 v[56:59], v[152:155], v[166:169], v[56:59]
	v_mfma_f32_16x16x32_bf16 v[44:47], v[144:147], v[174:177], v[44:47]
	v_mfma_f32_16x16x32_bf16 v[40:43], v[152:155], v[174:177], v[40:43]
	v_mfma_f32_16x16x32_bf16 v[28:31], v[144:147], v[182:185], v[28:31]
	v_mfma_f32_16x16x32_bf16 v[24:27], v[152:155], v[182:185], v[24:27]
	v_mfma_f32_16x16x32_bf16 v[12:15], v[144:147], v[190:193], v[12:15]
	v_mfma_f32_16x16x32_bf16 v[8:11], v[152:155], v[190:193], v[8:11]
	v_mfma_f32_16x16x32_bf16 v[60:63], v[148:151], v[170:173], v[60:63]
	v_mfma_f32_16x16x32_bf16 v[56:59], v[156:159], v[170:173], v[56:59]
	v_mfma_f32_16x16x32_bf16 v[44:47], v[148:151], v[178:181], v[44:47]
	v_mfma_f32_16x16x32_bf16 v[40:43], v[156:159], v[178:181], v[40:43]
	v_mfma_f32_16x16x32_bf16 v[28:31], v[148:151], v[186:189], v[28:31]
	v_mfma_f32_16x16x32_bf16 v[24:27], v[156:159], v[186:189], v[24:27]
	v_mfma_f32_16x16x32_bf16 v[12:15], v[148:151], v[194:197], v[12:15]
	v_mfma_f32_16x16x32_bf16 v[8:11], v[156:159], v[194:197], v[8:11]
	s_setprio 0
	s_barrier
	s_add_u32 s56, s56, 0x80080
	s_addc_u32 s57, s57, 0
	s_add_i32 s58, s58, s5
	v_lshl_add_u64 v[144:145], s[56:57], 0, v[128:129]
	s_mov_b32 m0, s58
	s_nop 0
	global_load_lds_dwordx4 v[144:145], off
	v_lshl_add_u64 v[144:145], s[56:57], 0, v[130:131]
	s_add_i32 m0, s58, 0x2000
	s_nop 0
	global_load_lds_dwordx4 v[144:145], off
	s_waitcnt vmcnt(6)
	s_barrier
	s_setprio 1
	v_mfma_f32_16x16x32_bf16 v[52:55], v[198:201], v[166:169], v[52:55]
	v_mfma_f32_16x16x32_bf16 v[48:51], v[206:209], v[166:169], v[48:51]
	v_mfma_f32_16x16x32_bf16 v[36:39], v[198:201], v[174:177], v[36:39]
	v_mfma_f32_16x16x32_bf16 v[32:35], v[206:209], v[174:177], v[32:35]
	v_mfma_f32_16x16x32_bf16 v[20:23], v[198:201], v[182:185], v[20:23]
	v_mfma_f32_16x16x32_bf16 v[16:19], v[206:209], v[182:185], v[16:19]
	v_mfma_f32_16x16x32_bf16 v[4:7], v[198:201], v[190:193], v[4:7]
	v_mfma_f32_16x16x32_bf16 v[0:3], v[206:209], v[190:193], v[0:3]
	v_mfma_f32_16x16x32_bf16 v[52:55], v[202:205], v[170:173], v[52:55]
	v_mfma_f32_16x16x32_bf16 v[48:51], v[210:213], v[170:173], v[48:51]
	v_mfma_f32_16x16x32_bf16 v[36:39], v[202:205], v[178:181], v[36:39]
	v_mfma_f32_16x16x32_bf16 v[32:35], v[210:213], v[178:181], v[32:35]
	v_mfma_f32_16x16x32_bf16 v[20:23], v[202:205], v[186:189], v[20:23]
	v_mfma_f32_16x16x32_bf16 v[16:19], v[210:213], v[186:189], v[16:19]
	v_mfma_f32_16x16x32_bf16 v[4:7], v[202:205], v[194:197], v[4:7]
	v_mfma_f32_16x16x32_bf16 v[0:3], v[210:213], v[194:197], v[0:3]
	s_setprio 0
	s_add_i32 s64, s64, 2
	s_add_u32 s14, s14, 0x100
	s_addc_u32 s15, s15, 0
	s_add_u32 s62, s62, 0x100
	s_addc_u32 s63, s63, 0
	s_cmp_gt_u32 s64, 29
	s_barrier
	s_cbranch_scc0 .LBB0_1893
	v_lshl_add_u32 v154, s12, 8, v133
	v_ashrrev_i32_e32 v155, 31, v154
	s_lshl_b32 s10, s10, 8
	s_ashr_i32 s11, s10, 31
	v_mov_b32_e32 v147, s11
	v_or_b32_e32 v146, s10, v132
	v_bfe_u32 v231, v136, 4, 1
	v_mul_u32_u24_e32 v231, 24, v231
	v_mov_b32_e32 v144, v154
	v_mov_b32_e32 v145, v155
	v_lshl_add_u64 v[148:149], v[144:145], 2, s[16:17]
	global_load_dword v216, v[148:149], off
	v_add_u32_e32 v144, 0x10, v154
	v_mov_b32_e32 v145, v155
	v_lshl_add_u64 v[148:149], v[144:145], 2, s[16:17]
	global_load_dword v217, v[148:149], off
	v_add_u32_e32 v144, 0x20, v154
	v_mov_b32_e32 v145, v155
	v_lshl_add_u64 v[148:149], v[144:145], 2, s[16:17]
	global_load_dword v218, v[148:149], off
	v_add_u32_e32 v144, 0x30, v154
	v_mov_b32_e32 v145, v155
	v_lshl_add_u64 v[148:149], v[144:145], 2, s[16:17]
	global_load_dword v219, v[148:149], off
	v_add_u32_e32 v144, 0x80, v154
	v_mov_b32_e32 v145, v155
	v_lshl_add_u64 v[148:149], v[144:145], 2, s[16:17]
	global_load_dword v220, v[148:149], off
	v_add_u32_e32 v144, 0x90, v154
	v_mov_b32_e32 v145, v155
	v_lshl_add_u64 v[148:149], v[144:145], 2, s[16:17]
	global_load_dword v221, v[148:149], off
	v_add_u32_e32 v144, 0xa0, v154
	v_mov_b32_e32 v145, v155
	v_lshl_add_u64 v[148:149], v[144:145], 2, s[16:17]
	global_load_dword v222, v[148:149], off
	v_add_u32_e32 v144, 0xb0, v154
	v_mov_b32_e32 v145, v155
	v_lshl_add_u64 v[148:149], v[144:145], 2, s[16:17]
	global_load_dword v223, v[148:149], off
	v_mov_b32_e32 v144, v154
	v_mov_b32_e32 v145, v155
	v_lshlrev_b64 v[148:149], 11, v[144:145]
	v_lshl_add_u64 v[148:149], v[148:149], 0, v[146:147]
	v_lshl_add_u64 v[150:151], v[148:149], 2, s[28:29]
	v_lshl_add_u64 v[152:153], v[148:149], 1, s[42:43]
	global_load_dwordx2 v[184:185], v[152:153], off
	global_load_dwordx4 v[168:171], v[150:151], off
	global_load_dwordx2 v[186:187], v[152:153], off offset:32
	global_load_dwordx4 v[172:175], v[150:151], off offset:64
	global_load_dwordx2 v[188:189], v[152:153], off offset:256
	global_load_dwordx4 v[176:179], v[150:151], off offset:512
	global_load_dwordx2 v[190:191], v[152:153], off offset:288
	global_load_dwordx4 v[180:183], v[150:151], off offset:576
	v_add_u32_e32 v144, 0x10, v154
	v_mov_b32_e32 v145, v155
	v_lshlrev_b64 v[148:149], 11, v[144:145]
	v_lshl_add_u64 v[148:149], v[148:149], 0, v[146:147]
	v_lshl_add_u64 v[150:151], v[148:149], 2, s[28:29]
	v_lshl_add_u64 v[152:153], v[148:149], 1, s[42:43]
	global_load_dwordx2 v[208:209], v[152:153], off
	global_load_dwordx4 v[192:195], v[150:151], off
	global_load_dwordx2 v[210:211], v[152:153], off offset:32
	global_load_dwordx4 v[196:199], v[150:151], off offset:64
	global_load_dwordx2 v[212:213], v[152:153], off offset:256
	global_load_dwordx4 v[200:203], v[150:151], off offset:512
	global_load_dwordx2 v[214:215], v[152:153], off offset:288
	global_load_dwordx4 v[204:207], v[150:151], off offset:576
	s_waitcnt vmcnt(8)
	v_fmamk_f32 v216, v216, 0x3a000000, v164
	v_mul_f32_e32 v235, 0x4b800000, v216
	v_cmp_gt_f32_e32 vcc, s61, v216
	s_nop 1
	v_cndmask_b32_e32 v216, v216, v235, vcc
	v_rsq_f32_e32 v216, v216
	s_nop 0
	v_mul_f32_e32 v235, 0x45800000, v216
	v_cndmask_b32_e32 v234, v216, v235, vcc
	v_mov_b32_e32 v144, v154
	v_mov_b32_e32 v145, v155
	v_lshlrev_b64 v[148:149], 11, v[144:145]
	v_lshl_add_u64 v[148:149], v[148:149], 0, v[146:147]
	v_lshl_add_u64 v[150:151], v[148:149], 2, s[28:29]
	v_lshl_add_u64 v[166:167], v[148:149], 1, s[24:25]
	v_add_co_u32_e32 v166, vcc, v166, v231
	s_nop 1
	v_addc_co_u32_e32 v167, vcc, 0, v167, vcc
	v_pk_mul_f32 v[124:125], v[124:125], v[234:235] op_sel_hi:[1,0]
	v_pk_mul_f32 v[126:127], v[126:127], v[234:235] op_sel_hi:[1,0]
	v_mul_f32_e32 v124, 0xbfb8aa3b, v124
	v_mul_f32_e32 v125, 0xbfb8aa3b, v125
	v_mul_f32_e32 v126, 0xbfb8aa3b, v126
	v_mul_f32_e32 v127, 0xbfb8aa3b, v127
	v_exp_f32_e32 v124, v124
	v_exp_f32_e32 v125, v125
	v_exp_f32_e32 v126, v126
	v_exp_f32_e32 v127, v127
	v_pk_add_f32 v[124:125], v[124:125], 1.0 op_sel_hi:[1,0]
	v_pk_add_f32 v[126:127], v[126:127], 1.0 op_sel_hi:[1,0]
	v_div_scale_f32 v224, s[10:11], v124, v124, 1.0
	v_rcp_f32_e32 v225, v224
	s_nop 0
	v_fma_f32 v226, -v224, v225, 1.0
	v_fmac_f32_e32 v225, v226, v225
	v_div_scale_f32 v226, vcc, 1.0, v124, 1.0
	v_mul_f32_e32 v227, v226, v225
	v_fma_f32 v228, -v224, v227, v226
	v_fmac_f32_e32 v227, v228, v225
	v_fma_f32 v224, -v224, v227, v226
	v_div_fmas_f32 v224, v224, v225, v227
	v_div_fixup_f32 v124, v224, v124, 1.0
	v_div_scale_f32 v224, s[10:11], v125, v125, 1.0
	v_rcp_f32_e32 v225, v224
	s_nop 0
	v_fma_f32 v226, -v224, v225, 1.0
	v_fmac_f32_e32 v225, v226, v225
	v_div_scale_f32 v226, vcc, 1.0, v125, 1.0
	v_mul_f32_e32 v227, v226, v225
	v_fma_f32 v228, -v224, v227, v226
	v_fmac_f32_e32 v227, v228, v225
	v_fma_f32 v224, -v224, v227, v226
	v_div_fmas_f32 v224, v224, v225, v227
	v_div_fixup_f32 v125, v224, v125, 1.0
	v_div_scale_f32 v224, s[10:11], v126, v126, 1.0
	v_rcp_f32_e32 v225, v224
	s_nop 0
	v_fma_f32 v226, -v224, v225, 1.0
	v_fmac_f32_e32 v225, v226, v225
	v_div_scale_f32 v226, vcc, 1.0, v126, 1.0
	v_mul_f32_e32 v227, v226, v225
	v_fma_f32 v228, -v224, v227, v226
	v_fmac_f32_e32 v227, v228, v225
	v_fma_f32 v224, -v224, v227, v226
	v_div_fmas_f32 v224, v224, v225, v227
	v_div_fixup_f32 v126, v224, v126, 1.0
	v_div_scale_f32 v224, s[10:11], v127, v127, 1.0
	v_rcp_f32_e32 v225, v224
	s_nop 0
	v_fma_f32 v226, -v224, v225, 1.0
	v_fmac_f32_e32 v225, v226, v225
	v_div_scale_f32 v226, vcc, 1.0, v127, 1.0
	v_mul_f32_e32 v227, v226, v225
	v_fma_f32 v228, -v224, v227, v226
	v_fmac_f32_e32 v227, v228, v225
	v_fma_f32 v224, -v224, v227, v226
	v_div_fmas_f32 v224, v224, v225, v227
	v_div_fixup_f32 v127, v224, v127, 1.0
	v_lshlrev_b32_e32 v236, 16, v184
	v_and_b32_e32 v237, 0xffff0000, v184
	v_lshlrev_b32_e32 v238, 16, v185
	v_and_b32_e32 v239, 0xffff0000, v185
	v_pk_fma_f32 v[124:125], v[124:125], v[236:237], v[168:169]
	v_pk_fma_f32 v[126:127], v[126:127], v[238:239], v[170:171]
	v_cvt_pk_bf16_f32 v157, v126, v127
	v_cvt_pk_bf16_f32 v156, v124, v125
	global_store_dwordx4 v[150:151], v[124:127], off
	s_nop 1
	v_mul_f32_e32 v125, v125, v125
	v_mul_f32_e32 v127, v127, v127
	v_fmac_f32_e32 v125, v124, v124
	v_fmac_f32_e32 v127, v126, v126
	v_add_f32_e32 v229, v125, v127
	v_pk_mul_f32 v[120:121], v[120:121], v[234:235] op_sel_hi:[1,0]
	v_pk_mul_f32 v[122:123], v[122:123], v[234:235] op_sel_hi:[1,0]
	v_mul_f32_e32 v120, 0xbfb8aa3b, v120
	v_mul_f32_e32 v121, 0xbfb8aa3b, v121
	v_mul_f32_e32 v122, 0xbfb8aa3b, v122
	v_mul_f32_e32 v123, 0xbfb8aa3b, v123
	v_exp_f32_e32 v120, v120
	v_exp_f32_e32 v121, v121
	v_exp_f32_e32 v122, v122
	v_exp_f32_e32 v123, v123
	v_pk_add_f32 v[120:121], v[120:121], 1.0 op_sel_hi:[1,0]
	v_pk_add_f32 v[122:123], v[122:123], 1.0 op_sel_hi:[1,0]
	v_div_scale_f32 v224, s[10:11], v120, v120, 1.0
	v_rcp_f32_e32 v225, v224
	s_nop 0
	v_fma_f32 v226, -v224, v225, 1.0
	v_fmac_f32_e32 v225, v226, v225
	v_div_scale_f32 v226, vcc, 1.0, v120, 1.0
	v_mul_f32_e32 v227, v226, v225
	v_fma_f32 v228, -v224, v227, v226
	v_fmac_f32_e32 v227, v228, v225
	v_fma_f32 v224, -v224, v227, v226
	v_div_fmas_f32 v224, v224, v225, v227
	v_div_fixup_f32 v120, v224, v120, 1.0
	v_div_scale_f32 v224, s[10:11], v121, v121, 1.0
	v_rcp_f32_e32 v225, v224
	s_nop 0
	v_fma_f32 v226, -v224, v225, 1.0
	v_fmac_f32_e32 v225, v226, v225
	v_div_scale_f32 v226, vcc, 1.0, v121, 1.0
	v_mul_f32_e32 v227, v226, v225
	v_fma_f32 v228, -v224, v227, v226
	v_fmac_f32_e32 v227, v228, v225
	v_fma_f32 v224, -v224, v227, v226
	v_div_fmas_f32 v224, v224, v225, v227
	v_div_fixup_f32 v121, v224, v121, 1.0
	v_div_scale_f32 v224, s[10:11], v122, v122, 1.0
	v_rcp_f32_e32 v225, v224
	s_nop 0
	v_fma_f32 v226, -v224, v225, 1.0
	v_fmac_f32_e32 v225, v226, v225
	v_div_scale_f32 v226, vcc, 1.0, v122, 1.0
	v_mul_f32_e32 v227, v226, v225
	v_fma_f32 v228, -v224, v227, v226
	v_fmac_f32_e32 v227, v228, v225
	v_fma_f32 v224, -v224, v227, v226
	v_div_fmas_f32 v224, v224, v225, v227
	v_div_fixup_f32 v122, v224, v122, 1.0
	v_div_scale_f32 v224, s[10:11], v123, v123, 1.0
	v_rcp_f32_e32 v225, v224
	s_nop 0
	v_fma_f32 v226, -v224, v225, 1.0
	v_fmac_f32_e32 v225, v226, v225
	v_div_scale_f32 v226, vcc, 1.0, v123, 1.0
	v_mul_f32_e32 v227, v226, v225
	v_fma_f32 v228, -v224, v227, v226
	v_fmac_f32_e32 v227, v228, v225
	v_fma_f32 v224, -v224, v227, v226
	v_div_fmas_f32 v224, v224, v225, v227
	v_div_fixup_f32 v123, v224, v123, 1.0
	v_lshlrev_b32_e32 v236, 16, v186
	v_and_b32_e32 v237, 0xffff0000, v186
	v_lshlrev_b32_e32 v238, 16, v187
	v_and_b32_e32 v239, 0xffff0000, v187
	v_pk_fma_f32 v[120:121], v[120:121], v[236:237], v[172:173]
	v_pk_fma_f32 v[122:123], v[122:123], v[238:239], v[174:175]
	v_cvt_pk_bf16_f32 v159, v122, v123
	v_cvt_pk_bf16_f32 v158, v120, v121
	global_store_dwordx4 v[150:151], v[120:123], off offset:64
	s_nop 1
	v_mul_f32_e32 v121, v121, v121
	v_mul_f32_e32 v123, v123, v123
	v_fmac_f32_e32 v121, v120, v120
	v_fmac_f32_e32 v123, v122, v122
	v_add_f32_e32 v120, v121, v123
	v_add_f32_e32 v229, v229, v120
	v_permlane16_swap_b32_e32 v156, v158
	v_permlane16_swap_b32_e32 v157, v159
	global_store_dwordx4 v[166:167], v[156:159], off
	s_nop 0
	v_pk_mul_f32 v[116:117], v[116:117], v[234:235] op_sel_hi:[1,0]
	v_pk_mul_f32 v[118:119], v[118:119], v[234:235] op_sel_hi:[1,0]
	v_mul_f32_e32 v116, 0xbfb8aa3b, v116
	v_mul_f32_e32 v117, 0xbfb8aa3b, v117
	v_mul_f32_e32 v118, 0xbfb8aa3b, v118
	v_mul_f32_e32 v119, 0xbfb8aa3b, v119
	v_exp_f32_e32 v116, v116
	v_exp_f32_e32 v117, v117
	v_exp_f32_e32 v118, v118
	v_exp_f32_e32 v119, v119
	v_pk_add_f32 v[116:117], v[116:117], 1.0 op_sel_hi:[1,0]
	v_pk_add_f32 v[118:119], v[118:119], 1.0 op_sel_hi:[1,0]
	v_div_scale_f32 v224, s[10:11], v116, v116, 1.0
	v_rcp_f32_e32 v225, v224
	s_nop 0
	v_fma_f32 v226, -v224, v225, 1.0
	v_fmac_f32_e32 v225, v226, v225
	v_div_scale_f32 v226, vcc, 1.0, v116, 1.0
	v_mul_f32_e32 v227, v226, v225
	v_fma_f32 v228, -v224, v227, v226
	v_fmac_f32_e32 v227, v228, v225
	v_fma_f32 v224, -v224, v227, v226
	v_div_fmas_f32 v224, v224, v225, v227
	v_div_fixup_f32 v116, v224, v116, 1.0
	v_div_scale_f32 v224, s[10:11], v117, v117, 1.0
	v_rcp_f32_e32 v225, v224
	s_nop 0
	v_fma_f32 v226, -v224, v225, 1.0
	v_fmac_f32_e32 v225, v226, v225
	v_div_scale_f32 v226, vcc, 1.0, v117, 1.0
	v_mul_f32_e32 v227, v226, v225
	v_fma_f32 v228, -v224, v227, v226
	v_fmac_f32_e32 v227, v228, v225
	v_fma_f32 v224, -v224, v227, v226
	v_div_fmas_f32 v224, v224, v225, v227
	v_div_fixup_f32 v117, v224, v117, 1.0
	v_div_scale_f32 v224, s[10:11], v118, v118, 1.0
	v_rcp_f32_e32 v225, v224
	s_nop 0
	v_fma_f32 v226, -v224, v225, 1.0
	v_fmac_f32_e32 v225, v226, v225
	v_div_scale_f32 v226, vcc, 1.0, v118, 1.0
	v_mul_f32_e32 v227, v226, v225
	v_fma_f32 v228, -v224, v227, v226
	v_fmac_f32_e32 v227, v228, v225
	v_fma_f32 v224, -v224, v227, v226
	v_div_fmas_f32 v224, v224, v225, v227
	v_div_fixup_f32 v118, v224, v118, 1.0
	v_div_scale_f32 v224, s[10:11], v119, v119, 1.0
	v_rcp_f32_e32 v225, v224
	s_nop 0
	v_fma_f32 v226, -v224, v225, 1.0
	v_fmac_f32_e32 v225, v226, v225
	v_div_scale_f32 v226, vcc, 1.0, v119, 1.0
	v_mul_f32_e32 v227, v226, v225
	v_fma_f32 v228, -v224, v227, v226
	v_fmac_f32_e32 v227, v228, v225
	v_fma_f32 v224, -v224, v227, v226
	v_div_fmas_f32 v224, v224, v225, v227
	v_div_fixup_f32 v119, v224, v119, 1.0
	v_lshlrev_b32_e32 v236, 16, v188
	v_and_b32_e32 v237, 0xffff0000, v188
	v_lshlrev_b32_e32 v238, 16, v189
	v_and_b32_e32 v239, 0xffff0000, v189
	v_pk_fma_f32 v[116:117], v[116:117], v[236:237], v[176:177]
	v_pk_fma_f32 v[118:119], v[118:119], v[238:239], v[178:179]
	v_cvt_pk_bf16_f32 v157, v118, v119
	v_cvt_pk_bf16_f32 v156, v116, v117
	global_store_dwordx4 v[150:151], v[116:119], off offset:512
	s_nop 1
	v_mul_f32_e32 v117, v117, v117
	v_mul_f32_e32 v119, v119, v119
	v_fmac_f32_e32 v117, v116, v116
	v_fmac_f32_e32 v119, v118, v118
	v_add_f32_e32 v116, v117, v119
	v_add_f32_e32 v229, v229, v116
	v_pk_mul_f32 v[112:113], v[112:113], v[234:235] op_sel_hi:[1,0]
	v_pk_mul_f32 v[114:115], v[114:115], v[234:235] op_sel_hi:[1,0]
	v_mul_f32_e32 v112, 0xbfb8aa3b, v112
	v_mul_f32_e32 v113, 0xbfb8aa3b, v113
	v_mul_f32_e32 v114, 0xbfb8aa3b, v114
	v_mul_f32_e32 v115, 0xbfb8aa3b, v115
	v_exp_f32_e32 v112, v112
	v_exp_f32_e32 v113, v113
	v_exp_f32_e32 v114, v114
	v_exp_f32_e32 v115, v115
	v_pk_add_f32 v[112:113], v[112:113], 1.0 op_sel_hi:[1,0]
	v_pk_add_f32 v[114:115], v[114:115], 1.0 op_sel_hi:[1,0]
	v_div_scale_f32 v224, s[10:11], v112, v112, 1.0
	v_rcp_f32_e32 v225, v224
	s_nop 0
	v_fma_f32 v226, -v224, v225, 1.0
	v_fmac_f32_e32 v225, v226, v225
	v_div_scale_f32 v226, vcc, 1.0, v112, 1.0
	v_mul_f32_e32 v227, v226, v225
	v_fma_f32 v228, -v224, v227, v226
	v_fmac_f32_e32 v227, v228, v225
	v_fma_f32 v224, -v224, v227, v226
	v_div_fmas_f32 v224, v224, v225, v227
	v_div_fixup_f32 v112, v224, v112, 1.0
	v_div_scale_f32 v224, s[10:11], v113, v113, 1.0
	v_rcp_f32_e32 v225, v224
	s_nop 0
	v_fma_f32 v226, -v224, v225, 1.0
	v_fmac_f32_e32 v225, v226, v225
	v_div_scale_f32 v226, vcc, 1.0, v113, 1.0
	v_mul_f32_e32 v227, v226, v225
	v_fma_f32 v228, -v224, v227, v226
	v_fmac_f32_e32 v227, v228, v225
	v_fma_f32 v224, -v224, v227, v226
	v_div_fmas_f32 v224, v224, v225, v227
	v_div_fixup_f32 v113, v224, v113, 1.0
	v_div_scale_f32 v224, s[10:11], v114, v114, 1.0
	v_rcp_f32_e32 v225, v224
	s_nop 0
	v_fma_f32 v226, -v224, v225, 1.0
	v_fmac_f32_e32 v225, v226, v225
	v_div_scale_f32 v226, vcc, 1.0, v114, 1.0
	v_mul_f32_e32 v227, v226, v225
	v_fma_f32 v228, -v224, v227, v226
	v_fmac_f32_e32 v227, v228, v225
	v_fma_f32 v224, -v224, v227, v226
	v_div_fmas_f32 v224, v224, v225, v227
	v_div_fixup_f32 v114, v224, v114, 1.0
	v_div_scale_f32 v224, s[10:11], v115, v115, 1.0
	v_rcp_f32_e32 v225, v224
	s_nop 0
	v_fma_f32 v226, -v224, v225, 1.0
	v_fmac_f32_e32 v225, v226, v225
	v_div_scale_f32 v226, vcc, 1.0, v115, 1.0
	v_mul_f32_e32 v227, v226, v225
	v_fma_f32 v228, -v224, v227, v226
	v_fmac_f32_e32 v227, v228, v225
	v_fma_f32 v224, -v224, v227, v226
	v_div_fmas_f32 v224, v224, v225, v227
	v_div_fixup_f32 v115, v224, v115, 1.0
	v_lshlrev_b32_e32 v236, 16, v190
	v_and_b32_e32 v237, 0xffff0000, v190
	v_lshlrev_b32_e32 v238, 16, v191
	v_and_b32_e32 v239, 0xffff0000, v191
	v_pk_fma_f32 v[112:113], v[112:113], v[236:237], v[180:181]
	v_pk_fma_f32 v[114:115], v[114:115], v[238:239], v[182:183]
	v_cvt_pk_bf16_f32 v159, v114, v115
	v_cvt_pk_bf16_f32 v158, v112, v113
	global_store_dwordx4 v[150:151], v[112:115], off offset:576
	s_nop 1
	v_mul_f32_e32 v113, v113, v113
	v_mul_f32_e32 v115, v115, v115
	v_fmac_f32_e32 v113, v112, v112
	v_fmac_f32_e32 v115, v114, v114
	v_add_f32_e32 v112, v113, v115
	v_add_f32_e32 v229, v229, v112
	v_permlane16_swap_b32_e32 v156, v158
	v_permlane16_swap_b32_e32 v157, v159
	global_store_dwordx4 v[166:167], v[156:159], off offset:256
	s_nop 0
	v_mov_b32_e32 v230, v229
	s_nop 1
	v_permlane16_swap_b32_e32 v229, v230
	v_add_f32_e32 v229, v229, v230
	v_mov_b32_e32 v230, v229
	s_nop 1
	v_permlane32_swap_b32_e32 v229, v230
	s_and_saveexec_b64 s[10:11], s[6:7]
	v_lshl_add_u64 v[156:157], v[144:145], 2, s[18:19]
	v_add_f32_e32 v229, v229, v230
	global_atomic_add_f32 v[156:157], v229, off
	s_or_b64 exec, exec, s[10:11]
	v_add_u32_e32 v144, 0x20, v154
	v_mov_b32_e32 v145, v155
	v_lshlrev_b64 v[148:149], 11, v[144:145]
	v_lshl_add_u64 v[148:149], v[148:149], 0, v[146:147]
	v_lshl_add_u64 v[150:151], v[148:149], 2, s[28:29]
	v_lshl_add_u64 v[152:153], v[148:149], 1, s[42:43]
	global_load_dwordx2 v[184:185], v[152:153], off
	global_load_dwordx4 v[168:171], v[150:151], off
	global_load_dwordx2 v[186:187], v[152:153], off offset:32
	global_load_dwordx4 v[172:175], v[150:151], off offset:64
	global_load_dwordx2 v[188:189], v[152:153], off offset:256
	global_load_dwordx4 v[176:179], v[150:151], off offset:512
	global_load_dwordx2 v[190:191], v[152:153], off offset:288
	global_load_dwordx4 v[180:183], v[150:151], off offset:576
	s_waitcnt vmcnt(15)
	v_fmamk_f32 v217, v217, 0x3a000000, v164
	v_mul_f32_e32 v235, 0x4b800000, v217
	v_cmp_gt_f32_e32 vcc, s61, v217
	s_nop 1
	v_cndmask_b32_e32 v217, v217, v235, vcc
	v_rsq_f32_e32 v217, v217
	s_nop 0
	v_mul_f32_e32 v235, 0x45800000, v217
	v_cndmask_b32_e32 v234, v217, v235, vcc
	v_add_u32_e32 v144, 0x10, v154
	v_mov_b32_e32 v145, v155
	v_lshlrev_b64 v[148:149], 11, v[144:145]
	v_lshl_add_u64 v[148:149], v[148:149], 0, v[146:147]
	v_lshl_add_u64 v[150:151], v[148:149], 2, s[28:29]
	v_lshl_add_u64 v[166:167], v[148:149], 1, s[24:25]
	v_add_co_u32_e32 v166, vcc, v166, v231
	s_nop 1
	v_addc_co_u32_e32 v167, vcc, 0, v167, vcc
	v_pk_mul_f32 v[108:109], v[108:109], v[234:235] op_sel_hi:[1,0]
	v_pk_mul_f32 v[110:111], v[110:111], v[234:235] op_sel_hi:[1,0]
	v_mul_f32_e32 v108, 0xbfb8aa3b, v108
	v_mul_f32_e32 v109, 0xbfb8aa3b, v109
	v_mul_f32_e32 v110, 0xbfb8aa3b, v110
	v_mul_f32_e32 v111, 0xbfb8aa3b, v111
	v_exp_f32_e32 v108, v108
	v_exp_f32_e32 v109, v109
	v_exp_f32_e32 v110, v110
	v_exp_f32_e32 v111, v111
	v_pk_add_f32 v[108:109], v[108:109], 1.0 op_sel_hi:[1,0]
	v_pk_add_f32 v[110:111], v[110:111], 1.0 op_sel_hi:[1,0]
	v_div_scale_f32 v224, s[10:11], v108, v108, 1.0
	v_rcp_f32_e32 v225, v224
	s_nop 0
	v_fma_f32 v226, -v224, v225, 1.0
	v_fmac_f32_e32 v225, v226, v225
	v_div_scale_f32 v226, vcc, 1.0, v108, 1.0
	v_mul_f32_e32 v227, v226, v225
	v_fma_f32 v228, -v224, v227, v226
	v_fmac_f32_e32 v227, v228, v225
	v_fma_f32 v224, -v224, v227, v226
	v_div_fmas_f32 v224, v224, v225, v227
	v_div_fixup_f32 v108, v224, v108, 1.0
	v_div_scale_f32 v224, s[10:11], v109, v109, 1.0
	v_rcp_f32_e32 v225, v224
	s_nop 0
	v_fma_f32 v226, -v224, v225, 1.0
	v_fmac_f32_e32 v225, v226, v225
	v_div_scale_f32 v226, vcc, 1.0, v109, 1.0
	v_mul_f32_e32 v227, v226, v225
	v_fma_f32 v228, -v224, v227, v226
	v_fmac_f32_e32 v227, v228, v225
	v_fma_f32 v224, -v224, v227, v226
	v_div_fmas_f32 v224, v224, v225, v227
	v_div_fixup_f32 v109, v224, v109, 1.0
	v_div_scale_f32 v224, s[10:11], v110, v110, 1.0
	v_rcp_f32_e32 v225, v224
	s_nop 0
	v_fma_f32 v226, -v224, v225, 1.0
	v_fmac_f32_e32 v225, v226, v225
	v_div_scale_f32 v226, vcc, 1.0, v110, 1.0
	v_mul_f32_e32 v227, v226, v225
	v_fma_f32 v228, -v224, v227, v226
	v_fmac_f32_e32 v227, v228, v225
	v_fma_f32 v224, -v224, v227, v226
	v_div_fmas_f32 v224, v224, v225, v227
	v_div_fixup_f32 v110, v224, v110, 1.0
	v_div_scale_f32 v224, s[10:11], v111, v111, 1.0
	v_rcp_f32_e32 v225, v224
	s_nop 0
	v_fma_f32 v226, -v224, v225, 1.0
	v_fmac_f32_e32 v225, v226, v225
	v_div_scale_f32 v226, vcc, 1.0, v111, 1.0
	v_mul_f32_e32 v227, v226, v225
	v_fma_f32 v228, -v224, v227, v226
	v_fmac_f32_e32 v227, v228, v225
	v_fma_f32 v224, -v224, v227, v226
	v_div_fmas_f32 v224, v224, v225, v227
	v_div_fixup_f32 v111, v224, v111, 1.0
	v_lshlrev_b32_e32 v236, 16, v208
	v_and_b32_e32 v237, 0xffff0000, v208
	v_lshlrev_b32_e32 v238, 16, v209
	v_and_b32_e32 v239, 0xffff0000, v209
	v_pk_fma_f32 v[108:109], v[108:109], v[236:237], v[192:193]
	v_pk_fma_f32 v[110:111], v[110:111], v[238:239], v[194:195]
	v_cvt_pk_bf16_f32 v157, v110, v111
	v_cvt_pk_bf16_f32 v156, v108, v109
	global_store_dwordx4 v[150:151], v[108:111], off
	s_nop 1
	v_mul_f32_e32 v109, v109, v109
	v_mul_f32_e32 v111, v111, v111
	v_fmac_f32_e32 v109, v108, v108
	v_fmac_f32_e32 v111, v110, v110
	v_add_f32_e32 v229, v109, v111
	v_pk_mul_f32 v[104:105], v[104:105], v[234:235] op_sel_hi:[1,0]
	v_pk_mul_f32 v[106:107], v[106:107], v[234:235] op_sel_hi:[1,0]
	v_mul_f32_e32 v104, 0xbfb8aa3b, v104
	v_mul_f32_e32 v105, 0xbfb8aa3b, v105
	v_mul_f32_e32 v106, 0xbfb8aa3b, v106
	v_mul_f32_e32 v107, 0xbfb8aa3b, v107
	v_exp_f32_e32 v104, v104
	v_exp_f32_e32 v105, v105
	v_exp_f32_e32 v106, v106
	v_exp_f32_e32 v107, v107
	v_pk_add_f32 v[104:105], v[104:105], 1.0 op_sel_hi:[1,0]
	v_pk_add_f32 v[106:107], v[106:107], 1.0 op_sel_hi:[1,0]
	v_div_scale_f32 v224, s[10:11], v104, v104, 1.0
	v_rcp_f32_e32 v225, v224
	s_nop 0
	v_fma_f32 v226, -v224, v225, 1.0
	v_fmac_f32_e32 v225, v226, v225
	v_div_scale_f32 v226, vcc, 1.0, v104, 1.0
	v_mul_f32_e32 v227, v226, v225
	v_fma_f32 v228, -v224, v227, v226
	v_fmac_f32_e32 v227, v228, v225
	v_fma_f32 v224, -v224, v227, v226
	v_div_fmas_f32 v224, v224, v225, v227
	v_div_fixup_f32 v104, v224, v104, 1.0
	v_div_scale_f32 v224, s[10:11], v105, v105, 1.0
	v_rcp_f32_e32 v225, v224
	s_nop 0
	v_fma_f32 v226, -v224, v225, 1.0
	v_fmac_f32_e32 v225, v226, v225
	v_div_scale_f32 v226, vcc, 1.0, v105, 1.0
	v_mul_f32_e32 v227, v226, v225
	v_fma_f32 v228, -v224, v227, v226
	v_fmac_f32_e32 v227, v228, v225
	v_fma_f32 v224, -v224, v227, v226
	v_div_fmas_f32 v224, v224, v225, v227
	v_div_fixup_f32 v105, v224, v105, 1.0
	v_div_scale_f32 v224, s[10:11], v106, v106, 1.0
	v_rcp_f32_e32 v225, v224
	s_nop 0
	v_fma_f32 v226, -v224, v225, 1.0
	v_fmac_f32_e32 v225, v226, v225
	v_div_scale_f32 v226, vcc, 1.0, v106, 1.0
	v_mul_f32_e32 v227, v226, v225
	v_fma_f32 v228, -v224, v227, v226
	v_fmac_f32_e32 v227, v228, v225
	v_fma_f32 v224, -v224, v227, v226
	v_div_fmas_f32 v224, v224, v225, v227
	v_div_fixup_f32 v106, v224, v106, 1.0
	v_div_scale_f32 v224, s[10:11], v107, v107, 1.0
	v_rcp_f32_e32 v225, v224
	s_nop 0
	v_fma_f32 v226, -v224, v225, 1.0
	v_fmac_f32_e32 v225, v226, v225
	v_div_scale_f32 v226, vcc, 1.0, v107, 1.0
	v_mul_f32_e32 v227, v226, v225
	v_fma_f32 v228, -v224, v227, v226
	v_fmac_f32_e32 v227, v228, v225
	v_fma_f32 v224, -v224, v227, v226
	v_div_fmas_f32 v224, v224, v225, v227
	v_div_fixup_f32 v107, v224, v107, 1.0
	v_lshlrev_b32_e32 v236, 16, v210
	v_and_b32_e32 v237, 0xffff0000, v210
	v_lshlrev_b32_e32 v238, 16, v211
	v_and_b32_e32 v239, 0xffff0000, v211
	v_pk_fma_f32 v[104:105], v[104:105], v[236:237], v[196:197]
	v_pk_fma_f32 v[106:107], v[106:107], v[238:239], v[198:199]
	v_cvt_pk_bf16_f32 v159, v106, v107
	v_cvt_pk_bf16_f32 v158, v104, v105
	global_store_dwordx4 v[150:151], v[104:107], off offset:64
	s_nop 1
	v_mul_f32_e32 v105, v105, v105
	v_mul_f32_e32 v107, v107, v107
	v_fmac_f32_e32 v105, v104, v104
	v_fmac_f32_e32 v107, v106, v106
	v_add_f32_e32 v104, v105, v107
	v_add_f32_e32 v229, v229, v104
	v_permlane16_swap_b32_e32 v156, v158
	v_permlane16_swap_b32_e32 v157, v159
	global_store_dwordx4 v[166:167], v[156:159], off
	s_nop 0
	v_pk_mul_f32 v[100:101], v[100:101], v[234:235] op_sel_hi:[1,0]
	v_pk_mul_f32 v[102:103], v[102:103], v[234:235] op_sel_hi:[1,0]
	v_mul_f32_e32 v100, 0xbfb8aa3b, v100
	v_mul_f32_e32 v101, 0xbfb8aa3b, v101
	v_mul_f32_e32 v102, 0xbfb8aa3b, v102
	v_mul_f32_e32 v103, 0xbfb8aa3b, v103
	v_exp_f32_e32 v100, v100
	v_exp_f32_e32 v101, v101
	v_exp_f32_e32 v102, v102
	v_exp_f32_e32 v103, v103
	v_pk_add_f32 v[100:101], v[100:101], 1.0 op_sel_hi:[1,0]
	v_pk_add_f32 v[102:103], v[102:103], 1.0 op_sel_hi:[1,0]
	v_div_scale_f32 v224, s[10:11], v100, v100, 1.0
	v_rcp_f32_e32 v225, v224
	s_nop 0
	v_fma_f32 v226, -v224, v225, 1.0
	v_fmac_f32_e32 v225, v226, v225
	v_div_scale_f32 v226, vcc, 1.0, v100, 1.0
	v_mul_f32_e32 v227, v226, v225
	v_fma_f32 v228, -v224, v227, v226
	v_fmac_f32_e32 v227, v228, v225
	v_fma_f32 v224, -v224, v227, v226
	v_div_fmas_f32 v224, v224, v225, v227
	v_div_fixup_f32 v100, v224, v100, 1.0
	v_div_scale_f32 v224, s[10:11], v101, v101, 1.0
	v_rcp_f32_e32 v225, v224
	s_nop 0
	v_fma_f32 v226, -v224, v225, 1.0
	v_fmac_f32_e32 v225, v226, v225
	v_div_scale_f32 v226, vcc, 1.0, v101, 1.0
	v_mul_f32_e32 v227, v226, v225
	v_fma_f32 v228, -v224, v227, v226
	v_fmac_f32_e32 v227, v228, v225
	v_fma_f32 v224, -v224, v227, v226
	v_div_fmas_f32 v224, v224, v225, v227
	v_div_fixup_f32 v101, v224, v101, 1.0
	v_div_scale_f32 v224, s[10:11], v102, v102, 1.0
	v_rcp_f32_e32 v225, v224
	s_nop 0
	v_fma_f32 v226, -v224, v225, 1.0
	v_fmac_f32_e32 v225, v226, v225
	v_div_scale_f32 v226, vcc, 1.0, v102, 1.0
	v_mul_f32_e32 v227, v226, v225
	v_fma_f32 v228, -v224, v227, v226
	v_fmac_f32_e32 v227, v228, v225
	v_fma_f32 v224, -v224, v227, v226
	v_div_fmas_f32 v224, v224, v225, v227
	v_div_fixup_f32 v102, v224, v102, 1.0
	v_div_scale_f32 v224, s[10:11], v103, v103, 1.0
	v_rcp_f32_e32 v225, v224
	s_nop 0
	v_fma_f32 v226, -v224, v225, 1.0
	v_fmac_f32_e32 v225, v226, v225
	v_div_scale_f32 v226, vcc, 1.0, v103, 1.0
	v_mul_f32_e32 v227, v226, v225
	v_fma_f32 v228, -v224, v227, v226
	v_fmac_f32_e32 v227, v228, v225
	v_fma_f32 v224, -v224, v227, v226
	v_div_fmas_f32 v224, v224, v225, v227
	v_div_fixup_f32 v103, v224, v103, 1.0
	v_lshlrev_b32_e32 v236, 16, v212
	v_and_b32_e32 v237, 0xffff0000, v212
	v_lshlrev_b32_e32 v238, 16, v213
	v_and_b32_e32 v239, 0xffff0000, v213
	v_pk_fma_f32 v[100:101], v[100:101], v[236:237], v[200:201]
	v_pk_fma_f32 v[102:103], v[102:103], v[238:239], v[202:203]
	v_cvt_pk_bf16_f32 v157, v102, v103
	v_cvt_pk_bf16_f32 v156, v100, v101
	global_store_dwordx4 v[150:151], v[100:103], off offset:512
	s_nop 1
	v_mul_f32_e32 v101, v101, v101
	v_mul_f32_e32 v103, v103, v103
	v_fmac_f32_e32 v101, v100, v100
	v_fmac_f32_e32 v103, v102, v102
	v_add_f32_e32 v100, v101, v103
	v_add_f32_e32 v229, v229, v100
	v_pk_mul_f32 v[96:97], v[96:97], v[234:235] op_sel_hi:[1,0]
	v_pk_mul_f32 v[98:99], v[98:99], v[234:235] op_sel_hi:[1,0]
	v_mul_f32_e32 v96, 0xbfb8aa3b, v96
	v_mul_f32_e32 v97, 0xbfb8aa3b, v97
	v_mul_f32_e32 v98, 0xbfb8aa3b, v98
	v_mul_f32_e32 v99, 0xbfb8aa3b, v99
	v_exp_f32_e32 v96, v96
	v_exp_f32_e32 v97, v97
	v_exp_f32_e32 v98, v98
	v_exp_f32_e32 v99, v99
	v_pk_add_f32 v[96:97], v[96:97], 1.0 op_sel_hi:[1,0]
	v_pk_add_f32 v[98:99], v[98:99], 1.0 op_sel_hi:[1,0]
	v_div_scale_f32 v224, s[10:11], v96, v96, 1.0
	v_rcp_f32_e32 v225, v224
	s_nop 0
	v_fma_f32 v226, -v224, v225, 1.0
	v_fmac_f32_e32 v225, v226, v225
	v_div_scale_f32 v226, vcc, 1.0, v96, 1.0
	v_mul_f32_e32 v227, v226, v225
	v_fma_f32 v228, -v224, v227, v226
	v_fmac_f32_e32 v227, v228, v225
	v_fma_f32 v224, -v224, v227, v226
	v_div_fmas_f32 v224, v224, v225, v227
	v_div_fixup_f32 v96, v224, v96, 1.0
	v_div_scale_f32 v224, s[10:11], v97, v97, 1.0
	v_rcp_f32_e32 v225, v224
	s_nop 0
	v_fma_f32 v226, -v224, v225, 1.0
	v_fmac_f32_e32 v225, v226, v225
	v_div_scale_f32 v226, vcc, 1.0, v97, 1.0
	v_mul_f32_e32 v227, v226, v225
	v_fma_f32 v228, -v224, v227, v226
	v_fmac_f32_e32 v227, v228, v225
	v_fma_f32 v224, -v224, v227, v226
	v_div_fmas_f32 v224, v224, v225, v227
	v_div_fixup_f32 v97, v224, v97, 1.0
	v_div_scale_f32 v224, s[10:11], v98, v98, 1.0
	v_rcp_f32_e32 v225, v224
	s_nop 0
	v_fma_f32 v226, -v224, v225, 1.0
	v_fmac_f32_e32 v225, v226, v225
	v_div_scale_f32 v226, vcc, 1.0, v98, 1.0
	v_mul_f32_e32 v227, v226, v225
	v_fma_f32 v228, -v224, v227, v226
	v_fmac_f32_e32 v227, v228, v225
	v_fma_f32 v224, -v224, v227, v226
	v_div_fmas_f32 v224, v224, v225, v227
	v_div_fixup_f32 v98, v224, v98, 1.0
	v_div_scale_f32 v224, s[10:11], v99, v99, 1.0
	v_rcp_f32_e32 v225, v224
	s_nop 0
	v_fma_f32 v226, -v224, v225, 1.0
	v_fmac_f32_e32 v225, v226, v225
	v_div_scale_f32 v226, vcc, 1.0, v99, 1.0
	v_mul_f32_e32 v227, v226, v225
	v_fma_f32 v228, -v224, v227, v226
	v_fmac_f32_e32 v227, v228, v225
	v_fma_f32 v224, -v224, v227, v226
	v_div_fmas_f32 v224, v224, v225, v227
	v_div_fixup_f32 v99, v224, v99, 1.0
	v_lshlrev_b32_e32 v236, 16, v214
	v_and_b32_e32 v237, 0xffff0000, v214
	v_lshlrev_b32_e32 v238, 16, v215
	v_and_b32_e32 v239, 0xffff0000, v215
	v_pk_fma_f32 v[96:97], v[96:97], v[236:237], v[204:205]
	v_pk_fma_f32 v[98:99], v[98:99], v[238:239], v[206:207]
	v_cvt_pk_bf16_f32 v159, v98, v99
	v_cvt_pk_bf16_f32 v158, v96, v97
	global_store_dwordx4 v[150:151], v[96:99], off offset:576
	s_nop 1
	v_mul_f32_e32 v97, v97, v97
	v_mul_f32_e32 v99, v99, v99
	v_fmac_f32_e32 v97, v96, v96
	v_fmac_f32_e32 v99, v98, v98
	v_add_f32_e32 v96, v97, v99
	v_add_f32_e32 v229, v229, v96
	v_permlane16_swap_b32_e32 v156, v158
	v_permlane16_swap_b32_e32 v157, v159
	global_store_dwordx4 v[166:167], v[156:159], off offset:256
	s_nop 0
	v_mov_b32_e32 v230, v229
	s_nop 1
	v_permlane16_swap_b32_e32 v229, v230
	v_add_f32_e32 v229, v229, v230
	v_mov_b32_e32 v230, v229
	s_nop 1
	v_permlane32_swap_b32_e32 v229, v230
	s_and_saveexec_b64 s[10:11], s[6:7]
	v_lshl_add_u64 v[156:157], v[144:145], 2, s[18:19]
	v_add_f32_e32 v229, v229, v230
	global_atomic_add_f32 v[156:157], v229, off
	s_or_b64 exec, exec, s[10:11]
	v_add_u32_e32 v144, 0x30, v154
	v_mov_b32_e32 v145, v155
	v_lshlrev_b64 v[148:149], 11, v[144:145]
	v_lshl_add_u64 v[148:149], v[148:149], 0, v[146:147]
	v_lshl_add_u64 v[150:151], v[148:149], 2, s[28:29]
	v_lshl_add_u64 v[152:153], v[148:149], 1, s[42:43]
	global_load_dwordx2 v[208:209], v[152:153], off
	global_load_dwordx4 v[192:195], v[150:151], off
	global_load_dwordx2 v[210:211], v[152:153], off offset:32
	global_load_dwordx4 v[196:199], v[150:151], off offset:64
	global_load_dwordx2 v[212:213], v[152:153], off offset:256
	global_load_dwordx4 v[200:203], v[150:151], off offset:512
	global_load_dwordx2 v[214:215], v[152:153], off offset:288
	global_load_dwordx4 v[204:207], v[150:151], off offset:576
	s_waitcnt vmcnt(15)
	v_fmamk_f32 v218, v218, 0x3a000000, v164
	v_mul_f32_e32 v235, 0x4b800000, v218
	v_cmp_gt_f32_e32 vcc, s61, v218
	s_nop 1
	v_cndmask_b32_e32 v218, v218, v235, vcc
	v_rsq_f32_e32 v218, v218
	s_nop 0
	v_mul_f32_e32 v235, 0x45800000, v218
	v_cndmask_b32_e32 v234, v218, v235, vcc
	v_add_u32_e32 v144, 0x20, v154
	v_mov_b32_e32 v145, v155
	v_lshlrev_b64 v[148:149], 11, v[144:145]
	v_lshl_add_u64 v[148:149], v[148:149], 0, v[146:147]
	v_lshl_add_u64 v[150:151], v[148:149], 2, s[28:29]
	v_lshl_add_u64 v[166:167], v[148:149], 1, s[24:25]
	v_add_co_u32_e32 v166, vcc, v166, v231
	s_nop 1
	v_addc_co_u32_e32 v167, vcc, 0, v167, vcc
	v_pk_mul_f32 v[92:93], v[92:93], v[234:235] op_sel_hi:[1,0]
	v_pk_mul_f32 v[94:95], v[94:95], v[234:235] op_sel_hi:[1,0]
	v_mul_f32_e32 v92, 0xbfb8aa3b, v92
	v_mul_f32_e32 v93, 0xbfb8aa3b, v93
	v_mul_f32_e32 v94, 0xbfb8aa3b, v94
	v_mul_f32_e32 v95, 0xbfb8aa3b, v95
	v_exp_f32_e32 v92, v92
	v_exp_f32_e32 v93, v93
	v_exp_f32_e32 v94, v94
	v_exp_f32_e32 v95, v95
	v_pk_add_f32 v[92:93], v[92:93], 1.0 op_sel_hi:[1,0]
	v_pk_add_f32 v[94:95], v[94:95], 1.0 op_sel_hi:[1,0]
	v_div_scale_f32 v224, s[10:11], v92, v92, 1.0
	v_rcp_f32_e32 v225, v224
	s_nop 0
	v_fma_f32 v226, -v224, v225, 1.0
	v_fmac_f32_e32 v225, v226, v225
	v_div_scale_f32 v226, vcc, 1.0, v92, 1.0
	v_mul_f32_e32 v227, v226, v225
	v_fma_f32 v228, -v224, v227, v226
	v_fmac_f32_e32 v227, v228, v225
	v_fma_f32 v224, -v224, v227, v226
	v_div_fmas_f32 v224, v224, v225, v227
	v_div_fixup_f32 v92, v224, v92, 1.0
	v_div_scale_f32 v224, s[10:11], v93, v93, 1.0
	v_rcp_f32_e32 v225, v224
	s_nop 0
	v_fma_f32 v226, -v224, v225, 1.0
	v_fmac_f32_e32 v225, v226, v225
	v_div_scale_f32 v226, vcc, 1.0, v93, 1.0
	v_mul_f32_e32 v227, v226, v225
	v_fma_f32 v228, -v224, v227, v226
	v_fmac_f32_e32 v227, v228, v225
	v_fma_f32 v224, -v224, v227, v226
	v_div_fmas_f32 v224, v224, v225, v227
	v_div_fixup_f32 v93, v224, v93, 1.0
	v_div_scale_f32 v224, s[10:11], v94, v94, 1.0
	v_rcp_f32_e32 v225, v224
	s_nop 0
	v_fma_f32 v226, -v224, v225, 1.0
	v_fmac_f32_e32 v225, v226, v225
	v_div_scale_f32 v226, vcc, 1.0, v94, 1.0
	v_mul_f32_e32 v227, v226, v225
	v_fma_f32 v228, -v224, v227, v226
	v_fmac_f32_e32 v227, v228, v225
	v_fma_f32 v224, -v224, v227, v226
	v_div_fmas_f32 v224, v224, v225, v227
	v_div_fixup_f32 v94, v224, v94, 1.0
	v_div_scale_f32 v224, s[10:11], v95, v95, 1.0
	v_rcp_f32_e32 v225, v224
	s_nop 0
	v_fma_f32 v226, -v224, v225, 1.0
	v_fmac_f32_e32 v225, v226, v225
	v_div_scale_f32 v226, vcc, 1.0, v95, 1.0
	v_mul_f32_e32 v227, v226, v225
	v_fma_f32 v228, -v224, v227, v226
	v_fmac_f32_e32 v227, v228, v225
	v_fma_f32 v224, -v224, v227, v226
	v_div_fmas_f32 v224, v224, v225, v227
	v_div_fixup_f32 v95, v224, v95, 1.0
	v_lshlrev_b32_e32 v236, 16, v184
	v_and_b32_e32 v237, 0xffff0000, v184
	v_lshlrev_b32_e32 v238, 16, v185
	v_and_b32_e32 v239, 0xffff0000, v185
	v_pk_fma_f32 v[92:93], v[92:93], v[236:237], v[168:169]
	v_pk_fma_f32 v[94:95], v[94:95], v[238:239], v[170:171]
	v_cvt_pk_bf16_f32 v157, v94, v95
	v_cvt_pk_bf16_f32 v156, v92, v93
	global_store_dwordx4 v[150:151], v[92:95], off
	s_nop 1
	v_mul_f32_e32 v93, v93, v93
	v_mul_f32_e32 v95, v95, v95
	v_fmac_f32_e32 v93, v92, v92
	v_fmac_f32_e32 v95, v94, v94
	v_add_f32_e32 v229, v93, v95
	v_pk_mul_f32 v[88:89], v[88:89], v[234:235] op_sel_hi:[1,0]
	v_pk_mul_f32 v[90:91], v[90:91], v[234:235] op_sel_hi:[1,0]
	v_mul_f32_e32 v88, 0xbfb8aa3b, v88
	v_mul_f32_e32 v89, 0xbfb8aa3b, v89
	v_mul_f32_e32 v90, 0xbfb8aa3b, v90
	v_mul_f32_e32 v91, 0xbfb8aa3b, v91
	v_exp_f32_e32 v88, v88
	v_exp_f32_e32 v89, v89
	v_exp_f32_e32 v90, v90
	v_exp_f32_e32 v91, v91
	v_pk_add_f32 v[88:89], v[88:89], 1.0 op_sel_hi:[1,0]
	v_pk_add_f32 v[90:91], v[90:91], 1.0 op_sel_hi:[1,0]
	v_div_scale_f32 v224, s[10:11], v88, v88, 1.0
	v_rcp_f32_e32 v225, v224
	s_nop 0
	v_fma_f32 v226, -v224, v225, 1.0
	v_fmac_f32_e32 v225, v226, v225
	v_div_scale_f32 v226, vcc, 1.0, v88, 1.0
	v_mul_f32_e32 v227, v226, v225
	v_fma_f32 v228, -v224, v227, v226
	v_fmac_f32_e32 v227, v228, v225
	v_fma_f32 v224, -v224, v227, v226
	v_div_fmas_f32 v224, v224, v225, v227
	v_div_fixup_f32 v88, v224, v88, 1.0
	v_div_scale_f32 v224, s[10:11], v89, v89, 1.0
	v_rcp_f32_e32 v225, v224
	s_nop 0
	v_fma_f32 v226, -v224, v225, 1.0
	v_fmac_f32_e32 v225, v226, v225
	v_div_scale_f32 v226, vcc, 1.0, v89, 1.0
	v_mul_f32_e32 v227, v226, v225
	v_fma_f32 v228, -v224, v227, v226
	v_fmac_f32_e32 v227, v228, v225
	v_fma_f32 v224, -v224, v227, v226
	v_div_fmas_f32 v224, v224, v225, v227
	v_div_fixup_f32 v89, v224, v89, 1.0
	v_div_scale_f32 v224, s[10:11], v90, v90, 1.0
	v_rcp_f32_e32 v225, v224
	s_nop 0
	v_fma_f32 v226, -v224, v225, 1.0
	v_fmac_f32_e32 v225, v226, v225
	v_div_scale_f32 v226, vcc, 1.0, v90, 1.0
	v_mul_f32_e32 v227, v226, v225
	v_fma_f32 v228, -v224, v227, v226
	v_fmac_f32_e32 v227, v228, v225
	v_fma_f32 v224, -v224, v227, v226
	v_div_fmas_f32 v224, v224, v225, v227
	v_div_fixup_f32 v90, v224, v90, 1.0
	v_div_scale_f32 v224, s[10:11], v91, v91, 1.0
	v_rcp_f32_e32 v225, v224
	s_nop 0
	v_fma_f32 v226, -v224, v225, 1.0
	v_fmac_f32_e32 v225, v226, v225
	v_div_scale_f32 v226, vcc, 1.0, v91, 1.0
	v_mul_f32_e32 v227, v226, v225
	v_fma_f32 v228, -v224, v227, v226
	v_fmac_f32_e32 v227, v228, v225
	v_fma_f32 v224, -v224, v227, v226
	v_div_fmas_f32 v224, v224, v225, v227
	v_div_fixup_f32 v91, v224, v91, 1.0
	v_lshlrev_b32_e32 v236, 16, v186
	v_and_b32_e32 v237, 0xffff0000, v186
	v_lshlrev_b32_e32 v238, 16, v187
	v_and_b32_e32 v239, 0xffff0000, v187
	v_pk_fma_f32 v[88:89], v[88:89], v[236:237], v[172:173]
	v_pk_fma_f32 v[90:91], v[90:91], v[238:239], v[174:175]
	v_cvt_pk_bf16_f32 v159, v90, v91
	v_cvt_pk_bf16_f32 v158, v88, v89
	global_store_dwordx4 v[150:151], v[88:91], off offset:64
	s_nop 1
	v_mul_f32_e32 v89, v89, v89
	v_mul_f32_e32 v91, v91, v91
	v_fmac_f32_e32 v89, v88, v88
	v_fmac_f32_e32 v91, v90, v90
	v_add_f32_e32 v88, v89, v91
	v_add_f32_e32 v229, v229, v88
	v_permlane16_swap_b32_e32 v156, v158
	v_permlane16_swap_b32_e32 v157, v159
	global_store_dwordx4 v[166:167], v[156:159], off
	s_nop 0
	v_pk_mul_f32 v[84:85], v[84:85], v[234:235] op_sel_hi:[1,0]
	v_pk_mul_f32 v[86:87], v[86:87], v[234:235] op_sel_hi:[1,0]
	v_mul_f32_e32 v84, 0xbfb8aa3b, v84
	v_mul_f32_e32 v85, 0xbfb8aa3b, v85
	v_mul_f32_e32 v86, 0xbfb8aa3b, v86
	v_mul_f32_e32 v87, 0xbfb8aa3b, v87
	v_exp_f32_e32 v84, v84
	v_exp_f32_e32 v85, v85
	v_exp_f32_e32 v86, v86
	v_exp_f32_e32 v87, v87
	v_pk_add_f32 v[84:85], v[84:85], 1.0 op_sel_hi:[1,0]
	v_pk_add_f32 v[86:87], v[86:87], 1.0 op_sel_hi:[1,0]
	v_div_scale_f32 v224, s[10:11], v84, v84, 1.0
	v_rcp_f32_e32 v225, v224
	s_nop 0
	v_fma_f32 v226, -v224, v225, 1.0
	v_fmac_f32_e32 v225, v226, v225
	v_div_scale_f32 v226, vcc, 1.0, v84, 1.0
	v_mul_f32_e32 v227, v226, v225
	v_fma_f32 v228, -v224, v227, v226
	v_fmac_f32_e32 v227, v228, v225
	v_fma_f32 v224, -v224, v227, v226
	v_div_fmas_f32 v224, v224, v225, v227
	v_div_fixup_f32 v84, v224, v84, 1.0
	v_div_scale_f32 v224, s[10:11], v85, v85, 1.0
	v_rcp_f32_e32 v225, v224
	s_nop 0
	v_fma_f32 v226, -v224, v225, 1.0
	v_fmac_f32_e32 v225, v226, v225
	v_div_scale_f32 v226, vcc, 1.0, v85, 1.0
	v_mul_f32_e32 v227, v226, v225
	v_fma_f32 v228, -v224, v227, v226
	v_fmac_f32_e32 v227, v228, v225
	v_fma_f32 v224, -v224, v227, v226
	v_div_fmas_f32 v224, v224, v225, v227
	v_div_fixup_f32 v85, v224, v85, 1.0
	v_div_scale_f32 v224, s[10:11], v86, v86, 1.0
	v_rcp_f32_e32 v225, v224
	s_nop 0
	v_fma_f32 v226, -v224, v225, 1.0
	v_fmac_f32_e32 v225, v226, v225
	v_div_scale_f32 v226, vcc, 1.0, v86, 1.0
	v_mul_f32_e32 v227, v226, v225
	v_fma_f32 v228, -v224, v227, v226
	v_fmac_f32_e32 v227, v228, v225
	v_fma_f32 v224, -v224, v227, v226
	v_div_fmas_f32 v224, v224, v225, v227
	v_div_fixup_f32 v86, v224, v86, 1.0
	v_div_scale_f32 v224, s[10:11], v87, v87, 1.0
	v_rcp_f32_e32 v225, v224
	s_nop 0
	v_fma_f32 v226, -v224, v225, 1.0
	v_fmac_f32_e32 v225, v226, v225
	v_div_scale_f32 v226, vcc, 1.0, v87, 1.0
	v_mul_f32_e32 v227, v226, v225
	v_fma_f32 v228, -v224, v227, v226
	v_fmac_f32_e32 v227, v228, v225
	v_fma_f32 v224, -v224, v227, v226
	v_div_fmas_f32 v224, v224, v225, v227
	v_div_fixup_f32 v87, v224, v87, 1.0
	v_lshlrev_b32_e32 v236, 16, v188
	v_and_b32_e32 v237, 0xffff0000, v188
	v_lshlrev_b32_e32 v238, 16, v189
	v_and_b32_e32 v239, 0xffff0000, v189
	v_pk_fma_f32 v[84:85], v[84:85], v[236:237], v[176:177]
	v_pk_fma_f32 v[86:87], v[86:87], v[238:239], v[178:179]
	v_cvt_pk_bf16_f32 v157, v86, v87
	v_cvt_pk_bf16_f32 v156, v84, v85
	global_store_dwordx4 v[150:151], v[84:87], off offset:512
	s_nop 1
	v_mul_f32_e32 v85, v85, v85
	v_mul_f32_e32 v87, v87, v87
	v_fmac_f32_e32 v85, v84, v84
	v_fmac_f32_e32 v87, v86, v86
	v_add_f32_e32 v84, v85, v87
	v_add_f32_e32 v229, v229, v84
	v_pk_mul_f32 v[80:81], v[80:81], v[234:235] op_sel_hi:[1,0]
	v_pk_mul_f32 v[82:83], v[82:83], v[234:235] op_sel_hi:[1,0]
	v_mul_f32_e32 v80, 0xbfb8aa3b, v80
	v_mul_f32_e32 v81, 0xbfb8aa3b, v81
	v_mul_f32_e32 v82, 0xbfb8aa3b, v82
	v_mul_f32_e32 v83, 0xbfb8aa3b, v83
	v_exp_f32_e32 v80, v80
	v_exp_f32_e32 v81, v81
	v_exp_f32_e32 v82, v82
	v_exp_f32_e32 v83, v83
	v_pk_add_f32 v[80:81], v[80:81], 1.0 op_sel_hi:[1,0]
	v_pk_add_f32 v[82:83], v[82:83], 1.0 op_sel_hi:[1,0]
	v_div_scale_f32 v224, s[10:11], v80, v80, 1.0
	v_rcp_f32_e32 v225, v224
	s_nop 0
	v_fma_f32 v226, -v224, v225, 1.0
	v_fmac_f32_e32 v225, v226, v225
	v_div_scale_f32 v226, vcc, 1.0, v80, 1.0
	v_mul_f32_e32 v227, v226, v225
	v_fma_f32 v228, -v224, v227, v226
	v_fmac_f32_e32 v227, v228, v225
	v_fma_f32 v224, -v224, v227, v226
	v_div_fmas_f32 v224, v224, v225, v227
	v_div_fixup_f32 v80, v224, v80, 1.0
	v_div_scale_f32 v224, s[10:11], v81, v81, 1.0
	v_rcp_f32_e32 v225, v224
	s_nop 0
	v_fma_f32 v226, -v224, v225, 1.0
	v_fmac_f32_e32 v225, v226, v225
	v_div_scale_f32 v226, vcc, 1.0, v81, 1.0
	v_mul_f32_e32 v227, v226, v225
	v_fma_f32 v228, -v224, v227, v226
	v_fmac_f32_e32 v227, v228, v225
	v_fma_f32 v224, -v224, v227, v226
	v_div_fmas_f32 v224, v224, v225, v227
	v_div_fixup_f32 v81, v224, v81, 1.0
	v_div_scale_f32 v224, s[10:11], v82, v82, 1.0
	v_rcp_f32_e32 v225, v224
	s_nop 0
	v_fma_f32 v226, -v224, v225, 1.0
	v_fmac_f32_e32 v225, v226, v225
	v_div_scale_f32 v226, vcc, 1.0, v82, 1.0
	v_mul_f32_e32 v227, v226, v225
	v_fma_f32 v228, -v224, v227, v226
	v_fmac_f32_e32 v227, v228, v225
	v_fma_f32 v224, -v224, v227, v226
	v_div_fmas_f32 v224, v224, v225, v227
	v_div_fixup_f32 v82, v224, v82, 1.0
	v_div_scale_f32 v224, s[10:11], v83, v83, 1.0
	v_rcp_f32_e32 v225, v224
	s_nop 0
	v_fma_f32 v226, -v224, v225, 1.0
	v_fmac_f32_e32 v225, v226, v225
	v_div_scale_f32 v226, vcc, 1.0, v83, 1.0
	v_mul_f32_e32 v227, v226, v225
	v_fma_f32 v228, -v224, v227, v226
	v_fmac_f32_e32 v227, v228, v225
	v_fma_f32 v224, -v224, v227, v226
	v_div_fmas_f32 v224, v224, v225, v227
	v_div_fixup_f32 v83, v224, v83, 1.0
	v_lshlrev_b32_e32 v236, 16, v190
	v_and_b32_e32 v237, 0xffff0000, v190
	v_lshlrev_b32_e32 v238, 16, v191
	v_and_b32_e32 v239, 0xffff0000, v191
	v_pk_fma_f32 v[80:81], v[80:81], v[236:237], v[180:181]
	v_pk_fma_f32 v[82:83], v[82:83], v[238:239], v[182:183]
	v_cvt_pk_bf16_f32 v159, v82, v83
	v_cvt_pk_bf16_f32 v158, v80, v81
	global_store_dwordx4 v[150:151], v[80:83], off offset:576
	s_nop 1
	v_mul_f32_e32 v81, v81, v81
	v_mul_f32_e32 v83, v83, v83
	v_fmac_f32_e32 v81, v80, v80
	v_fmac_f32_e32 v83, v82, v82
	v_add_f32_e32 v80, v81, v83
	v_add_f32_e32 v229, v229, v80
	v_permlane16_swap_b32_e32 v156, v158
	v_permlane16_swap_b32_e32 v157, v159
	global_store_dwordx4 v[166:167], v[156:159], off offset:256
	s_nop 0
	v_mov_b32_e32 v230, v229
	s_nop 1
	v_permlane16_swap_b32_e32 v229, v230
	v_add_f32_e32 v229, v229, v230
	v_mov_b32_e32 v230, v229
	s_nop 1
	v_permlane32_swap_b32_e32 v229, v230
	s_and_saveexec_b64 s[10:11], s[6:7]
	v_lshl_add_u64 v[156:157], v[144:145], 2, s[18:19]
	v_add_f32_e32 v229, v229, v230
	global_atomic_add_f32 v[156:157], v229, off
	s_or_b64 exec, exec, s[10:11]
	v_add_u32_e32 v144, 0x80, v154
	v_mov_b32_e32 v145, v155
	v_lshlrev_b64 v[148:149], 11, v[144:145]
	v_lshl_add_u64 v[148:149], v[148:149], 0, v[146:147]
	v_lshl_add_u64 v[150:151], v[148:149], 2, s[28:29]
	v_lshl_add_u64 v[152:153], v[148:149], 1, s[42:43]
	global_load_dwordx2 v[184:185], v[152:153], off
	global_load_dwordx4 v[168:171], v[150:151], off
	global_load_dwordx2 v[186:187], v[152:153], off offset:32
	global_load_dwordx4 v[172:175], v[150:151], off offset:64
	global_load_dwordx2 v[188:189], v[152:153], off offset:256
	global_load_dwordx4 v[176:179], v[150:151], off offset:512
	global_load_dwordx2 v[190:191], v[152:153], off offset:288
	global_load_dwordx4 v[180:183], v[150:151], off offset:576
	s_waitcnt vmcnt(15)
	v_fmamk_f32 v219, v219, 0x3a000000, v164
	v_mul_f32_e32 v235, 0x4b800000, v219
	v_cmp_gt_f32_e32 vcc, s61, v219
	s_nop 1
	v_cndmask_b32_e32 v219, v219, v235, vcc
	v_rsq_f32_e32 v219, v219
	s_nop 0
	v_mul_f32_e32 v235, 0x45800000, v219
	v_cndmask_b32_e32 v234, v219, v235, vcc
	v_add_u32_e32 v144, 0x30, v154
	v_mov_b32_e32 v145, v155
	v_lshlrev_b64 v[148:149], 11, v[144:145]
	v_lshl_add_u64 v[148:149], v[148:149], 0, v[146:147]
	v_lshl_add_u64 v[150:151], v[148:149], 2, s[28:29]
	v_lshl_add_u64 v[166:167], v[148:149], 1, s[24:25]
	v_add_co_u32_e32 v166, vcc, v166, v231
	s_nop 1
	v_addc_co_u32_e32 v167, vcc, 0, v167, vcc
	v_pk_mul_f32 v[76:77], v[76:77], v[234:235] op_sel_hi:[1,0]
	v_pk_mul_f32 v[78:79], v[78:79], v[234:235] op_sel_hi:[1,0]
	v_mul_f32_e32 v76, 0xbfb8aa3b, v76
	v_mul_f32_e32 v77, 0xbfb8aa3b, v77
	v_mul_f32_e32 v78, 0xbfb8aa3b, v78
	v_mul_f32_e32 v79, 0xbfb8aa3b, v79
	v_exp_f32_e32 v76, v76
	v_exp_f32_e32 v77, v77
	v_exp_f32_e32 v78, v78
	v_exp_f32_e32 v79, v79
	v_pk_add_f32 v[76:77], v[76:77], 1.0 op_sel_hi:[1,0]
	v_pk_add_f32 v[78:79], v[78:79], 1.0 op_sel_hi:[1,0]
	v_div_scale_f32 v224, s[10:11], v76, v76, 1.0
	v_rcp_f32_e32 v225, v224
	s_nop 0
	v_fma_f32 v226, -v224, v225, 1.0
	v_fmac_f32_e32 v225, v226, v225
	v_div_scale_f32 v226, vcc, 1.0, v76, 1.0
	v_mul_f32_e32 v227, v226, v225
	v_fma_f32 v228, -v224, v227, v226
	v_fmac_f32_e32 v227, v228, v225
	v_fma_f32 v224, -v224, v227, v226
	v_div_fmas_f32 v224, v224, v225, v227
	v_div_fixup_f32 v76, v224, v76, 1.0
	v_div_scale_f32 v224, s[10:11], v77, v77, 1.0
	v_rcp_f32_e32 v225, v224
	s_nop 0
	v_fma_f32 v226, -v224, v225, 1.0
	v_fmac_f32_e32 v225, v226, v225
	v_div_scale_f32 v226, vcc, 1.0, v77, 1.0
	v_mul_f32_e32 v227, v226, v225
	v_fma_f32 v228, -v224, v227, v226
	v_fmac_f32_e32 v227, v228, v225
	v_fma_f32 v224, -v224, v227, v226
	v_div_fmas_f32 v224, v224, v225, v227
	v_div_fixup_f32 v77, v224, v77, 1.0
	v_div_scale_f32 v224, s[10:11], v78, v78, 1.0
	v_rcp_f32_e32 v225, v224
	s_nop 0
	v_fma_f32 v226, -v224, v225, 1.0
	v_fmac_f32_e32 v225, v226, v225
	v_div_scale_f32 v226, vcc, 1.0, v78, 1.0
	v_mul_f32_e32 v227, v226, v225
	v_fma_f32 v228, -v224, v227, v226
	v_fmac_f32_e32 v227, v228, v225
	v_fma_f32 v224, -v224, v227, v226
	v_div_fmas_f32 v224, v224, v225, v227
	v_div_fixup_f32 v78, v224, v78, 1.0
	v_div_scale_f32 v224, s[10:11], v79, v79, 1.0
	v_rcp_f32_e32 v225, v224
	s_nop 0
	v_fma_f32 v226, -v224, v225, 1.0
	v_fmac_f32_e32 v225, v226, v225
	v_div_scale_f32 v226, vcc, 1.0, v79, 1.0
	v_mul_f32_e32 v227, v226, v225
	v_fma_f32 v228, -v224, v227, v226
	v_fmac_f32_e32 v227, v228, v225
	v_fma_f32 v224, -v224, v227, v226
	v_div_fmas_f32 v224, v224, v225, v227
	v_div_fixup_f32 v79, v224, v79, 1.0
	v_lshlrev_b32_e32 v236, 16, v208
	v_and_b32_e32 v237, 0xffff0000, v208
	v_lshlrev_b32_e32 v238, 16, v209
	v_and_b32_e32 v239, 0xffff0000, v209
	v_pk_fma_f32 v[76:77], v[76:77], v[236:237], v[192:193]
	v_pk_fma_f32 v[78:79], v[78:79], v[238:239], v[194:195]
	v_cvt_pk_bf16_f32 v157, v78, v79
	v_cvt_pk_bf16_f32 v156, v76, v77
	global_store_dwordx4 v[150:151], v[76:79], off
	s_nop 1
	v_mul_f32_e32 v77, v77, v77
	v_mul_f32_e32 v79, v79, v79
	v_fmac_f32_e32 v77, v76, v76
	v_fmac_f32_e32 v79, v78, v78
	v_add_f32_e32 v229, v77, v79
	v_pk_mul_f32 v[72:73], v[72:73], v[234:235] op_sel_hi:[1,0]
	v_pk_mul_f32 v[74:75], v[74:75], v[234:235] op_sel_hi:[1,0]
	v_mul_f32_e32 v72, 0xbfb8aa3b, v72
	v_mul_f32_e32 v73, 0xbfb8aa3b, v73
	v_mul_f32_e32 v74, 0xbfb8aa3b, v74
	v_mul_f32_e32 v75, 0xbfb8aa3b, v75
	v_exp_f32_e32 v72, v72
	v_exp_f32_e32 v73, v73
	v_exp_f32_e32 v74, v74
	v_exp_f32_e32 v75, v75
	v_pk_add_f32 v[72:73], v[72:73], 1.0 op_sel_hi:[1,0]
	v_pk_add_f32 v[74:75], v[74:75], 1.0 op_sel_hi:[1,0]
	v_div_scale_f32 v224, s[10:11], v72, v72, 1.0
	v_rcp_f32_e32 v225, v224
	s_nop 0
	v_fma_f32 v226, -v224, v225, 1.0
	v_fmac_f32_e32 v225, v226, v225
	v_div_scale_f32 v226, vcc, 1.0, v72, 1.0
	v_mul_f32_e32 v227, v226, v225
	v_fma_f32 v228, -v224, v227, v226
	v_fmac_f32_e32 v227, v228, v225
	v_fma_f32 v224, -v224, v227, v226
	v_div_fmas_f32 v224, v224, v225, v227
	v_div_fixup_f32 v72, v224, v72, 1.0
	v_div_scale_f32 v224, s[10:11], v73, v73, 1.0
	v_rcp_f32_e32 v225, v224
	s_nop 0
	v_fma_f32 v226, -v224, v225, 1.0
	v_fmac_f32_e32 v225, v226, v225
	v_div_scale_f32 v226, vcc, 1.0, v73, 1.0
	v_mul_f32_e32 v227, v226, v225
	v_fma_f32 v228, -v224, v227, v226
	v_fmac_f32_e32 v227, v228, v225
	v_fma_f32 v224, -v224, v227, v226
	v_div_fmas_f32 v224, v224, v225, v227
	v_div_fixup_f32 v73, v224, v73, 1.0
	v_div_scale_f32 v224, s[10:11], v74, v74, 1.0
	v_rcp_f32_e32 v225, v224
	s_nop 0
	v_fma_f32 v226, -v224, v225, 1.0
	v_fmac_f32_e32 v225, v226, v225
	v_div_scale_f32 v226, vcc, 1.0, v74, 1.0
	v_mul_f32_e32 v227, v226, v225
	v_fma_f32 v228, -v224, v227, v226
	v_fmac_f32_e32 v227, v228, v225
	v_fma_f32 v224, -v224, v227, v226
	v_div_fmas_f32 v224, v224, v225, v227
	v_div_fixup_f32 v74, v224, v74, 1.0
	v_div_scale_f32 v224, s[10:11], v75, v75, 1.0
	v_rcp_f32_e32 v225, v224
	s_nop 0
	v_fma_f32 v226, -v224, v225, 1.0
	v_fmac_f32_e32 v225, v226, v225
	v_div_scale_f32 v226, vcc, 1.0, v75, 1.0
	v_mul_f32_e32 v227, v226, v225
	v_fma_f32 v228, -v224, v227, v226
	v_fmac_f32_e32 v227, v228, v225
	v_fma_f32 v224, -v224, v227, v226
	v_div_fmas_f32 v224, v224, v225, v227
	v_div_fixup_f32 v75, v224, v75, 1.0
	v_lshlrev_b32_e32 v236, 16, v210
	v_and_b32_e32 v237, 0xffff0000, v210
	v_lshlrev_b32_e32 v238, 16, v211
	v_and_b32_e32 v239, 0xffff0000, v211
	v_pk_fma_f32 v[72:73], v[72:73], v[236:237], v[196:197]
	v_pk_fma_f32 v[74:75], v[74:75], v[238:239], v[198:199]
	v_cvt_pk_bf16_f32 v159, v74, v75
	v_cvt_pk_bf16_f32 v158, v72, v73
	global_store_dwordx4 v[150:151], v[72:75], off offset:64
	s_nop 1
	v_mul_f32_e32 v73, v73, v73
	v_mul_f32_e32 v75, v75, v75
	v_fmac_f32_e32 v73, v72, v72
	v_fmac_f32_e32 v75, v74, v74
	v_add_f32_e32 v72, v73, v75
	v_add_f32_e32 v229, v229, v72
	v_permlane16_swap_b32_e32 v156, v158
	v_permlane16_swap_b32_e32 v157, v159
	global_store_dwordx4 v[166:167], v[156:159], off
	s_nop 0
	v_pk_mul_f32 v[68:69], v[68:69], v[234:235] op_sel_hi:[1,0]
	v_pk_mul_f32 v[70:71], v[70:71], v[234:235] op_sel_hi:[1,0]
	v_mul_f32_e32 v68, 0xbfb8aa3b, v68
	v_mul_f32_e32 v69, 0xbfb8aa3b, v69
	v_mul_f32_e32 v70, 0xbfb8aa3b, v70
	v_mul_f32_e32 v71, 0xbfb8aa3b, v71
	v_exp_f32_e32 v68, v68
	v_exp_f32_e32 v69, v69
	v_exp_f32_e32 v70, v70
	v_exp_f32_e32 v71, v71
	v_pk_add_f32 v[68:69], v[68:69], 1.0 op_sel_hi:[1,0]
	v_pk_add_f32 v[70:71], v[70:71], 1.0 op_sel_hi:[1,0]
	v_div_scale_f32 v224, s[10:11], v68, v68, 1.0
	v_rcp_f32_e32 v225, v224
	s_nop 0
	v_fma_f32 v226, -v224, v225, 1.0
	v_fmac_f32_e32 v225, v226, v225
	v_div_scale_f32 v226, vcc, 1.0, v68, 1.0
	v_mul_f32_e32 v227, v226, v225
	v_fma_f32 v228, -v224, v227, v226
	v_fmac_f32_e32 v227, v228, v225
	v_fma_f32 v224, -v224, v227, v226
	v_div_fmas_f32 v224, v224, v225, v227
	v_div_fixup_f32 v68, v224, v68, 1.0
	v_div_scale_f32 v224, s[10:11], v69, v69, 1.0
	v_rcp_f32_e32 v225, v224
	s_nop 0
	v_fma_f32 v226, -v224, v225, 1.0
	v_fmac_f32_e32 v225, v226, v225
	v_div_scale_f32 v226, vcc, 1.0, v69, 1.0
	v_mul_f32_e32 v227, v226, v225
	v_fma_f32 v228, -v224, v227, v226
	v_fmac_f32_e32 v227, v228, v225
	v_fma_f32 v224, -v224, v227, v226
	v_div_fmas_f32 v224, v224, v225, v227
	v_div_fixup_f32 v69, v224, v69, 1.0
	v_div_scale_f32 v224, s[10:11], v70, v70, 1.0
	v_rcp_f32_e32 v225, v224
	s_nop 0
	v_fma_f32 v226, -v224, v225, 1.0
	v_fmac_f32_e32 v225, v226, v225
	v_div_scale_f32 v226, vcc, 1.0, v70, 1.0
	v_mul_f32_e32 v227, v226, v225
	v_fma_f32 v228, -v224, v227, v226
	v_fmac_f32_e32 v227, v228, v225
	v_fma_f32 v224, -v224, v227, v226
	v_div_fmas_f32 v224, v224, v225, v227
	v_div_fixup_f32 v70, v224, v70, 1.0
	v_div_scale_f32 v224, s[10:11], v71, v71, 1.0
	v_rcp_f32_e32 v225, v224
	s_nop 0
	v_fma_f32 v226, -v224, v225, 1.0
	v_fmac_f32_e32 v225, v226, v225
	v_div_scale_f32 v226, vcc, 1.0, v71, 1.0
	v_mul_f32_e32 v227, v226, v225
	v_fma_f32 v228, -v224, v227, v226
	v_fmac_f32_e32 v227, v228, v225
	v_fma_f32 v224, -v224, v227, v226
	v_div_fmas_f32 v224, v224, v225, v227
	v_div_fixup_f32 v71, v224, v71, 1.0
	v_lshlrev_b32_e32 v236, 16, v212
	v_and_b32_e32 v237, 0xffff0000, v212
	v_lshlrev_b32_e32 v238, 16, v213
	v_and_b32_e32 v239, 0xffff0000, v213
	v_pk_fma_f32 v[68:69], v[68:69], v[236:237], v[200:201]
	v_pk_fma_f32 v[70:71], v[70:71], v[238:239], v[202:203]
	v_cvt_pk_bf16_f32 v157, v70, v71
	v_cvt_pk_bf16_f32 v156, v68, v69
	global_store_dwordx4 v[150:151], v[68:71], off offset:512
	s_nop 1
	v_mul_f32_e32 v69, v69, v69
	v_mul_f32_e32 v71, v71, v71
	v_fmac_f32_e32 v69, v68, v68
	v_fmac_f32_e32 v71, v70, v70
	v_add_f32_e32 v68, v69, v71
	v_add_f32_e32 v229, v229, v68
	v_pk_mul_f32 v[64:65], v[64:65], v[234:235] op_sel_hi:[1,0]
	v_pk_mul_f32 v[66:67], v[66:67], v[234:235] op_sel_hi:[1,0]
	v_mul_f32_e32 v64, 0xbfb8aa3b, v64
	v_mul_f32_e32 v65, 0xbfb8aa3b, v65
	v_mul_f32_e32 v66, 0xbfb8aa3b, v66
	v_mul_f32_e32 v67, 0xbfb8aa3b, v67
	v_exp_f32_e32 v64, v64
	v_exp_f32_e32 v65, v65
	v_exp_f32_e32 v66, v66
	v_exp_f32_e32 v67, v67
	v_pk_add_f32 v[64:65], v[64:65], 1.0 op_sel_hi:[1,0]
	v_pk_add_f32 v[66:67], v[66:67], 1.0 op_sel_hi:[1,0]
	v_div_scale_f32 v224, s[10:11], v64, v64, 1.0
	v_rcp_f32_e32 v225, v224
	s_nop 0
	v_fma_f32 v226, -v224, v225, 1.0
	v_fmac_f32_e32 v225, v226, v225
	v_div_scale_f32 v226, vcc, 1.0, v64, 1.0
	v_mul_f32_e32 v227, v226, v225
	v_fma_f32 v228, -v224, v227, v226
	v_fmac_f32_e32 v227, v228, v225
	v_fma_f32 v224, -v224, v227, v226
	v_div_fmas_f32 v224, v224, v225, v227
	v_div_fixup_f32 v64, v224, v64, 1.0
	v_div_scale_f32 v224, s[10:11], v65, v65, 1.0
	v_rcp_f32_e32 v225, v224
	s_nop 0
	v_fma_f32 v226, -v224, v225, 1.0
	v_fmac_f32_e32 v225, v226, v225
	v_div_scale_f32 v226, vcc, 1.0, v65, 1.0
	v_mul_f32_e32 v227, v226, v225
	v_fma_f32 v228, -v224, v227, v226
	v_fmac_f32_e32 v227, v228, v225
	v_fma_f32 v224, -v224, v227, v226
	v_div_fmas_f32 v224, v224, v225, v227
	v_div_fixup_f32 v65, v224, v65, 1.0
	v_div_scale_f32 v224, s[10:11], v66, v66, 1.0
	v_rcp_f32_e32 v225, v224
	s_nop 0
	v_fma_f32 v226, -v224, v225, 1.0
	v_fmac_f32_e32 v225, v226, v225
	v_div_scale_f32 v226, vcc, 1.0, v66, 1.0
	v_mul_f32_e32 v227, v226, v225
	v_fma_f32 v228, -v224, v227, v226
	v_fmac_f32_e32 v227, v228, v225
	v_fma_f32 v224, -v224, v227, v226
	v_div_fmas_f32 v224, v224, v225, v227
	v_div_fixup_f32 v66, v224, v66, 1.0
	v_div_scale_f32 v224, s[10:11], v67, v67, 1.0
	v_rcp_f32_e32 v225, v224
	s_nop 0
	v_fma_f32 v226, -v224, v225, 1.0
	v_fmac_f32_e32 v225, v226, v225
	v_div_scale_f32 v226, vcc, 1.0, v67, 1.0
	v_mul_f32_e32 v227, v226, v225
	v_fma_f32 v228, -v224, v227, v226
	v_fmac_f32_e32 v227, v228, v225
	v_fma_f32 v224, -v224, v227, v226
	v_div_fmas_f32 v224, v224, v225, v227
	v_div_fixup_f32 v67, v224, v67, 1.0
	v_lshlrev_b32_e32 v236, 16, v214
	v_and_b32_e32 v237, 0xffff0000, v214
	v_lshlrev_b32_e32 v238, 16, v215
	v_and_b32_e32 v239, 0xffff0000, v215
	v_pk_fma_f32 v[64:65], v[64:65], v[236:237], v[204:205]
	v_pk_fma_f32 v[66:67], v[66:67], v[238:239], v[206:207]
	v_cvt_pk_bf16_f32 v159, v66, v67
	v_cvt_pk_bf16_f32 v158, v64, v65
	global_store_dwordx4 v[150:151], v[64:67], off offset:576
	s_nop 1
	v_mul_f32_e32 v65, v65, v65
	v_mul_f32_e32 v67, v67, v67
	v_fmac_f32_e32 v65, v64, v64
	v_fmac_f32_e32 v67, v66, v66
	v_add_f32_e32 v64, v65, v67
	v_add_f32_e32 v229, v229, v64
	v_permlane16_swap_b32_e32 v156, v158
	v_permlane16_swap_b32_e32 v157, v159
	global_store_dwordx4 v[166:167], v[156:159], off offset:256
	s_nop 0
	v_mov_b32_e32 v230, v229
	s_nop 1
	v_permlane16_swap_b32_e32 v229, v230
	v_add_f32_e32 v229, v229, v230
	v_mov_b32_e32 v230, v229
	s_nop 1
	v_permlane32_swap_b32_e32 v229, v230
	s_and_saveexec_b64 s[10:11], s[6:7]
	v_lshl_add_u64 v[156:157], v[144:145], 2, s[18:19]
	v_add_f32_e32 v229, v229, v230
	global_atomic_add_f32 v[156:157], v229, off
	s_or_b64 exec, exec, s[10:11]
	v_add_u32_e32 v144, 0x90, v154
	v_mov_b32_e32 v145, v155
	v_lshlrev_b64 v[148:149], 11, v[144:145]
	v_lshl_add_u64 v[148:149], v[148:149], 0, v[146:147]
	v_lshl_add_u64 v[150:151], v[148:149], 2, s[28:29]
	v_lshl_add_u64 v[152:153], v[148:149], 1, s[42:43]
	global_load_dwordx2 v[208:209], v[152:153], off
	global_load_dwordx4 v[192:195], v[150:151], off
	global_load_dwordx2 v[210:211], v[152:153], off offset:32
	global_load_dwordx4 v[196:199], v[150:151], off offset:64
	global_load_dwordx2 v[212:213], v[152:153], off offset:256
	global_load_dwordx4 v[200:203], v[150:151], off offset:512
	global_load_dwordx2 v[214:215], v[152:153], off offset:288
	global_load_dwordx4 v[204:207], v[150:151], off offset:576
	s_waitcnt vmcnt(15)
	v_fmamk_f32 v220, v220, 0x3a000000, v164
	v_mul_f32_e32 v235, 0x4b800000, v220
	v_cmp_gt_f32_e32 vcc, s61, v220
	s_nop 1
	v_cndmask_b32_e32 v220, v220, v235, vcc
	v_rsq_f32_e32 v220, v220
	s_nop 0
	v_mul_f32_e32 v235, 0x45800000, v220
	v_cndmask_b32_e32 v234, v220, v235, vcc
	v_add_u32_e32 v144, 0x80, v154
	v_mov_b32_e32 v145, v155
	v_lshlrev_b64 v[148:149], 11, v[144:145]
	v_lshl_add_u64 v[148:149], v[148:149], 0, v[146:147]
	v_lshl_add_u64 v[150:151], v[148:149], 2, s[28:29]
	v_lshl_add_u64 v[166:167], v[148:149], 1, s[24:25]
	v_add_co_u32_e32 v166, vcc, v166, v231
	s_nop 1
	v_addc_co_u32_e32 v167, vcc, 0, v167, vcc
	v_pk_mul_f32 v[60:61], v[60:61], v[234:235] op_sel_hi:[1,0]
	v_pk_mul_f32 v[62:63], v[62:63], v[234:235] op_sel_hi:[1,0]
	v_mul_f32_e32 v60, 0xbfb8aa3b, v60
	v_mul_f32_e32 v61, 0xbfb8aa3b, v61
	v_mul_f32_e32 v62, 0xbfb8aa3b, v62
	v_mul_f32_e32 v63, 0xbfb8aa3b, v63
	v_exp_f32_e32 v60, v60
	v_exp_f32_e32 v61, v61
	v_exp_f32_e32 v62, v62
	v_exp_f32_e32 v63, v63
	v_pk_add_f32 v[60:61], v[60:61], 1.0 op_sel_hi:[1,0]
	v_pk_add_f32 v[62:63], v[62:63], 1.0 op_sel_hi:[1,0]
	v_div_scale_f32 v224, s[10:11], v60, v60, 1.0
	v_rcp_f32_e32 v225, v224
	s_nop 0
	v_fma_f32 v226, -v224, v225, 1.0
	v_fmac_f32_e32 v225, v226, v225
	v_div_scale_f32 v226, vcc, 1.0, v60, 1.0
	v_mul_f32_e32 v227, v226, v225
	v_fma_f32 v228, -v224, v227, v226
	v_fmac_f32_e32 v227, v228, v225
	v_fma_f32 v224, -v224, v227, v226
	v_div_fmas_f32 v224, v224, v225, v227
	v_div_fixup_f32 v60, v224, v60, 1.0
	v_div_scale_f32 v224, s[10:11], v61, v61, 1.0
	v_rcp_f32_e32 v225, v224
	s_nop 0
	v_fma_f32 v226, -v224, v225, 1.0
	v_fmac_f32_e32 v225, v226, v225
	v_div_scale_f32 v226, vcc, 1.0, v61, 1.0
	v_mul_f32_e32 v227, v226, v225
	v_fma_f32 v228, -v224, v227, v226
	v_fmac_f32_e32 v227, v228, v225
	v_fma_f32 v224, -v224, v227, v226
	v_div_fmas_f32 v224, v224, v225, v227
	v_div_fixup_f32 v61, v224, v61, 1.0
	v_div_scale_f32 v224, s[10:11], v62, v62, 1.0
	v_rcp_f32_e32 v225, v224
	s_nop 0
	v_fma_f32 v226, -v224, v225, 1.0
	v_fmac_f32_e32 v225, v226, v225
	v_div_scale_f32 v226, vcc, 1.0, v62, 1.0
	v_mul_f32_e32 v227, v226, v225
	v_fma_f32 v228, -v224, v227, v226
	v_fmac_f32_e32 v227, v228, v225
	v_fma_f32 v224, -v224, v227, v226
	v_div_fmas_f32 v224, v224, v225, v227
	v_div_fixup_f32 v62, v224, v62, 1.0
	v_div_scale_f32 v224, s[10:11], v63, v63, 1.0
	v_rcp_f32_e32 v225, v224
	s_nop 0
	v_fma_f32 v226, -v224, v225, 1.0
	v_fmac_f32_e32 v225, v226, v225
	v_div_scale_f32 v226, vcc, 1.0, v63, 1.0
	v_mul_f32_e32 v227, v226, v225
	v_fma_f32 v228, -v224, v227, v226
	v_fmac_f32_e32 v227, v228, v225
	v_fma_f32 v224, -v224, v227, v226
	v_div_fmas_f32 v224, v224, v225, v227
	v_div_fixup_f32 v63, v224, v63, 1.0
	v_lshlrev_b32_e32 v236, 16, v184
	v_and_b32_e32 v237, 0xffff0000, v184
	v_lshlrev_b32_e32 v238, 16, v185
	v_and_b32_e32 v239, 0xffff0000, v185
	v_pk_fma_f32 v[60:61], v[60:61], v[236:237], v[168:169]
	v_pk_fma_f32 v[62:63], v[62:63], v[238:239], v[170:171]
	v_cvt_pk_bf16_f32 v157, v62, v63
	v_cvt_pk_bf16_f32 v156, v60, v61
	global_store_dwordx4 v[150:151], v[60:63], off
	s_nop 1
	v_mul_f32_e32 v61, v61, v61
	v_mul_f32_e32 v63, v63, v63
	v_fmac_f32_e32 v61, v60, v60
	v_fmac_f32_e32 v63, v62, v62
	v_add_f32_e32 v229, v61, v63
	v_pk_mul_f32 v[56:57], v[56:57], v[234:235] op_sel_hi:[1,0]
	v_pk_mul_f32 v[58:59], v[58:59], v[234:235] op_sel_hi:[1,0]
	v_mul_f32_e32 v56, 0xbfb8aa3b, v56
	v_mul_f32_e32 v57, 0xbfb8aa3b, v57
	v_mul_f32_e32 v58, 0xbfb8aa3b, v58
	v_mul_f32_e32 v59, 0xbfb8aa3b, v59
	v_exp_f32_e32 v56, v56
	v_exp_f32_e32 v57, v57
	v_exp_f32_e32 v58, v58
	v_exp_f32_e32 v59, v59
	v_pk_add_f32 v[56:57], v[56:57], 1.0 op_sel_hi:[1,0]
	v_pk_add_f32 v[58:59], v[58:59], 1.0 op_sel_hi:[1,0]
	v_div_scale_f32 v224, s[10:11], v56, v56, 1.0
	v_rcp_f32_e32 v225, v224
	s_nop 0
	v_fma_f32 v226, -v224, v225, 1.0
	v_fmac_f32_e32 v225, v226, v225
	v_div_scale_f32 v226, vcc, 1.0, v56, 1.0
	v_mul_f32_e32 v227, v226, v225
	v_fma_f32 v228, -v224, v227, v226
	v_fmac_f32_e32 v227, v228, v225
	v_fma_f32 v224, -v224, v227, v226
	v_div_fmas_f32 v224, v224, v225, v227
	v_div_fixup_f32 v56, v224, v56, 1.0
	v_div_scale_f32 v224, s[10:11], v57, v57, 1.0
	v_rcp_f32_e32 v225, v224
	s_nop 0
	v_fma_f32 v226, -v224, v225, 1.0
	v_fmac_f32_e32 v225, v226, v225
	v_div_scale_f32 v226, vcc, 1.0, v57, 1.0
	v_mul_f32_e32 v227, v226, v225
	v_fma_f32 v228, -v224, v227, v226
	v_fmac_f32_e32 v227, v228, v225
	v_fma_f32 v224, -v224, v227, v226
	v_div_fmas_f32 v224, v224, v225, v227
	v_div_fixup_f32 v57, v224, v57, 1.0
	v_div_scale_f32 v224, s[10:11], v58, v58, 1.0
	v_rcp_f32_e32 v225, v224
	s_nop 0
	v_fma_f32 v226, -v224, v225, 1.0
	v_fmac_f32_e32 v225, v226, v225
	v_div_scale_f32 v226, vcc, 1.0, v58, 1.0
	v_mul_f32_e32 v227, v226, v225
	v_fma_f32 v228, -v224, v227, v226
	v_fmac_f32_e32 v227, v228, v225
	v_fma_f32 v224, -v224, v227, v226
	v_div_fmas_f32 v224, v224, v225, v227
	v_div_fixup_f32 v58, v224, v58, 1.0
	v_div_scale_f32 v224, s[10:11], v59, v59, 1.0
	v_rcp_f32_e32 v225, v224
	s_nop 0
	v_fma_f32 v226, -v224, v225, 1.0
	v_fmac_f32_e32 v225, v226, v225
	v_div_scale_f32 v226, vcc, 1.0, v59, 1.0
	v_mul_f32_e32 v227, v226, v225
	v_fma_f32 v228, -v224, v227, v226
	v_fmac_f32_e32 v227, v228, v225
	v_fma_f32 v224, -v224, v227, v226
	v_div_fmas_f32 v224, v224, v225, v227
	v_div_fixup_f32 v59, v224, v59, 1.0
	v_lshlrev_b32_e32 v236, 16, v186
	v_and_b32_e32 v237, 0xffff0000, v186
	v_lshlrev_b32_e32 v238, 16, v187
	v_and_b32_e32 v239, 0xffff0000, v187
	v_pk_fma_f32 v[56:57], v[56:57], v[236:237], v[172:173]
	v_pk_fma_f32 v[58:59], v[58:59], v[238:239], v[174:175]
	v_cvt_pk_bf16_f32 v159, v58, v59
	v_cvt_pk_bf16_f32 v158, v56, v57
	global_store_dwordx4 v[150:151], v[56:59], off offset:64
	s_nop 1
	v_mul_f32_e32 v57, v57, v57
	v_mul_f32_e32 v59, v59, v59
	v_fmac_f32_e32 v57, v56, v56
	v_fmac_f32_e32 v59, v58, v58
	v_add_f32_e32 v56, v57, v59
	v_add_f32_e32 v229, v229, v56
	v_permlane16_swap_b32_e32 v156, v158
	v_permlane16_swap_b32_e32 v157, v159
	global_store_dwordx4 v[166:167], v[156:159], off
	s_nop 0
	v_pk_mul_f32 v[52:53], v[52:53], v[234:235] op_sel_hi:[1,0]
	v_pk_mul_f32 v[54:55], v[54:55], v[234:235] op_sel_hi:[1,0]
	v_mul_f32_e32 v52, 0xbfb8aa3b, v52
	v_mul_f32_e32 v53, 0xbfb8aa3b, v53
	v_mul_f32_e32 v54, 0xbfb8aa3b, v54
	v_mul_f32_e32 v55, 0xbfb8aa3b, v55
	v_exp_f32_e32 v52, v52
	v_exp_f32_e32 v53, v53
	v_exp_f32_e32 v54, v54
	v_exp_f32_e32 v55, v55
	v_pk_add_f32 v[52:53], v[52:53], 1.0 op_sel_hi:[1,0]
	v_pk_add_f32 v[54:55], v[54:55], 1.0 op_sel_hi:[1,0]
	v_div_scale_f32 v224, s[10:11], v52, v52, 1.0
	v_rcp_f32_e32 v225, v224
	s_nop 0
	v_fma_f32 v226, -v224, v225, 1.0
	v_fmac_f32_e32 v225, v226, v225
	v_div_scale_f32 v226, vcc, 1.0, v52, 1.0
	v_mul_f32_e32 v227, v226, v225
	v_fma_f32 v228, -v224, v227, v226
	v_fmac_f32_e32 v227, v228, v225
	v_fma_f32 v224, -v224, v227, v226
	v_div_fmas_f32 v224, v224, v225, v227
	v_div_fixup_f32 v52, v224, v52, 1.0
	v_div_scale_f32 v224, s[10:11], v53, v53, 1.0
	v_rcp_f32_e32 v225, v224
	s_nop 0
	v_fma_f32 v226, -v224, v225, 1.0
	v_fmac_f32_e32 v225, v226, v225
	v_div_scale_f32 v226, vcc, 1.0, v53, 1.0
	v_mul_f32_e32 v227, v226, v225
	v_fma_f32 v228, -v224, v227, v226
	v_fmac_f32_e32 v227, v228, v225
	v_fma_f32 v224, -v224, v227, v226
	v_div_fmas_f32 v224, v224, v225, v227
	v_div_fixup_f32 v53, v224, v53, 1.0
	v_div_scale_f32 v224, s[10:11], v54, v54, 1.0
	v_rcp_f32_e32 v225, v224
	s_nop 0
	v_fma_f32 v226, -v224, v225, 1.0
	v_fmac_f32_e32 v225, v226, v225
	v_div_scale_f32 v226, vcc, 1.0, v54, 1.0
	v_mul_f32_e32 v227, v226, v225
	v_fma_f32 v228, -v224, v227, v226
	v_fmac_f32_e32 v227, v228, v225
	v_fma_f32 v224, -v224, v227, v226
	v_div_fmas_f32 v224, v224, v225, v227
	v_div_fixup_f32 v54, v224, v54, 1.0
	v_div_scale_f32 v224, s[10:11], v55, v55, 1.0
	v_rcp_f32_e32 v225, v224
	s_nop 0
	v_fma_f32 v226, -v224, v225, 1.0
	v_fmac_f32_e32 v225, v226, v225
	v_div_scale_f32 v226, vcc, 1.0, v55, 1.0
	v_mul_f32_e32 v227, v226, v225
	v_fma_f32 v228, -v224, v227, v226
	v_fmac_f32_e32 v227, v228, v225
	v_fma_f32 v224, -v224, v227, v226
	v_div_fmas_f32 v224, v224, v225, v227
	v_div_fixup_f32 v55, v224, v55, 1.0
	v_lshlrev_b32_e32 v236, 16, v188
	v_and_b32_e32 v237, 0xffff0000, v188
	v_lshlrev_b32_e32 v238, 16, v189
	v_and_b32_e32 v239, 0xffff0000, v189
	v_pk_fma_f32 v[52:53], v[52:53], v[236:237], v[176:177]
	v_pk_fma_f32 v[54:55], v[54:55], v[238:239], v[178:179]
	v_cvt_pk_bf16_f32 v157, v54, v55
	v_cvt_pk_bf16_f32 v156, v52, v53
	global_store_dwordx4 v[150:151], v[52:55], off offset:512
	s_nop 1
	v_mul_f32_e32 v53, v53, v53
	v_mul_f32_e32 v55, v55, v55
	v_fmac_f32_e32 v53, v52, v52
	v_fmac_f32_e32 v55, v54, v54
	v_add_f32_e32 v52, v53, v55
	v_add_f32_e32 v229, v229, v52
	v_pk_mul_f32 v[48:49], v[48:49], v[234:235] op_sel_hi:[1,0]
	v_pk_mul_f32 v[50:51], v[50:51], v[234:235] op_sel_hi:[1,0]
	v_mul_f32_e32 v48, 0xbfb8aa3b, v48
	v_mul_f32_e32 v49, 0xbfb8aa3b, v49
	v_mul_f32_e32 v50, 0xbfb8aa3b, v50
	v_mul_f32_e32 v51, 0xbfb8aa3b, v51
	v_exp_f32_e32 v48, v48
	v_exp_f32_e32 v49, v49
	v_exp_f32_e32 v50, v50
	v_exp_f32_e32 v51, v51
	v_pk_add_f32 v[48:49], v[48:49], 1.0 op_sel_hi:[1,0]
	v_pk_add_f32 v[50:51], v[50:51], 1.0 op_sel_hi:[1,0]
	v_div_scale_f32 v224, s[10:11], v48, v48, 1.0
	v_rcp_f32_e32 v225, v224
	s_nop 0
	v_fma_f32 v226, -v224, v225, 1.0
	v_fmac_f32_e32 v225, v226, v225
	v_div_scale_f32 v226, vcc, 1.0, v48, 1.0
	v_mul_f32_e32 v227, v226, v225
	v_fma_f32 v228, -v224, v227, v226
	v_fmac_f32_e32 v227, v228, v225
	v_fma_f32 v224, -v224, v227, v226
	v_div_fmas_f32 v224, v224, v225, v227
	v_div_fixup_f32 v48, v224, v48, 1.0
	v_div_scale_f32 v224, s[10:11], v49, v49, 1.0
	v_rcp_f32_e32 v225, v224
	s_nop 0
	v_fma_f32 v226, -v224, v225, 1.0
	v_fmac_f32_e32 v225, v226, v225
	v_div_scale_f32 v226, vcc, 1.0, v49, 1.0
	v_mul_f32_e32 v227, v226, v225
	v_fma_f32 v228, -v224, v227, v226
	v_fmac_f32_e32 v227, v228, v225
	v_fma_f32 v224, -v224, v227, v226
	v_div_fmas_f32 v224, v224, v225, v227
	v_div_fixup_f32 v49, v224, v49, 1.0
	v_div_scale_f32 v224, s[10:11], v50, v50, 1.0
	v_rcp_f32_e32 v225, v224
	s_nop 0
	v_fma_f32 v226, -v224, v225, 1.0
	v_fmac_f32_e32 v225, v226, v225
	v_div_scale_f32 v226, vcc, 1.0, v50, 1.0
	v_mul_f32_e32 v227, v226, v225
	v_fma_f32 v228, -v224, v227, v226
	v_fmac_f32_e32 v227, v228, v225
	v_fma_f32 v224, -v224, v227, v226
	v_div_fmas_f32 v224, v224, v225, v227
	v_div_fixup_f32 v50, v224, v50, 1.0
	v_div_scale_f32 v224, s[10:11], v51, v51, 1.0
	v_rcp_f32_e32 v225, v224
	s_nop 0
	v_fma_f32 v226, -v224, v225, 1.0
	v_fmac_f32_e32 v225, v226, v225
	v_div_scale_f32 v226, vcc, 1.0, v51, 1.0
	v_mul_f32_e32 v227, v226, v225
	v_fma_f32 v228, -v224, v227, v226
	v_fmac_f32_e32 v227, v228, v225
	v_fma_f32 v224, -v224, v227, v226
	v_div_fmas_f32 v224, v224, v225, v227
	v_div_fixup_f32 v51, v224, v51, 1.0
	v_lshlrev_b32_e32 v236, 16, v190
	v_and_b32_e32 v237, 0xffff0000, v190
	v_lshlrev_b32_e32 v238, 16, v191
	v_and_b32_e32 v239, 0xffff0000, v191
	v_pk_fma_f32 v[48:49], v[48:49], v[236:237], v[180:181]
	v_pk_fma_f32 v[50:51], v[50:51], v[238:239], v[182:183]
	v_cvt_pk_bf16_f32 v159, v50, v51
	v_cvt_pk_bf16_f32 v158, v48, v49
	global_store_dwordx4 v[150:151], v[48:51], off offset:576
	s_nop 1
	v_mul_f32_e32 v49, v49, v49
	v_mul_f32_e32 v51, v51, v51
	v_fmac_f32_e32 v49, v48, v48
	v_fmac_f32_e32 v51, v50, v50
	v_add_f32_e32 v48, v49, v51
	v_add_f32_e32 v229, v229, v48
	v_permlane16_swap_b32_e32 v156, v158
	v_permlane16_swap_b32_e32 v157, v159
	global_store_dwordx4 v[166:167], v[156:159], off offset:256
	s_nop 0
	v_mov_b32_e32 v230, v229
	s_nop 1
	v_permlane16_swap_b32_e32 v229, v230
	v_add_f32_e32 v229, v229, v230
	v_mov_b32_e32 v230, v229
	s_nop 1
	v_permlane32_swap_b32_e32 v229, v230
	s_and_saveexec_b64 s[10:11], s[6:7]
	v_lshl_add_u64 v[156:157], v[144:145], 2, s[18:19]
	v_add_f32_e32 v229, v229, v230
	global_atomic_add_f32 v[156:157], v229, off
	s_or_b64 exec, exec, s[10:11]
	v_add_u32_e32 v144, 0xa0, v154
	v_mov_b32_e32 v145, v155
	v_lshlrev_b64 v[148:149], 11, v[144:145]
	v_lshl_add_u64 v[148:149], v[148:149], 0, v[146:147]
	v_lshl_add_u64 v[150:151], v[148:149], 2, s[28:29]
	v_lshl_add_u64 v[152:153], v[148:149], 1, s[42:43]
	global_load_dwordx2 v[184:185], v[152:153], off
	global_load_dwordx4 v[168:171], v[150:151], off
	global_load_dwordx2 v[186:187], v[152:153], off offset:32
	global_load_dwordx4 v[172:175], v[150:151], off offset:64
	global_load_dwordx2 v[188:189], v[152:153], off offset:256
	global_load_dwordx4 v[176:179], v[150:151], off offset:512
	global_load_dwordx2 v[190:191], v[152:153], off offset:288
	global_load_dwordx4 v[180:183], v[150:151], off offset:576
	s_waitcnt vmcnt(15)
	v_fmamk_f32 v221, v221, 0x3a000000, v164
	v_mul_f32_e32 v235, 0x4b800000, v221
	v_cmp_gt_f32_e32 vcc, s61, v221
	s_nop 1
	v_cndmask_b32_e32 v221, v221, v235, vcc
	v_rsq_f32_e32 v221, v221
	s_nop 0
	v_mul_f32_e32 v235, 0x45800000, v221
	v_cndmask_b32_e32 v234, v221, v235, vcc
	v_add_u32_e32 v144, 0x90, v154
	v_mov_b32_e32 v145, v155
	v_lshlrev_b64 v[148:149], 11, v[144:145]
	v_lshl_add_u64 v[148:149], v[148:149], 0, v[146:147]
	v_lshl_add_u64 v[150:151], v[148:149], 2, s[28:29]
	v_lshl_add_u64 v[166:167], v[148:149], 1, s[24:25]
	v_add_co_u32_e32 v166, vcc, v166, v231
	s_nop 1
	v_addc_co_u32_e32 v167, vcc, 0, v167, vcc
	v_pk_mul_f32 v[44:45], v[44:45], v[234:235] op_sel_hi:[1,0]
	v_pk_mul_f32 v[46:47], v[46:47], v[234:235] op_sel_hi:[1,0]
	v_mul_f32_e32 v44, 0xbfb8aa3b, v44
	v_mul_f32_e32 v45, 0xbfb8aa3b, v45
	v_mul_f32_e32 v46, 0xbfb8aa3b, v46
	v_mul_f32_e32 v47, 0xbfb8aa3b, v47
	v_exp_f32_e32 v44, v44
	v_exp_f32_e32 v45, v45
	v_exp_f32_e32 v46, v46
	v_exp_f32_e32 v47, v47
	v_pk_add_f32 v[44:45], v[44:45], 1.0 op_sel_hi:[1,0]
	v_pk_add_f32 v[46:47], v[46:47], 1.0 op_sel_hi:[1,0]
	v_div_scale_f32 v224, s[10:11], v44, v44, 1.0
	v_rcp_f32_e32 v225, v224
	s_nop 0
	v_fma_f32 v226, -v224, v225, 1.0
	v_fmac_f32_e32 v225, v226, v225
	v_div_scale_f32 v226, vcc, 1.0, v44, 1.0
	v_mul_f32_e32 v227, v226, v225
	v_fma_f32 v228, -v224, v227, v226
	v_fmac_f32_e32 v227, v228, v225
	v_fma_f32 v224, -v224, v227, v226
	v_div_fmas_f32 v224, v224, v225, v227
	v_div_fixup_f32 v44, v224, v44, 1.0
	v_div_scale_f32 v224, s[10:11], v45, v45, 1.0
	v_rcp_f32_e32 v225, v224
	s_nop 0
	v_fma_f32 v226, -v224, v225, 1.0
	v_fmac_f32_e32 v225, v226, v225
	v_div_scale_f32 v226, vcc, 1.0, v45, 1.0
	v_mul_f32_e32 v227, v226, v225
	v_fma_f32 v228, -v224, v227, v226
	v_fmac_f32_e32 v227, v228, v225
	v_fma_f32 v224, -v224, v227, v226
	v_div_fmas_f32 v224, v224, v225, v227
	v_div_fixup_f32 v45, v224, v45, 1.0
	v_div_scale_f32 v224, s[10:11], v46, v46, 1.0
	v_rcp_f32_e32 v225, v224
	s_nop 0
	v_fma_f32 v226, -v224, v225, 1.0
	v_fmac_f32_e32 v225, v226, v225
	v_div_scale_f32 v226, vcc, 1.0, v46, 1.0
	v_mul_f32_e32 v227, v226, v225
	v_fma_f32 v228, -v224, v227, v226
	v_fmac_f32_e32 v227, v228, v225
	v_fma_f32 v224, -v224, v227, v226
	v_div_fmas_f32 v224, v224, v225, v227
	v_div_fixup_f32 v46, v224, v46, 1.0
	v_div_scale_f32 v224, s[10:11], v47, v47, 1.0
	v_rcp_f32_e32 v225, v224
	s_nop 0
	v_fma_f32 v226, -v224, v225, 1.0
	v_fmac_f32_e32 v225, v226, v225
	v_div_scale_f32 v226, vcc, 1.0, v47, 1.0
	v_mul_f32_e32 v227, v226, v225
	v_fma_f32 v228, -v224, v227, v226
	v_fmac_f32_e32 v227, v228, v225
	v_fma_f32 v224, -v224, v227, v226
	v_div_fmas_f32 v224, v224, v225, v227
	v_div_fixup_f32 v47, v224, v47, 1.0
	v_lshlrev_b32_e32 v236, 16, v208
	v_and_b32_e32 v237, 0xffff0000, v208
	v_lshlrev_b32_e32 v238, 16, v209
	v_and_b32_e32 v239, 0xffff0000, v209
	v_pk_fma_f32 v[44:45], v[44:45], v[236:237], v[192:193]
	v_pk_fma_f32 v[46:47], v[46:47], v[238:239], v[194:195]
	v_cvt_pk_bf16_f32 v157, v46, v47
	v_cvt_pk_bf16_f32 v156, v44, v45
	global_store_dwordx4 v[150:151], v[44:47], off
	s_nop 1
	v_mul_f32_e32 v45, v45, v45
	v_mul_f32_e32 v47, v47, v47
	v_fmac_f32_e32 v45, v44, v44
	v_fmac_f32_e32 v47, v46, v46
	v_add_f32_e32 v229, v45, v47
	v_pk_mul_f32 v[40:41], v[40:41], v[234:235] op_sel_hi:[1,0]
	v_pk_mul_f32 v[42:43], v[42:43], v[234:235] op_sel_hi:[1,0]
	v_mul_f32_e32 v40, 0xbfb8aa3b, v40
	v_mul_f32_e32 v41, 0xbfb8aa3b, v41
	v_mul_f32_e32 v42, 0xbfb8aa3b, v42
	v_mul_f32_e32 v43, 0xbfb8aa3b, v43
	v_exp_f32_e32 v40, v40
	v_exp_f32_e32 v41, v41
	v_exp_f32_e32 v42, v42
	v_exp_f32_e32 v43, v43
	v_pk_add_f32 v[40:41], v[40:41], 1.0 op_sel_hi:[1,0]
	v_pk_add_f32 v[42:43], v[42:43], 1.0 op_sel_hi:[1,0]
	v_div_scale_f32 v224, s[10:11], v40, v40, 1.0
	v_rcp_f32_e32 v225, v224
	s_nop 0
	v_fma_f32 v226, -v224, v225, 1.0
	v_fmac_f32_e32 v225, v226, v225
	v_div_scale_f32 v226, vcc, 1.0, v40, 1.0
	v_mul_f32_e32 v227, v226, v225
	v_fma_f32 v228, -v224, v227, v226
	v_fmac_f32_e32 v227, v228, v225
	v_fma_f32 v224, -v224, v227, v226
	v_div_fmas_f32 v224, v224, v225, v227
	v_div_fixup_f32 v40, v224, v40, 1.0
	v_div_scale_f32 v224, s[10:11], v41, v41, 1.0
	v_rcp_f32_e32 v225, v224
	s_nop 0
	v_fma_f32 v226, -v224, v225, 1.0
	v_fmac_f32_e32 v225, v226, v225
	v_div_scale_f32 v226, vcc, 1.0, v41, 1.0
	v_mul_f32_e32 v227, v226, v225
	v_fma_f32 v228, -v224, v227, v226
	v_fmac_f32_e32 v227, v228, v225
	v_fma_f32 v224, -v224, v227, v226
	v_div_fmas_f32 v224, v224, v225, v227
	v_div_fixup_f32 v41, v224, v41, 1.0
	v_div_scale_f32 v224, s[10:11], v42, v42, 1.0
	v_rcp_f32_e32 v225, v224
	s_nop 0
	v_fma_f32 v226, -v224, v225, 1.0
	v_fmac_f32_e32 v225, v226, v225
	v_div_scale_f32 v226, vcc, 1.0, v42, 1.0
	v_mul_f32_e32 v227, v226, v225
	v_fma_f32 v228, -v224, v227, v226
	v_fmac_f32_e32 v227, v228, v225
	v_fma_f32 v224, -v224, v227, v226
	v_div_fmas_f32 v224, v224, v225, v227
	v_div_fixup_f32 v42, v224, v42, 1.0
	v_div_scale_f32 v224, s[10:11], v43, v43, 1.0
	v_rcp_f32_e32 v225, v224
	s_nop 0
	v_fma_f32 v226, -v224, v225, 1.0
	v_fmac_f32_e32 v225, v226, v225
	v_div_scale_f32 v226, vcc, 1.0, v43, 1.0
	v_mul_f32_e32 v227, v226, v225
	v_fma_f32 v228, -v224, v227, v226
	v_fmac_f32_e32 v227, v228, v225
	v_fma_f32 v224, -v224, v227, v226
	v_div_fmas_f32 v224, v224, v225, v227
	v_div_fixup_f32 v43, v224, v43, 1.0
	v_lshlrev_b32_e32 v236, 16, v210
	v_and_b32_e32 v237, 0xffff0000, v210
	v_lshlrev_b32_e32 v238, 16, v211
	v_and_b32_e32 v239, 0xffff0000, v211
	v_pk_fma_f32 v[40:41], v[40:41], v[236:237], v[196:197]
	v_pk_fma_f32 v[42:43], v[42:43], v[238:239], v[198:199]
	v_cvt_pk_bf16_f32 v159, v42, v43
	v_cvt_pk_bf16_f32 v158, v40, v41
	global_store_dwordx4 v[150:151], v[40:43], off offset:64
	s_nop 1
	v_mul_f32_e32 v41, v41, v41
	v_mul_f32_e32 v43, v43, v43
	v_fmac_f32_e32 v41, v40, v40
	v_fmac_f32_e32 v43, v42, v42
	v_add_f32_e32 v40, v41, v43
	v_add_f32_e32 v229, v229, v40
	v_permlane16_swap_b32_e32 v156, v158
	v_permlane16_swap_b32_e32 v157, v159
	global_store_dwordx4 v[166:167], v[156:159], off
	s_nop 0
	v_pk_mul_f32 v[36:37], v[36:37], v[234:235] op_sel_hi:[1,0]
	v_pk_mul_f32 v[38:39], v[38:39], v[234:235] op_sel_hi:[1,0]
	v_mul_f32_e32 v36, 0xbfb8aa3b, v36
	v_mul_f32_e32 v37, 0xbfb8aa3b, v37
	v_mul_f32_e32 v38, 0xbfb8aa3b, v38
	v_mul_f32_e32 v39, 0xbfb8aa3b, v39
	v_exp_f32_e32 v36, v36
	v_exp_f32_e32 v37, v37
	v_exp_f32_e32 v38, v38
	v_exp_f32_e32 v39, v39
	v_pk_add_f32 v[36:37], v[36:37], 1.0 op_sel_hi:[1,0]
	v_pk_add_f32 v[38:39], v[38:39], 1.0 op_sel_hi:[1,0]
	v_div_scale_f32 v224, s[10:11], v36, v36, 1.0
	v_rcp_f32_e32 v225, v224
	s_nop 0
	v_fma_f32 v226, -v224, v225, 1.0
	v_fmac_f32_e32 v225, v226, v225
	v_div_scale_f32 v226, vcc, 1.0, v36, 1.0
	v_mul_f32_e32 v227, v226, v225
	v_fma_f32 v228, -v224, v227, v226
	v_fmac_f32_e32 v227, v228, v225
	v_fma_f32 v224, -v224, v227, v226
	v_div_fmas_f32 v224, v224, v225, v227
	v_div_fixup_f32 v36, v224, v36, 1.0
	v_div_scale_f32 v224, s[10:11], v37, v37, 1.0
	v_rcp_f32_e32 v225, v224
	s_nop 0
	v_fma_f32 v226, -v224, v225, 1.0
	v_fmac_f32_e32 v225, v226, v225
	v_div_scale_f32 v226, vcc, 1.0, v37, 1.0
	v_mul_f32_e32 v227, v226, v225
	v_fma_f32 v228, -v224, v227, v226
	v_fmac_f32_e32 v227, v228, v225
	v_fma_f32 v224, -v224, v227, v226
	v_div_fmas_f32 v224, v224, v225, v227
	v_div_fixup_f32 v37, v224, v37, 1.0
	v_div_scale_f32 v224, s[10:11], v38, v38, 1.0
	v_rcp_f32_e32 v225, v224
	s_nop 0
	v_fma_f32 v226, -v224, v225, 1.0
	v_fmac_f32_e32 v225, v226, v225
	v_div_scale_f32 v226, vcc, 1.0, v38, 1.0
	v_mul_f32_e32 v227, v226, v225
	v_fma_f32 v228, -v224, v227, v226
	v_fmac_f32_e32 v227, v228, v225
	v_fma_f32 v224, -v224, v227, v226
	v_div_fmas_f32 v224, v224, v225, v227
	v_div_fixup_f32 v38, v224, v38, 1.0
	v_div_scale_f32 v224, s[10:11], v39, v39, 1.0
	v_rcp_f32_e32 v225, v224
	s_nop 0
	v_fma_f32 v226, -v224, v225, 1.0
	v_fmac_f32_e32 v225, v226, v225
	v_div_scale_f32 v226, vcc, 1.0, v39, 1.0
	v_mul_f32_e32 v227, v226, v225
	v_fma_f32 v228, -v224, v227, v226
	v_fmac_f32_e32 v227, v228, v225
	v_fma_f32 v224, -v224, v227, v226
	v_div_fmas_f32 v224, v224, v225, v227
	v_div_fixup_f32 v39, v224, v39, 1.0
	v_lshlrev_b32_e32 v236, 16, v212
	v_and_b32_e32 v237, 0xffff0000, v212
	v_lshlrev_b32_e32 v238, 16, v213
	v_and_b32_e32 v239, 0xffff0000, v213
	v_pk_fma_f32 v[36:37], v[36:37], v[236:237], v[200:201]
	v_pk_fma_f32 v[38:39], v[38:39], v[238:239], v[202:203]
	v_cvt_pk_bf16_f32 v157, v38, v39
	v_cvt_pk_bf16_f32 v156, v36, v37
	global_store_dwordx4 v[150:151], v[36:39], off offset:512
	s_nop 1
	v_mul_f32_e32 v37, v37, v37
	v_mul_f32_e32 v39, v39, v39
	v_fmac_f32_e32 v37, v36, v36
	v_fmac_f32_e32 v39, v38, v38
	v_add_f32_e32 v36, v37, v39
	v_add_f32_e32 v229, v229, v36
	v_pk_mul_f32 v[32:33], v[32:33], v[234:235] op_sel_hi:[1,0]
	v_pk_mul_f32 v[34:35], v[34:35], v[234:235] op_sel_hi:[1,0]
	v_mul_f32_e32 v32, 0xbfb8aa3b, v32
	v_mul_f32_e32 v33, 0xbfb8aa3b, v33
	v_mul_f32_e32 v34, 0xbfb8aa3b, v34
	v_mul_f32_e32 v35, 0xbfb8aa3b, v35
	v_exp_f32_e32 v32, v32
	v_exp_f32_e32 v33, v33
	v_exp_f32_e32 v34, v34
	v_exp_f32_e32 v35, v35
	v_pk_add_f32 v[32:33], v[32:33], 1.0 op_sel_hi:[1,0]
	v_pk_add_f32 v[34:35], v[34:35], 1.0 op_sel_hi:[1,0]
	v_div_scale_f32 v224, s[10:11], v32, v32, 1.0
	v_rcp_f32_e32 v225, v224
	s_nop 0
	v_fma_f32 v226, -v224, v225, 1.0
	v_fmac_f32_e32 v225, v226, v225
	v_div_scale_f32 v226, vcc, 1.0, v32, 1.0
	v_mul_f32_e32 v227, v226, v225
	v_fma_f32 v228, -v224, v227, v226
	v_fmac_f32_e32 v227, v228, v225
	v_fma_f32 v224, -v224, v227, v226
	v_div_fmas_f32 v224, v224, v225, v227
	v_div_fixup_f32 v32, v224, v32, 1.0
	v_div_scale_f32 v224, s[10:11], v33, v33, 1.0
	v_rcp_f32_e32 v225, v224
	s_nop 0
	v_fma_f32 v226, -v224, v225, 1.0
	v_fmac_f32_e32 v225, v226, v225
	v_div_scale_f32 v226, vcc, 1.0, v33, 1.0
	v_mul_f32_e32 v227, v226, v225
	v_fma_f32 v228, -v224, v227, v226
	v_fmac_f32_e32 v227, v228, v225
	v_fma_f32 v224, -v224, v227, v226
	v_div_fmas_f32 v224, v224, v225, v227
	v_div_fixup_f32 v33, v224, v33, 1.0
	v_div_scale_f32 v224, s[10:11], v34, v34, 1.0
	v_rcp_f32_e32 v225, v224
	s_nop 0
	v_fma_f32 v226, -v224, v225, 1.0
	v_fmac_f32_e32 v225, v226, v225
	v_div_scale_f32 v226, vcc, 1.0, v34, 1.0
	v_mul_f32_e32 v227, v226, v225
	v_fma_f32 v228, -v224, v227, v226
	v_fmac_f32_e32 v227, v228, v225
	v_fma_f32 v224, -v224, v227, v226
	v_div_fmas_f32 v224, v224, v225, v227
	v_div_fixup_f32 v34, v224, v34, 1.0
	v_div_scale_f32 v224, s[10:11], v35, v35, 1.0
	v_rcp_f32_e32 v225, v224
	s_nop 0
	v_fma_f32 v226, -v224, v225, 1.0
	v_fmac_f32_e32 v225, v226, v225
	v_div_scale_f32 v226, vcc, 1.0, v35, 1.0
	v_mul_f32_e32 v227, v226, v225
	v_fma_f32 v228, -v224, v227, v226
	v_fmac_f32_e32 v227, v228, v225
	v_fma_f32 v224, -v224, v227, v226
	v_div_fmas_f32 v224, v224, v225, v227
	v_div_fixup_f32 v35, v224, v35, 1.0
	v_lshlrev_b32_e32 v236, 16, v214
	v_and_b32_e32 v237, 0xffff0000, v214
	v_lshlrev_b32_e32 v238, 16, v215
	v_and_b32_e32 v239, 0xffff0000, v215
	v_pk_fma_f32 v[32:33], v[32:33], v[236:237], v[204:205]
	v_pk_fma_f32 v[34:35], v[34:35], v[238:239], v[206:207]
	v_cvt_pk_bf16_f32 v159, v34, v35
	v_cvt_pk_bf16_f32 v158, v32, v33
	global_store_dwordx4 v[150:151], v[32:35], off offset:576
	s_nop 1
	v_mul_f32_e32 v33, v33, v33
	v_mul_f32_e32 v35, v35, v35
	v_fmac_f32_e32 v33, v32, v32
	v_fmac_f32_e32 v35, v34, v34
	v_add_f32_e32 v32, v33, v35
	v_add_f32_e32 v229, v229, v32
	v_permlane16_swap_b32_e32 v156, v158
	v_permlane16_swap_b32_e32 v157, v159
	global_store_dwordx4 v[166:167], v[156:159], off offset:256
	s_nop 0
	v_mov_b32_e32 v230, v229
	s_nop 1
	v_permlane16_swap_b32_e32 v229, v230
	v_add_f32_e32 v229, v229, v230
	v_mov_b32_e32 v230, v229
	s_nop 1
	v_permlane32_swap_b32_e32 v229, v230
	s_and_saveexec_b64 s[10:11], s[6:7]
	v_lshl_add_u64 v[156:157], v[144:145], 2, s[18:19]
	v_add_f32_e32 v229, v229, v230
	global_atomic_add_f32 v[156:157], v229, off
	s_or_b64 exec, exec, s[10:11]
	v_add_u32_e32 v144, 0xb0, v154
	v_mov_b32_e32 v145, v155
	v_lshlrev_b64 v[148:149], 11, v[144:145]
	v_lshl_add_u64 v[148:149], v[148:149], 0, v[146:147]
	v_lshl_add_u64 v[150:151], v[148:149], 2, s[28:29]
	v_lshl_add_u64 v[152:153], v[148:149], 1, s[42:43]
	global_load_dwordx2 v[208:209], v[152:153], off
	global_load_dwordx4 v[192:195], v[150:151], off
	global_load_dwordx2 v[210:211], v[152:153], off offset:32
	global_load_dwordx4 v[196:199], v[150:151], off offset:64
	global_load_dwordx2 v[212:213], v[152:153], off offset:256
	global_load_dwordx4 v[200:203], v[150:151], off offset:512
	global_load_dwordx2 v[214:215], v[152:153], off offset:288
	global_load_dwordx4 v[204:207], v[150:151], off offset:576
	s_waitcnt vmcnt(15)
	v_fmamk_f32 v222, v222, 0x3a000000, v164
	v_mul_f32_e32 v235, 0x4b800000, v222
	v_cmp_gt_f32_e32 vcc, s61, v222
	s_nop 1
	v_cndmask_b32_e32 v222, v222, v235, vcc
	v_rsq_f32_e32 v222, v222
	s_nop 0
	v_mul_f32_e32 v235, 0x45800000, v222
	v_cndmask_b32_e32 v234, v222, v235, vcc
	v_add_u32_e32 v144, 0xa0, v154
	v_mov_b32_e32 v145, v155
	v_lshlrev_b64 v[148:149], 11, v[144:145]
	v_lshl_add_u64 v[148:149], v[148:149], 0, v[146:147]
	v_lshl_add_u64 v[150:151], v[148:149], 2, s[28:29]
	v_lshl_add_u64 v[166:167], v[148:149], 1, s[24:25]
	v_add_co_u32_e32 v166, vcc, v166, v231
	s_nop 1
	v_addc_co_u32_e32 v167, vcc, 0, v167, vcc
	v_pk_mul_f32 v[28:29], v[28:29], v[234:235] op_sel_hi:[1,0]
	v_pk_mul_f32 v[30:31], v[30:31], v[234:235] op_sel_hi:[1,0]
	v_mul_f32_e32 v28, 0xbfb8aa3b, v28
	v_mul_f32_e32 v29, 0xbfb8aa3b, v29
	v_mul_f32_e32 v30, 0xbfb8aa3b, v30
	v_mul_f32_e32 v31, 0xbfb8aa3b, v31
	v_exp_f32_e32 v28, v28
	v_exp_f32_e32 v29, v29
	v_exp_f32_e32 v30, v30
	v_exp_f32_e32 v31, v31
	v_pk_add_f32 v[28:29], v[28:29], 1.0 op_sel_hi:[1,0]
	v_pk_add_f32 v[30:31], v[30:31], 1.0 op_sel_hi:[1,0]
	v_div_scale_f32 v224, s[10:11], v28, v28, 1.0
	v_rcp_f32_e32 v225, v224
	s_nop 0
	v_fma_f32 v226, -v224, v225, 1.0
	v_fmac_f32_e32 v225, v226, v225
	v_div_scale_f32 v226, vcc, 1.0, v28, 1.0
	v_mul_f32_e32 v227, v226, v225
	v_fma_f32 v228, -v224, v227, v226
	v_fmac_f32_e32 v227, v228, v225
	v_fma_f32 v224, -v224, v227, v226
	v_div_fmas_f32 v224, v224, v225, v227
	v_div_fixup_f32 v28, v224, v28, 1.0
	v_div_scale_f32 v224, s[10:11], v29, v29, 1.0
	v_rcp_f32_e32 v225, v224
	s_nop 0
	v_fma_f32 v226, -v224, v225, 1.0
	v_fmac_f32_e32 v225, v226, v225
	v_div_scale_f32 v226, vcc, 1.0, v29, 1.0
	v_mul_f32_e32 v227, v226, v225
	v_fma_f32 v228, -v224, v227, v226
	v_fmac_f32_e32 v227, v228, v225
	v_fma_f32 v224, -v224, v227, v226
	v_div_fmas_f32 v224, v224, v225, v227
	v_div_fixup_f32 v29, v224, v29, 1.0
	v_div_scale_f32 v224, s[10:11], v30, v30, 1.0
	v_rcp_f32_e32 v225, v224
	s_nop 0
	v_fma_f32 v226, -v224, v225, 1.0
	v_fmac_f32_e32 v225, v226, v225
	v_div_scale_f32 v226, vcc, 1.0, v30, 1.0
	v_mul_f32_e32 v227, v226, v225
	v_fma_f32 v228, -v224, v227, v226
	v_fmac_f32_e32 v227, v228, v225
	v_fma_f32 v224, -v224, v227, v226
	v_div_fmas_f32 v224, v224, v225, v227
	v_div_fixup_f32 v30, v224, v30, 1.0
	v_div_scale_f32 v224, s[10:11], v31, v31, 1.0
	v_rcp_f32_e32 v225, v224
	s_nop 0
	v_fma_f32 v226, -v224, v225, 1.0
	v_fmac_f32_e32 v225, v226, v225
	v_div_scale_f32 v226, vcc, 1.0, v31, 1.0
	v_mul_f32_e32 v227, v226, v225
	v_fma_f32 v228, -v224, v227, v226
	v_fmac_f32_e32 v227, v228, v225
	v_fma_f32 v224, -v224, v227, v226
	v_div_fmas_f32 v224, v224, v225, v227
	v_div_fixup_f32 v31, v224, v31, 1.0
	v_lshlrev_b32_e32 v236, 16, v184
	v_and_b32_e32 v237, 0xffff0000, v184
	v_lshlrev_b32_e32 v238, 16, v185
	v_and_b32_e32 v239, 0xffff0000, v185
	v_pk_fma_f32 v[28:29], v[28:29], v[236:237], v[168:169]
	v_pk_fma_f32 v[30:31], v[30:31], v[238:239], v[170:171]
	v_cvt_pk_bf16_f32 v157, v30, v31
	v_cvt_pk_bf16_f32 v156, v28, v29
	global_store_dwordx4 v[150:151], v[28:31], off
	s_nop 1
	v_mul_f32_e32 v29, v29, v29
	v_mul_f32_e32 v31, v31, v31
	v_fmac_f32_e32 v29, v28, v28
	v_fmac_f32_e32 v31, v30, v30
	v_add_f32_e32 v229, v29, v31
	v_pk_mul_f32 v[24:25], v[24:25], v[234:235] op_sel_hi:[1,0]
	v_pk_mul_f32 v[26:27], v[26:27], v[234:235] op_sel_hi:[1,0]
	v_mul_f32_e32 v24, 0xbfb8aa3b, v24
	v_mul_f32_e32 v25, 0xbfb8aa3b, v25
	v_mul_f32_e32 v26, 0xbfb8aa3b, v26
	v_mul_f32_e32 v27, 0xbfb8aa3b, v27
	v_exp_f32_e32 v24, v24
	v_exp_f32_e32 v25, v25
	v_exp_f32_e32 v26, v26
	v_exp_f32_e32 v27, v27
	v_pk_add_f32 v[24:25], v[24:25], 1.0 op_sel_hi:[1,0]
	v_pk_add_f32 v[26:27], v[26:27], 1.0 op_sel_hi:[1,0]
	v_div_scale_f32 v224, s[10:11], v24, v24, 1.0
	v_rcp_f32_e32 v225, v224
	s_nop 0
	v_fma_f32 v226, -v224, v225, 1.0
	v_fmac_f32_e32 v225, v226, v225
	v_div_scale_f32 v226, vcc, 1.0, v24, 1.0
	v_mul_f32_e32 v227, v226, v225
	v_fma_f32 v228, -v224, v227, v226
	v_fmac_f32_e32 v227, v228, v225
	v_fma_f32 v224, -v224, v227, v226
	v_div_fmas_f32 v224, v224, v225, v227
	v_div_fixup_f32 v24, v224, v24, 1.0
	v_div_scale_f32 v224, s[10:11], v25, v25, 1.0
	v_rcp_f32_e32 v225, v224
	s_nop 0
	v_fma_f32 v226, -v224, v225, 1.0
	v_fmac_f32_e32 v225, v226, v225
	v_div_scale_f32 v226, vcc, 1.0, v25, 1.0
	v_mul_f32_e32 v227, v226, v225
	v_fma_f32 v228, -v224, v227, v226
	v_fmac_f32_e32 v227, v228, v225
	v_fma_f32 v224, -v224, v227, v226
	v_div_fmas_f32 v224, v224, v225, v227
	v_div_fixup_f32 v25, v224, v25, 1.0
	v_div_scale_f32 v224, s[10:11], v26, v26, 1.0
	v_rcp_f32_e32 v225, v224
	s_nop 0
	v_fma_f32 v226, -v224, v225, 1.0
	v_fmac_f32_e32 v225, v226, v225
	v_div_scale_f32 v226, vcc, 1.0, v26, 1.0
	v_mul_f32_e32 v227, v226, v225
	v_fma_f32 v228, -v224, v227, v226
	v_fmac_f32_e32 v227, v228, v225
	v_fma_f32 v224, -v224, v227, v226
	v_div_fmas_f32 v224, v224, v225, v227
	v_div_fixup_f32 v26, v224, v26, 1.0
	v_div_scale_f32 v224, s[10:11], v27, v27, 1.0
	v_rcp_f32_e32 v225, v224
	s_nop 0
	v_fma_f32 v226, -v224, v225, 1.0
	v_fmac_f32_e32 v225, v226, v225
	v_div_scale_f32 v226, vcc, 1.0, v27, 1.0
	v_mul_f32_e32 v227, v226, v225
	v_fma_f32 v228, -v224, v227, v226
	v_fmac_f32_e32 v227, v228, v225
	v_fma_f32 v224, -v224, v227, v226
	v_div_fmas_f32 v224, v224, v225, v227
	v_div_fixup_f32 v27, v224, v27, 1.0
	v_lshlrev_b32_e32 v236, 16, v186
	v_and_b32_e32 v237, 0xffff0000, v186
	v_lshlrev_b32_e32 v238, 16, v187
	v_and_b32_e32 v239, 0xffff0000, v187
	v_pk_fma_f32 v[24:25], v[24:25], v[236:237], v[172:173]
	v_pk_fma_f32 v[26:27], v[26:27], v[238:239], v[174:175]
	v_cvt_pk_bf16_f32 v159, v26, v27
	v_cvt_pk_bf16_f32 v158, v24, v25
	global_store_dwordx4 v[150:151], v[24:27], off offset:64
	s_nop 1
	v_mul_f32_e32 v25, v25, v25
	v_mul_f32_e32 v27, v27, v27
	v_fmac_f32_e32 v25, v24, v24
	v_fmac_f32_e32 v27, v26, v26
	v_add_f32_e32 v24, v25, v27
	v_add_f32_e32 v229, v229, v24
	v_permlane16_swap_b32_e32 v156, v158
	v_permlane16_swap_b32_e32 v157, v159
	global_store_dwordx4 v[166:167], v[156:159], off
	s_nop 0
	v_pk_mul_f32 v[20:21], v[20:21], v[234:235] op_sel_hi:[1,0]
	v_pk_mul_f32 v[22:23], v[22:23], v[234:235] op_sel_hi:[1,0]
	v_mul_f32_e32 v20, 0xbfb8aa3b, v20
	v_mul_f32_e32 v21, 0xbfb8aa3b, v21
	v_mul_f32_e32 v22, 0xbfb8aa3b, v22
	v_mul_f32_e32 v23, 0xbfb8aa3b, v23
	v_exp_f32_e32 v20, v20
	v_exp_f32_e32 v21, v21
	v_exp_f32_e32 v22, v22
	v_exp_f32_e32 v23, v23
	v_pk_add_f32 v[20:21], v[20:21], 1.0 op_sel_hi:[1,0]
	v_pk_add_f32 v[22:23], v[22:23], 1.0 op_sel_hi:[1,0]
	v_div_scale_f32 v224, s[10:11], v20, v20, 1.0
	v_rcp_f32_e32 v225, v224
	s_nop 0
	v_fma_f32 v226, -v224, v225, 1.0
	v_fmac_f32_e32 v225, v226, v225
	v_div_scale_f32 v226, vcc, 1.0, v20, 1.0
	v_mul_f32_e32 v227, v226, v225
	v_fma_f32 v228, -v224, v227, v226
	v_fmac_f32_e32 v227, v228, v225
	v_fma_f32 v224, -v224, v227, v226
	v_div_fmas_f32 v224, v224, v225, v227
	v_div_fixup_f32 v20, v224, v20, 1.0
	v_div_scale_f32 v224, s[10:11], v21, v21, 1.0
	v_rcp_f32_e32 v225, v224
	s_nop 0
	v_fma_f32 v226, -v224, v225, 1.0
	v_fmac_f32_e32 v225, v226, v225
	v_div_scale_f32 v226, vcc, 1.0, v21, 1.0
	v_mul_f32_e32 v227, v226, v225
	v_fma_f32 v228, -v224, v227, v226
	v_fmac_f32_e32 v227, v228, v225
	v_fma_f32 v224, -v224, v227, v226
	v_div_fmas_f32 v224, v224, v225, v227
	v_div_fixup_f32 v21, v224, v21, 1.0
	v_div_scale_f32 v224, s[10:11], v22, v22, 1.0
	v_rcp_f32_e32 v225, v224
	s_nop 0
	v_fma_f32 v226, -v224, v225, 1.0
	v_fmac_f32_e32 v225, v226, v225
	v_div_scale_f32 v226, vcc, 1.0, v22, 1.0
	v_mul_f32_e32 v227, v226, v225
	v_fma_f32 v228, -v224, v227, v226
	v_fmac_f32_e32 v227, v228, v225
	v_fma_f32 v224, -v224, v227, v226
	v_div_fmas_f32 v224, v224, v225, v227
	v_div_fixup_f32 v22, v224, v22, 1.0
	v_div_scale_f32 v224, s[10:11], v23, v23, 1.0
	v_rcp_f32_e32 v225, v224
	s_nop 0
	v_fma_f32 v226, -v224, v225, 1.0
	v_fmac_f32_e32 v225, v226, v225
	v_div_scale_f32 v226, vcc, 1.0, v23, 1.0
	v_mul_f32_e32 v227, v226, v225
	v_fma_f32 v228, -v224, v227, v226
	v_fmac_f32_e32 v227, v228, v225
	v_fma_f32 v224, -v224, v227, v226
	v_div_fmas_f32 v224, v224, v225, v227
	v_div_fixup_f32 v23, v224, v23, 1.0
	v_lshlrev_b32_e32 v236, 16, v188
	v_and_b32_e32 v237, 0xffff0000, v188
	v_lshlrev_b32_e32 v238, 16, v189
	v_and_b32_e32 v239, 0xffff0000, v189
	v_pk_fma_f32 v[20:21], v[20:21], v[236:237], v[176:177]
	v_pk_fma_f32 v[22:23], v[22:23], v[238:239], v[178:179]
	v_cvt_pk_bf16_f32 v157, v22, v23
	v_cvt_pk_bf16_f32 v156, v20, v21
	global_store_dwordx4 v[150:151], v[20:23], off offset:512
	s_nop 1
	v_mul_f32_e32 v21, v21, v21
	v_mul_f32_e32 v23, v23, v23
	v_fmac_f32_e32 v21, v20, v20
	v_fmac_f32_e32 v23, v22, v22
	v_add_f32_e32 v20, v21, v23
	v_add_f32_e32 v229, v229, v20
	v_pk_mul_f32 v[16:17], v[16:17], v[234:235] op_sel_hi:[1,0]
	v_pk_mul_f32 v[18:19], v[18:19], v[234:235] op_sel_hi:[1,0]
	v_mul_f32_e32 v16, 0xbfb8aa3b, v16
	v_mul_f32_e32 v17, 0xbfb8aa3b, v17
	v_mul_f32_e32 v18, 0xbfb8aa3b, v18
	v_mul_f32_e32 v19, 0xbfb8aa3b, v19
	v_exp_f32_e32 v16, v16
	v_exp_f32_e32 v17, v17
	v_exp_f32_e32 v18, v18
	v_exp_f32_e32 v19, v19
	v_pk_add_f32 v[16:17], v[16:17], 1.0 op_sel_hi:[1,0]
	v_pk_add_f32 v[18:19], v[18:19], 1.0 op_sel_hi:[1,0]
	v_div_scale_f32 v224, s[10:11], v16, v16, 1.0
	v_rcp_f32_e32 v225, v224
	s_nop 0
	v_fma_f32 v226, -v224, v225, 1.0
	v_fmac_f32_e32 v225, v226, v225
	v_div_scale_f32 v226, vcc, 1.0, v16, 1.0
	v_mul_f32_e32 v227, v226, v225
	v_fma_f32 v228, -v224, v227, v226
	v_fmac_f32_e32 v227, v228, v225
	v_fma_f32 v224, -v224, v227, v226
	v_div_fmas_f32 v224, v224, v225, v227
	v_div_fixup_f32 v16, v224, v16, 1.0
	v_div_scale_f32 v224, s[10:11], v17, v17, 1.0
	v_rcp_f32_e32 v225, v224
	s_nop 0
	v_fma_f32 v226, -v224, v225, 1.0
	v_fmac_f32_e32 v225, v226, v225
	v_div_scale_f32 v226, vcc, 1.0, v17, 1.0
	v_mul_f32_e32 v227, v226, v225
	v_fma_f32 v228, -v224, v227, v226
	v_fmac_f32_e32 v227, v228, v225
	v_fma_f32 v224, -v224, v227, v226
	v_div_fmas_f32 v224, v224, v225, v227
	v_div_fixup_f32 v17, v224, v17, 1.0
	v_div_scale_f32 v224, s[10:11], v18, v18, 1.0
	v_rcp_f32_e32 v225, v224
	s_nop 0
	v_fma_f32 v226, -v224, v225, 1.0
	v_fmac_f32_e32 v225, v226, v225
	v_div_scale_f32 v226, vcc, 1.0, v18, 1.0
	v_mul_f32_e32 v227, v226, v225
	v_fma_f32 v228, -v224, v227, v226
	v_fmac_f32_e32 v227, v228, v225
	v_fma_f32 v224, -v224, v227, v226
	v_div_fmas_f32 v224, v224, v225, v227
	v_div_fixup_f32 v18, v224, v18, 1.0
	v_div_scale_f32 v224, s[10:11], v19, v19, 1.0
	v_rcp_f32_e32 v225, v224
	s_nop 0
	v_fma_f32 v226, -v224, v225, 1.0
	v_fmac_f32_e32 v225, v226, v225
	v_div_scale_f32 v226, vcc, 1.0, v19, 1.0
	v_mul_f32_e32 v227, v226, v225
	v_fma_f32 v228, -v224, v227, v226
	v_fmac_f32_e32 v227, v228, v225
	v_fma_f32 v224, -v224, v227, v226
	v_div_fmas_f32 v224, v224, v225, v227
	v_div_fixup_f32 v19, v224, v19, 1.0
	v_lshlrev_b32_e32 v236, 16, v190
	v_and_b32_e32 v237, 0xffff0000, v190
	v_lshlrev_b32_e32 v238, 16, v191
	v_and_b32_e32 v239, 0xffff0000, v191
	v_pk_fma_f32 v[16:17], v[16:17], v[236:237], v[180:181]
	v_pk_fma_f32 v[18:19], v[18:19], v[238:239], v[182:183]
	v_cvt_pk_bf16_f32 v159, v18, v19
	v_cvt_pk_bf16_f32 v158, v16, v17
	global_store_dwordx4 v[150:151], v[16:19], off offset:576
	s_nop 1
	v_mul_f32_e32 v17, v17, v17
	v_mul_f32_e32 v19, v19, v19
	v_fmac_f32_e32 v17, v16, v16
	v_fmac_f32_e32 v19, v18, v18
	v_add_f32_e32 v16, v17, v19
	v_add_f32_e32 v229, v229, v16
	v_permlane16_swap_b32_e32 v156, v158
	v_permlane16_swap_b32_e32 v157, v159
	global_store_dwordx4 v[166:167], v[156:159], off offset:256
	s_nop 0
	v_mov_b32_e32 v230, v229
	s_nop 1
	v_permlane16_swap_b32_e32 v229, v230
	v_add_f32_e32 v229, v229, v230
	v_mov_b32_e32 v230, v229
	s_nop 1
	v_permlane32_swap_b32_e32 v229, v230
	s_and_saveexec_b64 s[10:11], s[6:7]
	v_lshl_add_u64 v[156:157], v[144:145], 2, s[18:19]
	v_add_f32_e32 v229, v229, v230
	global_atomic_add_f32 v[156:157], v229, off
	s_or_b64 exec, exec, s[10:11]
	s_waitcnt vmcnt(7)
	v_fmamk_f32 v223, v223, 0x3a000000, v164
	v_mul_f32_e32 v235, 0x4b800000, v223
	v_cmp_gt_f32_e32 vcc, s61, v223
	s_nop 1
	v_cndmask_b32_e32 v223, v223, v235, vcc
	v_rsq_f32_e32 v223, v223
	s_nop 0
	v_mul_f32_e32 v235, 0x45800000, v223
	v_cndmask_b32_e32 v234, v223, v235, vcc
	v_add_u32_e32 v144, 0xb0, v154
	v_mov_b32_e32 v145, v155
	v_lshlrev_b64 v[148:149], 11, v[144:145]
	v_lshl_add_u64 v[148:149], v[148:149], 0, v[146:147]
	v_lshl_add_u64 v[150:151], v[148:149], 2, s[28:29]
	v_lshl_add_u64 v[166:167], v[148:149], 1, s[24:25]
	v_add_co_u32_e32 v166, vcc, v166, v231
	s_nop 1
	v_addc_co_u32_e32 v167, vcc, 0, v167, vcc
	v_pk_mul_f32 v[12:13], v[12:13], v[234:235] op_sel_hi:[1,0]
	v_pk_mul_f32 v[14:15], v[14:15], v[234:235] op_sel_hi:[1,0]
	v_mul_f32_e32 v12, 0xbfb8aa3b, v12
	v_mul_f32_e32 v13, 0xbfb8aa3b, v13
	v_mul_f32_e32 v14, 0xbfb8aa3b, v14
	v_mul_f32_e32 v15, 0xbfb8aa3b, v15
	v_exp_f32_e32 v12, v12
	v_exp_f32_e32 v13, v13
	v_exp_f32_e32 v14, v14
	v_exp_f32_e32 v15, v15
	v_pk_add_f32 v[12:13], v[12:13], 1.0 op_sel_hi:[1,0]
	v_pk_add_f32 v[14:15], v[14:15], 1.0 op_sel_hi:[1,0]
	v_div_scale_f32 v224, s[10:11], v12, v12, 1.0
	v_rcp_f32_e32 v225, v224
	s_nop 0
	v_fma_f32 v226, -v224, v225, 1.0
	v_fmac_f32_e32 v225, v226, v225
	v_div_scale_f32 v226, vcc, 1.0, v12, 1.0
	v_mul_f32_e32 v227, v226, v225
	v_fma_f32 v228, -v224, v227, v226
	v_fmac_f32_e32 v227, v228, v225
	v_fma_f32 v224, -v224, v227, v226
	v_div_fmas_f32 v224, v224, v225, v227
	v_div_fixup_f32 v12, v224, v12, 1.0
	v_div_scale_f32 v224, s[10:11], v13, v13, 1.0
	v_rcp_f32_e32 v225, v224
	s_nop 0
	v_fma_f32 v226, -v224, v225, 1.0
	v_fmac_f32_e32 v225, v226, v225
	v_div_scale_f32 v226, vcc, 1.0, v13, 1.0
	v_mul_f32_e32 v227, v226, v225
	v_fma_f32 v228, -v224, v227, v226
	v_fmac_f32_e32 v227, v228, v225
	v_fma_f32 v224, -v224, v227, v226
	v_div_fmas_f32 v224, v224, v225, v227
	v_div_fixup_f32 v13, v224, v13, 1.0
	v_div_scale_f32 v224, s[10:11], v14, v14, 1.0
	v_rcp_f32_e32 v225, v224
	s_nop 0
	v_fma_f32 v226, -v224, v225, 1.0
	v_fmac_f32_e32 v225, v226, v225
	v_div_scale_f32 v226, vcc, 1.0, v14, 1.0
	v_mul_f32_e32 v227, v226, v225
	v_fma_f32 v228, -v224, v227, v226
	v_fmac_f32_e32 v227, v228, v225
	v_fma_f32 v224, -v224, v227, v226
	v_div_fmas_f32 v224, v224, v225, v227
	v_div_fixup_f32 v14, v224, v14, 1.0
	v_div_scale_f32 v224, s[10:11], v15, v15, 1.0
	v_rcp_f32_e32 v225, v224
	s_nop 0
	v_fma_f32 v226, -v224, v225, 1.0
	v_fmac_f32_e32 v225, v226, v225
	v_div_scale_f32 v226, vcc, 1.0, v15, 1.0
	v_mul_f32_e32 v227, v226, v225
	v_fma_f32 v228, -v224, v227, v226
	v_fmac_f32_e32 v227, v228, v225
	v_fma_f32 v224, -v224, v227, v226
	v_div_fmas_f32 v224, v224, v225, v227
	v_div_fixup_f32 v15, v224, v15, 1.0
	v_lshlrev_b32_e32 v236, 16, v208
	v_and_b32_e32 v237, 0xffff0000, v208
	v_lshlrev_b32_e32 v238, 16, v209
	v_and_b32_e32 v239, 0xffff0000, v209
	v_pk_fma_f32 v[12:13], v[12:13], v[236:237], v[192:193]
	v_pk_fma_f32 v[14:15], v[14:15], v[238:239], v[194:195]
	v_cvt_pk_bf16_f32 v157, v14, v15
	v_cvt_pk_bf16_f32 v156, v12, v13
	global_store_dwordx4 v[150:151], v[12:15], off
	s_nop 1
	v_mul_f32_e32 v13, v13, v13
	v_mul_f32_e32 v15, v15, v15
	v_fmac_f32_e32 v13, v12, v12
	v_fmac_f32_e32 v15, v14, v14
	v_add_f32_e32 v229, v13, v15
	v_pk_mul_f32 v[8:9], v[8:9], v[234:235] op_sel_hi:[1,0]
	v_pk_mul_f32 v[10:11], v[10:11], v[234:235] op_sel_hi:[1,0]
	v_mul_f32_e32 v8, 0xbfb8aa3b, v8
	v_mul_f32_e32 v9, 0xbfb8aa3b, v9
	v_mul_f32_e32 v10, 0xbfb8aa3b, v10
	v_mul_f32_e32 v11, 0xbfb8aa3b, v11
	v_exp_f32_e32 v8, v8
	v_exp_f32_e32 v9, v9
	v_exp_f32_e32 v10, v10
	v_exp_f32_e32 v11, v11
	v_pk_add_f32 v[8:9], v[8:9], 1.0 op_sel_hi:[1,0]
	v_pk_add_f32 v[10:11], v[10:11], 1.0 op_sel_hi:[1,0]
	v_div_scale_f32 v224, s[10:11], v8, v8, 1.0
	v_rcp_f32_e32 v225, v224
	s_nop 0
	v_fma_f32 v226, -v224, v225, 1.0
	v_fmac_f32_e32 v225, v226, v225
	v_div_scale_f32 v226, vcc, 1.0, v8, 1.0
	v_mul_f32_e32 v227, v226, v225
	v_fma_f32 v228, -v224, v227, v226
	v_fmac_f32_e32 v227, v228, v225
	v_fma_f32 v224, -v224, v227, v226
	v_div_fmas_f32 v224, v224, v225, v227
	v_div_fixup_f32 v8, v224, v8, 1.0
	v_div_scale_f32 v224, s[10:11], v9, v9, 1.0
	v_rcp_f32_e32 v225, v224
	s_nop 0
	v_fma_f32 v226, -v224, v225, 1.0
	v_fmac_f32_e32 v225, v226, v225
	v_div_scale_f32 v226, vcc, 1.0, v9, 1.0
	v_mul_f32_e32 v227, v226, v225
	v_fma_f32 v228, -v224, v227, v226
	v_fmac_f32_e32 v227, v228, v225
	v_fma_f32 v224, -v224, v227, v226
	v_div_fmas_f32 v224, v224, v225, v227
	v_div_fixup_f32 v9, v224, v9, 1.0
	v_div_scale_f32 v224, s[10:11], v10, v10, 1.0
	v_rcp_f32_e32 v225, v224
	s_nop 0
	v_fma_f32 v226, -v224, v225, 1.0
	v_fmac_f32_e32 v225, v226, v225
	v_div_scale_f32 v226, vcc, 1.0, v10, 1.0
	v_mul_f32_e32 v227, v226, v225
	v_fma_f32 v228, -v224, v227, v226
	v_fmac_f32_e32 v227, v228, v225
	v_fma_f32 v224, -v224, v227, v226
	v_div_fmas_f32 v224, v224, v225, v227
	v_div_fixup_f32 v10, v224, v10, 1.0
	v_div_scale_f32 v224, s[10:11], v11, v11, 1.0
	v_rcp_f32_e32 v225, v224
	s_nop 0
	v_fma_f32 v226, -v224, v225, 1.0
	v_fmac_f32_e32 v225, v226, v225
	v_div_scale_f32 v226, vcc, 1.0, v11, 1.0
	v_mul_f32_e32 v227, v226, v225
	v_fma_f32 v228, -v224, v227, v226
	v_fmac_f32_e32 v227, v228, v225
	v_fma_f32 v224, -v224, v227, v226
	v_div_fmas_f32 v224, v224, v225, v227
	v_div_fixup_f32 v11, v224, v11, 1.0
	v_lshlrev_b32_e32 v236, 16, v210
	v_and_b32_e32 v237, 0xffff0000, v210
	v_lshlrev_b32_e32 v238, 16, v211
	v_and_b32_e32 v239, 0xffff0000, v211
	v_pk_fma_f32 v[8:9], v[8:9], v[236:237], v[196:197]
	v_pk_fma_f32 v[10:11], v[10:11], v[238:239], v[198:199]
	v_cvt_pk_bf16_f32 v159, v10, v11
	v_cvt_pk_bf16_f32 v158, v8, v9
	global_store_dwordx4 v[150:151], v[8:11], off offset:64
	s_nop 1
	v_mul_f32_e32 v9, v9, v9
	v_mul_f32_e32 v11, v11, v11
	v_fmac_f32_e32 v9, v8, v8
	v_fmac_f32_e32 v11, v10, v10
	v_add_f32_e32 v8, v9, v11
	v_add_f32_e32 v229, v229, v8
	v_permlane16_swap_b32_e32 v156, v158
	v_permlane16_swap_b32_e32 v157, v159
	global_store_dwordx4 v[166:167], v[156:159], off
	s_nop 0
	v_pk_mul_f32 v[4:5], v[4:5], v[234:235] op_sel_hi:[1,0]
	v_pk_mul_f32 v[6:7], v[6:7], v[234:235] op_sel_hi:[1,0]
	v_mul_f32_e32 v4, 0xbfb8aa3b, v4
	v_mul_f32_e32 v5, 0xbfb8aa3b, v5
	v_mul_f32_e32 v6, 0xbfb8aa3b, v6
	v_mul_f32_e32 v7, 0xbfb8aa3b, v7
	v_exp_f32_e32 v4, v4
	v_exp_f32_e32 v5, v5
	v_exp_f32_e32 v6, v6
	v_exp_f32_e32 v7, v7
	v_pk_add_f32 v[4:5], v[4:5], 1.0 op_sel_hi:[1,0]
	v_pk_add_f32 v[6:7], v[6:7], 1.0 op_sel_hi:[1,0]
	v_div_scale_f32 v224, s[10:11], v4, v4, 1.0
	v_rcp_f32_e32 v225, v224
	s_nop 0
	v_fma_f32 v226, -v224, v225, 1.0
	v_fmac_f32_e32 v225, v226, v225
	v_div_scale_f32 v226, vcc, 1.0, v4, 1.0
	v_mul_f32_e32 v227, v226, v225
	v_fma_f32 v228, -v224, v227, v226
	v_fmac_f32_e32 v227, v228, v225
	v_fma_f32 v224, -v224, v227, v226
	v_div_fmas_f32 v224, v224, v225, v227
	v_div_fixup_f32 v4, v224, v4, 1.0
	v_div_scale_f32 v224, s[10:11], v5, v5, 1.0
	v_rcp_f32_e32 v225, v224
	s_nop 0
	v_fma_f32 v226, -v224, v225, 1.0
	v_fmac_f32_e32 v225, v226, v225
	v_div_scale_f32 v226, vcc, 1.0, v5, 1.0
	v_mul_f32_e32 v227, v226, v225
	v_fma_f32 v228, -v224, v227, v226
	v_fmac_f32_e32 v227, v228, v225
	v_fma_f32 v224, -v224, v227, v226
	v_div_fmas_f32 v224, v224, v225, v227
	v_div_fixup_f32 v5, v224, v5, 1.0
	v_div_scale_f32 v224, s[10:11], v6, v6, 1.0
	v_rcp_f32_e32 v225, v224
	s_nop 0
	v_fma_f32 v226, -v224, v225, 1.0
	v_fmac_f32_e32 v225, v226, v225
	v_div_scale_f32 v226, vcc, 1.0, v6, 1.0
	v_mul_f32_e32 v227, v226, v225
	v_fma_f32 v228, -v224, v227, v226
	v_fmac_f32_e32 v227, v228, v225
	v_fma_f32 v224, -v224, v227, v226
	v_div_fmas_f32 v224, v224, v225, v227
	v_div_fixup_f32 v6, v224, v6, 1.0
	v_div_scale_f32 v224, s[10:11], v7, v7, 1.0
	v_rcp_f32_e32 v225, v224
	s_nop 0
	v_fma_f32 v226, -v224, v225, 1.0
	v_fmac_f32_e32 v225, v226, v225
	v_div_scale_f32 v226, vcc, 1.0, v7, 1.0
	v_mul_f32_e32 v227, v226, v225
	v_fma_f32 v228, -v224, v227, v226
	v_fmac_f32_e32 v227, v228, v225
	v_fma_f32 v224, -v224, v227, v226
	v_div_fmas_f32 v224, v224, v225, v227
	v_div_fixup_f32 v7, v224, v7, 1.0
	v_lshlrev_b32_e32 v236, 16, v212
	v_and_b32_e32 v237, 0xffff0000, v212
	v_lshlrev_b32_e32 v238, 16, v213
	v_and_b32_e32 v239, 0xffff0000, v213
	v_pk_fma_f32 v[4:5], v[4:5], v[236:237], v[200:201]
	v_pk_fma_f32 v[6:7], v[6:7], v[238:239], v[202:203]
	v_cvt_pk_bf16_f32 v157, v6, v7
	v_cvt_pk_bf16_f32 v156, v4, v5
	global_store_dwordx4 v[150:151], v[4:7], off offset:512
	s_nop 1
	v_mul_f32_e32 v5, v5, v5
	v_mul_f32_e32 v7, v7, v7
	v_fmac_f32_e32 v5, v4, v4
	v_fmac_f32_e32 v7, v6, v6
	v_add_f32_e32 v4, v5, v7
	v_add_f32_e32 v229, v229, v4
	v_pk_mul_f32 v[0:1], v[0:1], v[234:235] op_sel_hi:[1,0]
	v_pk_mul_f32 v[2:3], v[2:3], v[234:235] op_sel_hi:[1,0]
	v_mul_f32_e32 v0, 0xbfb8aa3b, v0
	v_mul_f32_e32 v1, 0xbfb8aa3b, v1
	v_mul_f32_e32 v2, 0xbfb8aa3b, v2
	v_mul_f32_e32 v3, 0xbfb8aa3b, v3
	v_exp_f32_e32 v0, v0
	v_exp_f32_e32 v1, v1
	v_exp_f32_e32 v2, v2
	v_exp_f32_e32 v3, v3
	v_pk_add_f32 v[0:1], v[0:1], 1.0 op_sel_hi:[1,0]
	v_pk_add_f32 v[2:3], v[2:3], 1.0 op_sel_hi:[1,0]
	v_div_scale_f32 v224, s[10:11], v0, v0, 1.0
	v_rcp_f32_e32 v225, v224
	s_nop 0
	v_fma_f32 v226, -v224, v225, 1.0
	v_fmac_f32_e32 v225, v226, v225
	v_div_scale_f32 v226, vcc, 1.0, v0, 1.0
	v_mul_f32_e32 v227, v226, v225
	v_fma_f32 v228, -v224, v227, v226
	v_fmac_f32_e32 v227, v228, v225
	v_fma_f32 v224, -v224, v227, v226
	v_div_fmas_f32 v224, v224, v225, v227
	v_div_fixup_f32 v0, v224, v0, 1.0
	v_div_scale_f32 v224, s[10:11], v1, v1, 1.0
	v_rcp_f32_e32 v225, v224
	s_nop 0
	v_fma_f32 v226, -v224, v225, 1.0
	v_fmac_f32_e32 v225, v226, v225
	v_div_scale_f32 v226, vcc, 1.0, v1, 1.0
	v_mul_f32_e32 v227, v226, v225
	v_fma_f32 v228, -v224, v227, v226
	v_fmac_f32_e32 v227, v228, v225
	v_fma_f32 v224, -v224, v227, v226
	v_div_fmas_f32 v224, v224, v225, v227
	v_div_fixup_f32 v1, v224, v1, 1.0
	v_div_scale_f32 v224, s[10:11], v2, v2, 1.0
	v_rcp_f32_e32 v225, v224
	s_nop 0
	v_fma_f32 v226, -v224, v225, 1.0
	v_fmac_f32_e32 v225, v226, v225
	v_div_scale_f32 v226, vcc, 1.0, v2, 1.0
	v_mul_f32_e32 v227, v226, v225
	v_fma_f32 v228, -v224, v227, v226
	v_fmac_f32_e32 v227, v228, v225
	v_fma_f32 v224, -v224, v227, v226
	v_div_fmas_f32 v224, v224, v225, v227
	v_div_fixup_f32 v2, v224, v2, 1.0
	v_div_scale_f32 v224, s[10:11], v3, v3, 1.0
	v_rcp_f32_e32 v225, v224
	s_nop 0
	v_fma_f32 v226, -v224, v225, 1.0
	v_fmac_f32_e32 v225, v226, v225
	v_div_scale_f32 v226, vcc, 1.0, v3, 1.0
	v_mul_f32_e32 v227, v226, v225
	v_fma_f32 v228, -v224, v227, v226
	v_fmac_f32_e32 v227, v228, v225
	v_fma_f32 v224, -v224, v227, v226
	v_div_fmas_f32 v224, v224, v225, v227
	v_div_fixup_f32 v3, v224, v3, 1.0
	v_lshlrev_b32_e32 v236, 16, v214
	v_and_b32_e32 v237, 0xffff0000, v214
	v_lshlrev_b32_e32 v238, 16, v215
	v_and_b32_e32 v239, 0xffff0000, v215
	v_pk_fma_f32 v[0:1], v[0:1], v[236:237], v[204:205]
	v_pk_fma_f32 v[2:3], v[2:3], v[238:239], v[206:207]
	v_cvt_pk_bf16_f32 v159, v2, v3
	v_cvt_pk_bf16_f32 v158, v0, v1
	global_store_dwordx4 v[150:151], v[0:3], off offset:576
	s_nop 1
	v_mul_f32_e32 v1, v1, v1
	v_mul_f32_e32 v3, v3, v3
	v_fmac_f32_e32 v1, v0, v0
	v_fmac_f32_e32 v3, v2, v2
	v_add_f32_e32 v0, v1, v3
	v_add_f32_e32 v229, v229, v0
	v_permlane16_swap_b32_e32 v156, v158
	v_permlane16_swap_b32_e32 v157, v159
	global_store_dwordx4 v[166:167], v[156:159], off offset:256
	s_nop 0
	v_mov_b32_e32 v230, v229
	s_nop 1
	v_permlane16_swap_b32_e32 v229, v230
	v_add_f32_e32 v229, v229, v230
	v_mov_b32_e32 v230, v229
	s_nop 1
	v_permlane32_swap_b32_e32 v229, v230
	s_and_saveexec_b64 s[10:11], s[6:7]
	v_lshl_add_u64 v[156:157], v[144:145], 2, s[18:19]
	v_add_f32_e32 v229, v229, v230
	global_atomic_add_f32 v[156:157], v229, off
	s_or_b64 exec, exec, s[10:11]
	s_branch .LBB0_1885
